# P8-epilogue-one-wait-per-section
# speedup vs baseline: 1.0260x; 1.0031x over previous
;     template <bool EDGE> __device__ __forceinline__ void body(const f32x4 (&acc)[2][2][4][2], const pg8::Unit& u, int wr, int wc, int fr, int fq) const {
;         const int tw0 = 252 * u.pm - 2 + 126 * wr;
;         const int chb = 128 * u.pn + 32 * wc + 8 * fq;
; #pragma unroll
;         for (int n = 0; n < 2; ++n) {
;             const int ch = chb + 4 * n;
;             const f32x4 wv0 = *(const f32x4*)(conv_w + ch), wv1 = *(const f32x4*)(conv_w + NUP + ch), wv2 = *(const f32x4*)(conv_w + 2 * NUP + ch), bv = *(const f32x4*)(conv_b + ch);
;             const f32x4 wg0 = *(const f32x4*)(conv_w + DFF + ch), wg1 = *(const f32x4*)(conv_w + NUP + DFF + ch), wg2 = *(const f32x4*)(conv_w + 2 * NUP + DFF + ch), bg = *(const f32x4*)(conv_b + DFF + ch);
;             const f32x4 v7 = dpp_shr1(acc[1][0][3][n]), v6 = dpp_shr1(acc[1][0][2][n]), g7 = dpp_shr1(acc[1][1][3][n]), g6 = dpp_shr1(acc[1][1][2][n]);
; #pragma unroll
;             for (int k = 0; k < 8; ++k) {
;                 const int ai = k >> 2, m = k & 3, lr = 8 * fr + k, tau = tw0 + lr, sp = tau & 4095;
;                 const f32x4 cv = acc[ai][0][m][n], cg = acc[ai][1][m][n];
;                 const f32x4 p1v = k >= 1 ? acc[(k >= 1 ? k - 1 : 0) >> 2][0][(k >= 1 ? k - 1 : 0) & 3][n] : v7;
;                 const f32x4 p1g = k >= 1 ? acc[(k >= 1 ? k - 1 : 0) >> 2][1][(k >= 1 ? k - 1 : 0) & 3][n] : g7;
;                 const f32x4 p2v = k >= 2 ? acc[(k >= 2 ? k - 2 : 0) >> 2][0][(k >= 2 ? k - 2 : 0) & 3][n] : (k == 1 ? v7 : v6);
;                 const f32x4 p2g = k >= 2 ? acc[(k >= 2 ? k - 2 : 0) >> 2][1][(k >= 2 ? k - 2 : 0) & 3][n] : (k == 1 ? g7 : g6);
;                 f32x4 val, gat;
;                 if (EDGE) { const float m1 = sp >= 1 ? 1.f : 0.f, m2 = sp >= 2 ? 1.f : 0.f;
;                     val = bv + wv2 * cv + (wv1 * m1) * p1v + (wv0 * m2) * p2v; gat = bg + wg2 * cg + (wg1 * m1) * p1g + (wg0 * m2) * p2g; }
;                 else { val = bv + wv2 * cv + wv1 * p1v + wv0 * p2v; gat = bg + wg2 * cg + wg1 * p1g + wg0 * p2g; }
;                 const f32x2 g01 = gelu_pk((f32x2){gat[0], gat[1]}), g23 = gelu_pk((f32x2){gat[2], gat[3]});
;                 u32x2 w; w.x = pk2(g01.x * val[0], g01.y * val[1]); w.y = pk2(g23.x * val[2], g23.y * val[3]);
;                 if (lr >= 2 && tau < NT) *(u32x2*)((char*)hidden + (unsigned)(tau * DFF + ch) * 2u) = w;
.LBB0_783:
	s_mul_i32 s0, s10, 0xfc
	s_add_i32 s25, s65, s0
	s_cmp_lt_i32 s25, 2
	s_cselect_b64 s[0:1], -1, 0
	s_and_b32 s2, s25, 0xffe
	s_cmp_eq_u32 s2, 0
	s_cselect_b64 s[2:3], -1, 0
	s_or_b64 s[0:1], s[0:1], s[2:3]
	s_and_b64 vcc, exec, s[0:1]
	s_cbranch_vccnz .LBB0_811
	s_add_i32 s0, s25, 0x7f
	s_xor_b32 s0, s0, s25
	s_cmpk_lt_u32 s0, 0x1000
	s_mov_b64 s[0:1], -1
	s_cbranch_scc0 .LBB0_811
	v_lshl_or_b32 v164, s24, 7, v204
	v_ashrrev_i32_e32 v165, 31, v164
	v_lshlrev_b64 v[156:157], 2, v[164:165]
	v_lshl_add_u64 v[166:167], s[28:29], 0, v[156:157]
	v_lshl_add_u64 v[132:133], s[44:45], 0, v[156:157]
	v_lshl_add_u64 v[136:137], s[46:47], 0, v[156:157]
	v_lshl_add_u64 v[168:169], s[30:31], 0, v[156:157]
	v_lshl_add_u64 v[144:145], s[48:49], 0, v[156:157]
	v_lshl_add_u64 v[148:149], s[50:51], 0, v[156:157]
	v_lshl_add_u64 v[152:153], s[52:53], 0, v[156:157]
	v_lshl_add_u64 v[156:157], s[54:55], 0, v[156:157]
	global_load_dwordx4 v[128:131], v[166:167], off
	s_nop 0
	global_load_dwordx4 v[132:135], v[132:133], off
	s_nop 0
	global_load_dwordx4 v[136:139], v[136:137], off
	v_add_u32_e32 v165, s25, v196
	global_load_dwordx4 v[140:143], v[168:169], off
	s_nop 0
	global_load_dwordx4 v[144:147], v[144:145], off
	s_nop 0
	global_load_dwordx4 v[148:151], v[148:149], off
	v_mov_b32_e32 v170, 0
	global_load_dwordx4 v[152:155], v[152:153], off
	v_mov_b32_e32 v171, 0
	global_load_dwordx4 v[156:159], v[156:157], off
	v_mov_b32_e32 v172, 0
	v_mov_b32_e32 v173, 0
	v_mov_b32_e32 v178, 0
	v_mov_b32_e32 v179, 0
	v_mov_b32_e32 v180, 0
	v_mov_b32_e32 v181, 0
	v_mov_b32_e32 v174, 0
	v_mov_b32_e32 v175, 0
	v_mov_b32_e32 v176, 0
	v_mov_b32_e32 v177, 0
	v_mov_b32_e32 v182, 0
	v_mov_b32_e32 v183, 0
	v_mov_b32_e32 v184, 0
	v_mov_b32_e32 v185, 0
	v_cmp_gt_u32_e32 vcc, s59, v165
	v_mov_b32_dpp v170, v64 row_shr:1 row_mask:0xf bank_mask:0xf
	v_mov_b32_dpp v171, v65 row_shr:1 row_mask:0xf bank_mask:0xf
	v_mov_b32_dpp v172, v66 row_shr:1 row_mask:0xf bank_mask:0xf
	v_mov_b32_dpp v173, v67 row_shr:1 row_mask:0xf bank_mask:0xf
	v_mov_b32_dpp v178, v68 row_shr:1 row_mask:0xf bank_mask:0xf
	v_mov_b32_dpp v179, v69 row_shr:1 row_mask:0xf bank_mask:0xf
	v_mov_b32_dpp v180, v70 row_shr:1 row_mask:0xf bank_mask:0xf
	v_mov_b32_dpp v181, v71 row_shr:1 row_mask:0xf bank_mask:0xf
	v_mov_b32_dpp v174, v80 row_shr:1 row_mask:0xf bank_mask:0xf
	v_mov_b32_dpp v175, v81 row_shr:1 row_mask:0xf bank_mask:0xf
	v_mov_b32_dpp v176, v82 row_shr:1 row_mask:0xf bank_mask:0xf
	v_mov_b32_dpp v177, v83 row_shr:1 row_mask:0xf bank_mask:0xf
	v_mov_b32_dpp v182, v84 row_shr:1 row_mask:0xf bank_mask:0xf
	v_mov_b32_dpp v183, v85 row_shr:1 row_mask:0xf bank_mask:0xf
	v_mov_b32_dpp v184, v86 row_shr:1 row_mask:0xf bank_mask:0xf
	v_mov_b32_dpp v185, v87 row_shr:1 row_mask:0xf bank_mask:0xf
	s_and_b64 s[0:1], s[6:7], vcc
	v_mul_lo_u32 v210, v165, s73
	s_waitcnt vmcnt(0)
	s_and_saveexec_b64 s[2:3], s[0:1]
	s_cbranch_execz .LBB0_787
	v_pk_fma_f32 v[212:213], v[124:125], v[152:153], v[156:157]
	v_mov_b64_e32 v[222:223], s[62:63]
	v_pk_fma_f32 v[212:213], v[148:149], v[174:175], v[212:213]
	v_pk_fma_f32 v[188:189], v[126:127], v[154:155], v[158:159]
	v_pk_fma_f32 v[182:183], v[144:145], v[182:183], v[212:213]
	v_pk_fma_f32 v[188:189], v[150:151], v[176:177], v[188:189]
	v_and_b32_e32 v215, 0x7fffffff, v183
	v_and_b32_e32 v214, 0x7fffffff, v182
	v_pk_fma_f32 v[220:221], v[214:215], s[58:59], 1.0 op_sel_hi:[1,0,0]
	v_pk_mul_f32 v[218:219], v[182:183], v[182:183]
	v_rcp_f32_e32 v220, v220
	v_rcp_f32_e32 v221, v221
	v_pk_mul_f32 v[218:219], v[218:219], s[56:57] op_sel_hi:[1,0]
	v_pk_fma_f32 v[184:185], v[146:147], v[184:185], v[188:189]
	v_exp_f32_e32 v218, v218
	v_pk_fma_f32 v[224:225], v[220:221], s[60:61], v[222:223] op_sel_hi:[1,0,0]
	v_exp_f32_e32 v219, v219
	v_pk_fma_f32 v[224:225], v[220:221], v[224:225], s[64:65] op_sel_hi:[1,1,0]
	v_max_f32_e32 v188, 0, v182
	v_pk_fma_f32 v[224:225], v[220:221], v[224:225], s[66:67] op_sel_hi:[1,1,0]
	v_and_b32_e32 v213, 0x7fffffff, v185
	v_pk_fma_f32 v[224:225], v[220:221], v[224:225], s[68:69] op_sel_hi:[1,1,0]
	v_and_b32_e32 v212, 0x7fffffff, v184
	v_pk_mul_f32 v[220:221], v[220:221], v[224:225]
	v_max_f32_e32 v189, 0, v183
	v_pk_mul_f32 v[218:219], v[218:219], v[220:221]
	v_pk_mul_f32 v[216:217], v[184:185], v[184:185]
	v_pk_fma_f32 v[182:183], v[214:215], v[218:219], v[188:189] neg_lo:[1,0,0] neg_hi:[1,0,0]
	v_pk_fma_f32 v[188:189], v[212:213], s[58:59], 1.0 op_sel_hi:[1,0,0]
	v_pk_mul_f32 v[214:215], v[216:217], s[56:57] op_sel_hi:[1,0]
	v_rcp_f32_e32 v188, v188
	v_rcp_f32_e32 v189, v189
	v_exp_f32_e32 v214, v214
	v_exp_f32_e32 v215, v215
	v_pk_fma_f32 v[224:225], v[120:121], v[136:137], v[140:141]
	v_pk_fma_f32 v[216:217], v[188:189], s[60:61], v[222:223] op_sel_hi:[1,0,0]
	v_pk_fma_f32 v[224:225], v[132:133], v[170:171], v[224:225]
	v_pk_fma_f32 v[216:217], v[188:189], v[216:217], s[64:65] op_sel_hi:[1,1,0]
	v_pk_fma_f32 v[220:221], v[122:123], v[138:139], v[142:143]
	v_pk_fma_f32 v[216:217], v[188:189], v[216:217], s[66:67] op_sel_hi:[1,1,0]
	v_pk_fma_f32 v[178:179], v[128:129], v[178:179], v[224:225]
	v_pk_fma_f32 v[216:217], v[188:189], v[216:217], s[68:69] op_sel_hi:[1,1,0]
	v_pk_fma_f32 v[220:221], v[134:135], v[172:173], v[220:221]
	v_pk_mul_f32 v[188:189], v[188:189], v[216:217]
	v_pk_mul_f32 v[178:179], v[178:179], v[182:183]
	v_max_f32_e32 v182, 0, v184
	v_pk_mul_f32 v[188:189], v[214:215], v[188:189]
	v_max_f32_e32 v183, 0, v185
	v_pk_fma_f32 v[180:181], v[130:131], v[180:181], v[220:221]
	v_pk_fma_f32 v[182:183], v[212:213], v[188:189], v[182:183] neg_lo:[1,0,0] neg_hi:[1,0,0]
	v_add_lshl_u32 v165, v210, v164, 1
	v_pk_mul_f32 v[180:181], v[180:181], v[182:183]
	v_cvt_pk_bf16_f32 v178, v178, v179
	v_cvt_pk_bf16_f32 v179, v180, v181
	global_store_dwordx2 v165, v[178:179], s[40:41]
; __device__ __forceinline__ unsigned pk2(float lo, float hi) { const f32x2 v = {lo, hi}; return __builtin_bit_cast(unsigned, __builtin_convertvector(v, bf16x2_hw)); }
;     template <bool EDGE> __device__ __forceinline__ void body(const f32x4 (&acc)[2][2][4][2], const pg8::Unit& u, int wr, int wc, int fr, int fq) const {
;     ...
; #pragma unroll
;             for (int k = 0; k < 8; ++k) {
;                 const int ai = k >> 2, m = k & 3, lr = 8 * fr + k, tau = tw0 + lr, sp = tau & 4095;
;                 const f32x4 cv = acc[ai][0][m][n], cg = acc[ai][1][m][n];
;                 const f32x4 p1v = k >= 1 ? acc[(k >= 1 ? k - 1 : 0) >> 2][0][(k >= 1 ? k - 1 : 0) & 3][n] : v7;
;                 const f32x4 p1g = k >= 1 ? acc[(k >= 1 ? k - 1 : 0) >> 2][1][(k >= 1 ? k - 1 : 0) & 3][n] : g7;
;                 const f32x4 p2v = k >= 2 ? acc[(k >= 2 ? k - 2 : 0) >> 2][0][(k >= 2 ? k - 2 : 0) & 3][n] : (k == 1 ? v7 : v6);
;                 const f32x4 p2g = k >= 2 ? acc[(k >= 2 ? k - 2 : 0) >> 2][1][(k >= 2 ? k - 2 : 0) & 3][n] : (k == 1 ? g7 : g6);
;                 f32x4 val, gat;
;                 if (EDGE) { const float m1 = sp >= 1 ? 1.f : 0.f, m2 = sp >= 2 ? 1.f : 0.f;
;                     val = bv + wv2 * cv + (wv1 * m1) * p1v + (wv0 * m2) * p2v; gat = bg + wg2 * cg + (wg1 * m1) * p1g + (wg0 * m2) * p2g; }
;                 else { val = bv + wv2 * cv + wv1 * p1v + wv0 * p2v; gat = bg + wg2 * cg + wg1 * p1g + wg0 * p2g; }
;                 const f32x2 g01 = gelu_pk((f32x2){gat[0], gat[1]}), g23 = gelu_pk((f32x2){gat[2], gat[3]});
;                 u32x2 w; w.x = pk2(g01.x * val[0], g01.y * val[1]); w.y = pk2(g23.x * val[2], g23.y * val[3]);
;                 if (lr >= 2 && tau < NT) *(u32x2*)((char*)hidden + (unsigned)(tau * DFF + ch) * 2u) = w;
;             }
.LBB0_787:
	s_or_b64 exec, exec, s[2:3]
	v_add_u32_e32 v165, s25, v197
	v_cmp_gt_u32_e32 vcc, s59, v165
	s_and_b64 s[2:3], s[6:7], vcc
	v_mul_lo_u32 v182, v165, s73
	s_and_saveexec_b64 s[10:11], s[2:3]
	s_cbranch_execz .LBB0_789
	v_pk_fma_f32 v[180:181], v[116:117], v[152:153], v[156:157]
	v_mov_b64_e32 v[216:217], s[62:63]
	v_pk_fma_f32 v[180:181], v[124:125], v[148:149], v[180:181]
	v_pk_fma_f32 v[178:179], v[118:119], v[154:155], v[158:159]
	v_pk_fma_f32 v[174:175], v[144:145], v[174:175], v[180:181]
	v_pk_fma_f32 v[178:179], v[126:127], v[150:151], v[178:179]
	v_and_b32_e32 v185, 0x7fffffff, v175
	v_and_b32_e32 v184, 0x7fffffff, v174
	v_pk_fma_f32 v[214:215], v[184:185], s[58:59], 1.0 op_sel_hi:[1,0,0]
	v_pk_mul_f32 v[212:213], v[174:175], v[174:175]
	v_rcp_f32_e32 v214, v214
	v_rcp_f32_e32 v215, v215
	v_pk_mul_f32 v[212:213], v[212:213], s[56:57] op_sel_hi:[1,0]
	v_pk_fma_f32 v[176:177], v[146:147], v[176:177], v[178:179]
	v_exp_f32_e32 v212, v212
	v_pk_fma_f32 v[218:219], v[214:215], s[60:61], v[216:217] op_sel_hi:[1,0,0]
	v_exp_f32_e32 v213, v213
	v_pk_fma_f32 v[218:219], v[214:215], v[218:219], s[64:65] op_sel_hi:[1,1,0]
	v_max_f32_e32 v178, 0, v174
	v_pk_fma_f32 v[218:219], v[214:215], v[218:219], s[66:67] op_sel_hi:[1,1,0]
	v_and_b32_e32 v181, 0x7fffffff, v177
	v_pk_fma_f32 v[218:219], v[214:215], v[218:219], s[68:69] op_sel_hi:[1,1,0]
	v_and_b32_e32 v180, 0x7fffffff, v176
	v_pk_mul_f32 v[214:215], v[214:215], v[218:219]
	v_max_f32_e32 v179, 0, v175
	v_pk_mul_f32 v[212:213], v[212:213], v[214:215]
	v_pk_mul_f32 v[188:189], v[176:177], v[176:177]
	v_pk_fma_f32 v[174:175], v[184:185], v[212:213], v[178:179] neg_lo:[1,0,0] neg_hi:[1,0,0]
	v_pk_fma_f32 v[178:179], v[180:181], s[58:59], 1.0 op_sel_hi:[1,0,0]
	v_pk_mul_f32 v[184:185], v[188:189], s[56:57] op_sel_hi:[1,0]
	v_rcp_f32_e32 v178, v178
	v_rcp_f32_e32 v179, v179
	v_exp_f32_e32 v184, v184
	v_exp_f32_e32 v185, v185
	v_pk_fma_f32 v[218:219], v[112:113], v[136:137], v[140:141]
	v_pk_fma_f32 v[188:189], v[178:179], s[60:61], v[216:217] op_sel_hi:[1,0,0]
	v_pk_fma_f32 v[218:219], v[120:121], v[132:133], v[218:219]
	v_pk_fma_f32 v[188:189], v[178:179], v[188:189], s[64:65] op_sel_hi:[1,1,0]
	v_pk_fma_f32 v[214:215], v[114:115], v[138:139], v[142:143]
	v_pk_fma_f32 v[188:189], v[178:179], v[188:189], s[66:67] op_sel_hi:[1,1,0]
	v_pk_fma_f32 v[170:171], v[128:129], v[170:171], v[218:219]
	v_pk_fma_f32 v[188:189], v[178:179], v[188:189], s[68:69] op_sel_hi:[1,1,0]
	v_pk_fma_f32 v[214:215], v[122:123], v[134:135], v[214:215]
	v_pk_mul_f32 v[178:179], v[178:179], v[188:189]
	v_pk_mul_f32 v[170:171], v[170:171], v[174:175]
	v_max_f32_e32 v174, 0, v176
	v_pk_mul_f32 v[178:179], v[184:185], v[178:179]
	v_max_f32_e32 v175, 0, v177
	v_pk_fma_f32 v[172:173], v[130:131], v[172:173], v[214:215]
	v_pk_fma_f32 v[174:175], v[180:181], v[178:179], v[174:175] neg_lo:[1,0,0] neg_hi:[1,0,0]
	v_add_lshl_u32 v165, v182, v164, 1
	v_pk_mul_f32 v[172:173], v[172:173], v[174:175]
	v_cvt_pk_bf16_f32 v170, v170, v171
	v_cvt_pk_bf16_f32 v171, v172, v173
	global_store_dwordx2 v165, v[170:171], s[40:41]
.LBB0_789:
	s_or_b64 exec, exec, s[10:11]
	v_add_u32_e32 v165, s25, v198
	v_cmp_gt_u32_e32 vcc, s59, v165
	v_mul_lo_u32 v183, v165, s73
	s_and_saveexec_b64 s[10:11], vcc
	s_cbranch_execz .LBB0_791
	v_pk_fma_f32 v[172:173], v[108:109], v[152:153], v[156:157]
	v_mov_b64_e32 v[212:213], s[62:63]
	v_pk_fma_f32 v[172:173], v[116:117], v[148:149], v[172:173]
	v_pk_fma_f32 v[170:171], v[110:111], v[154:155], v[158:159]
	v_pk_fma_f32 v[172:173], v[124:125], v[144:145], v[172:173]
	v_pk_fma_f32 v[170:171], v[118:119], v[150:151], v[170:171]
	v_and_b32_e32 v179, 0x7fffffff, v173
	v_and_b32_e32 v178, 0x7fffffff, v172
	v_pk_fma_f32 v[188:189], v[178:179], s[58:59], 1.0 op_sel_hi:[1,0,0]
	v_pk_mul_f32 v[184:185], v[172:173], v[172:173]
	v_rcp_f32_e32 v188, v188
	v_rcp_f32_e32 v189, v189
	v_pk_mul_f32 v[184:185], v[184:185], s[56:57] op_sel_hi:[1,0]
	v_pk_fma_f32 v[170:171], v[126:127], v[146:147], v[170:171]
	v_exp_f32_e32 v184, v184
	v_pk_fma_f32 v[214:215], v[188:189], s[60:61], v[212:213] op_sel_hi:[1,0,0]
	v_exp_f32_e32 v185, v185
	v_pk_fma_f32 v[214:215], v[188:189], v[214:215], s[64:65] op_sel_hi:[1,1,0]
	v_max_f32_e32 v174, 0, v172
	v_pk_fma_f32 v[214:215], v[188:189], v[214:215], s[66:67] op_sel_hi:[1,1,0]
	v_and_b32_e32 v177, 0x7fffffff, v171
	v_pk_fma_f32 v[214:215], v[188:189], v[214:215], s[68:69] op_sel_hi:[1,1,0]
	v_and_b32_e32 v176, 0x7fffffff, v170
	v_pk_mul_f32 v[188:189], v[188:189], v[214:215]
	v_max_f32_e32 v175, 0, v173
	v_pk_mul_f32 v[184:185], v[184:185], v[188:189]
	v_pk_mul_f32 v[180:181], v[170:171], v[170:171]
	v_pk_fma_f32 v[172:173], v[178:179], v[184:185], v[174:175] neg_lo:[1,0,0] neg_hi:[1,0,0]
	v_pk_fma_f32 v[174:175], v[176:177], s[58:59], 1.0 op_sel_hi:[1,0,0]
	v_pk_mul_f32 v[178:179], v[180:181], s[56:57] op_sel_hi:[1,0]
	v_rcp_f32_e32 v174, v174
	v_rcp_f32_e32 v175, v175
	v_exp_f32_e32 v178, v178
	v_exp_f32_e32 v179, v179
	v_pk_fma_f32 v[188:189], v[106:107], v[138:139], v[142:143]
	v_pk_fma_f32 v[180:181], v[174:175], s[60:61], v[212:213] op_sel_hi:[1,0,0]
	v_pk_fma_f32 v[214:215], v[104:105], v[136:137], v[140:141]
	v_pk_fma_f32 v[180:181], v[174:175], v[180:181], s[64:65] op_sel_hi:[1,1,0]
	v_pk_fma_f32 v[188:189], v[114:115], v[134:135], v[188:189]
	v_pk_fma_f32 v[180:181], v[174:175], v[180:181], s[66:67] op_sel_hi:[1,1,0]
	v_pk_fma_f32 v[214:215], v[112:113], v[132:133], v[214:215]
	v_pk_fma_f32 v[180:181], v[174:175], v[180:181], s[68:69] op_sel_hi:[1,1,0]
	v_max_f32_e32 v170, 0, v170
	v_pk_mul_f32 v[174:175], v[174:175], v[180:181]
	v_max_f32_e32 v171, 0, v171
	v_pk_mul_f32 v[174:175], v[178:179], v[174:175]
	v_pk_fma_f32 v[188:189], v[122:123], v[130:131], v[188:189]
	v_pk_fma_f32 v[214:215], v[120:121], v[128:129], v[214:215]
	v_pk_fma_f32 v[170:171], v[176:177], v[174:175], v[170:171] neg_lo:[1,0,0] neg_hi:[1,0,0]
	v_pk_mul_f32 v[172:173], v[214:215], v[172:173]
	v_pk_mul_f32 v[170:171], v[188:189], v[170:171]
	v_add_lshl_u32 v165, v183, v164, 1
	v_cvt_pk_bf16_f32 v172, v172, v173
	v_cvt_pk_bf16_f32 v173, v170, v171
	global_store_dwordx2 v165, v[172:173], s[40:41]
; __device__ __forceinline__ unsigned pk2(float lo, float hi) { const f32x2 v = {lo, hi}; return __builtin_bit_cast(unsigned, __builtin_convertvector(v, bf16x2_hw)); }
;     template <bool EDGE> __device__ __forceinline__ void body(const f32x4 (&acc)[2][2][4][2], const pg8::Unit& u, int wr, int wc, int fr, int fq) const {
;     ...
; #pragma unroll
;             for (int k = 0; k < 8; ++k) {
;                 const int ai = k >> 2, m = k & 3, lr = 8 * fr + k, tau = tw0 + lr, sp = tau & 4095;
;                 const f32x4 cv = acc[ai][0][m][n], cg = acc[ai][1][m][n];
;                 const f32x4 p1v = k >= 1 ? acc[(k >= 1 ? k - 1 : 0) >> 2][0][(k >= 1 ? k - 1 : 0) & 3][n] : v7;
;                 const f32x4 p1g = k >= 1 ? acc[(k >= 1 ? k - 1 : 0) >> 2][1][(k >= 1 ? k - 1 : 0) & 3][n] : g7;
;                 const f32x4 p2v = k >= 2 ? acc[(k >= 2 ? k - 2 : 0) >> 2][0][(k >= 2 ? k - 2 : 0) & 3][n] : (k == 1 ? v7 : v6);
;                 const f32x4 p2g = k >= 2 ? acc[(k >= 2 ? k - 2 : 0) >> 2][1][(k >= 2 ? k - 2 : 0) & 3][n] : (k == 1 ? g7 : g6);
;                 f32x4 val, gat;
;                 if (EDGE) { const float m1 = sp >= 1 ? 1.f : 0.f, m2 = sp >= 2 ? 1.f : 0.f;
;                     val = bv + wv2 * cv + (wv1 * m1) * p1v + (wv0 * m2) * p2v; gat = bg + wg2 * cg + (wg1 * m1) * p1g + (wg0 * m2) * p2g; }
;                 else { val = bv + wv2 * cv + wv1 * p1v + wv0 * p2v; gat = bg + wg2 * cg + wg1 * p1g + wg0 * p2g; }
;                 const f32x2 g01 = gelu_pk((f32x2){gat[0], gat[1]}), g23 = gelu_pk((f32x2){gat[2], gat[3]});
;                 u32x2 w; w.x = pk2(g01.x * val[0], g01.y * val[1]); w.y = pk2(g23.x * val[2], g23.y * val[3]);
;                 if (lr >= 2 && tau < NT) *(u32x2*)((char*)hidden + (unsigned)(tau * DFF + ch) * 2u) = w;
;             }
.LBB0_791:
	s_or_b64 exec, exec, s[10:11]
	v_add_u32_e32 v165, s25, v199
	v_cmp_gt_u32_e64 s[10:11], s59, v165
	v_mul_lo_u32 v184, v165, s73
	s_and_saveexec_b64 s[12:13], s[10:11]
	s_cbranch_execz .LBB0_793
	v_pk_fma_f32 v[172:173], v[100:101], v[152:153], v[156:157]
	v_mov_b64_e32 v[214:215], s[62:63]
	v_pk_fma_f32 v[172:173], v[108:109], v[148:149], v[172:173]
	v_pk_fma_f32 v[170:171], v[102:103], v[154:155], v[158:159]
	v_pk_fma_f32 v[172:173], v[116:117], v[144:145], v[172:173]
	v_pk_fma_f32 v[170:171], v[110:111], v[150:151], v[170:171]
	v_and_b32_e32 v179, 0x7fffffff, v173
	v_and_b32_e32 v178, 0x7fffffff, v172
	v_pk_fma_f32 v[212:213], v[178:179], s[58:59], 1.0 op_sel_hi:[1,0,0]
	v_pk_mul_f32 v[188:189], v[172:173], v[172:173]
	v_rcp_f32_e32 v212, v212
	v_rcp_f32_e32 v213, v213
	v_pk_mul_f32 v[188:189], v[188:189], s[56:57] op_sel_hi:[1,0]
	v_pk_fma_f32 v[170:171], v[118:119], v[146:147], v[170:171]
	v_exp_f32_e32 v188, v188
	v_pk_fma_f32 v[216:217], v[212:213], s[60:61], v[214:215] op_sel_hi:[1,0,0]
	v_exp_f32_e32 v189, v189
	v_pk_fma_f32 v[216:217], v[212:213], v[216:217], s[64:65] op_sel_hi:[1,1,0]
	v_max_f32_e32 v174, 0, v172
	v_pk_fma_f32 v[216:217], v[212:213], v[216:217], s[66:67] op_sel_hi:[1,1,0]
	v_and_b32_e32 v177, 0x7fffffff, v171
	v_pk_fma_f32 v[216:217], v[212:213], v[216:217], s[68:69] op_sel_hi:[1,1,0]
	v_and_b32_e32 v176, 0x7fffffff, v170
	v_pk_mul_f32 v[212:213], v[212:213], v[216:217]
	v_max_f32_e32 v175, 0, v173
	v_pk_mul_f32 v[188:189], v[188:189], v[212:213]
	v_pk_mul_f32 v[180:181], v[170:171], v[170:171]
	v_pk_fma_f32 v[172:173], v[178:179], v[188:189], v[174:175] neg_lo:[1,0,0] neg_hi:[1,0,0]
	v_pk_fma_f32 v[174:175], v[176:177], s[58:59], 1.0 op_sel_hi:[1,0,0]
	v_pk_mul_f32 v[178:179], v[180:181], s[56:57] op_sel_hi:[1,0]
	v_rcp_f32_e32 v174, v174
	v_rcp_f32_e32 v175, v175
	v_exp_f32_e32 v178, v178
	v_exp_f32_e32 v179, v179
	v_pk_fma_f32 v[212:213], v[98:99], v[138:139], v[142:143]
	v_pk_fma_f32 v[180:181], v[174:175], s[60:61], v[214:215] op_sel_hi:[1,0,0]
	v_pk_fma_f32 v[216:217], v[96:97], v[136:137], v[140:141]
	v_pk_fma_f32 v[180:181], v[174:175], v[180:181], s[64:65] op_sel_hi:[1,1,0]
	v_pk_fma_f32 v[212:213], v[106:107], v[134:135], v[212:213]
	v_pk_fma_f32 v[180:181], v[174:175], v[180:181], s[66:67] op_sel_hi:[1,1,0]
	v_pk_fma_f32 v[216:217], v[104:105], v[132:133], v[216:217]
	v_pk_fma_f32 v[180:181], v[174:175], v[180:181], s[68:69] op_sel_hi:[1,1,0]
	v_max_f32_e32 v170, 0, v170
	v_pk_mul_f32 v[174:175], v[174:175], v[180:181]
	v_max_f32_e32 v171, 0, v171
	v_pk_mul_f32 v[174:175], v[178:179], v[174:175]
	v_pk_fma_f32 v[212:213], v[114:115], v[130:131], v[212:213]
	v_pk_fma_f32 v[216:217], v[112:113], v[128:129], v[216:217]
	v_pk_fma_f32 v[170:171], v[176:177], v[174:175], v[170:171] neg_lo:[1,0,0] neg_hi:[1,0,0]
	v_pk_mul_f32 v[172:173], v[216:217], v[172:173]
	v_pk_mul_f32 v[170:171], v[212:213], v[170:171]
	v_add_lshl_u32 v165, v184, v164, 1
	v_cvt_pk_bf16_f32 v172, v172, v173
	v_cvt_pk_bf16_f32 v173, v170, v171
	global_store_dwordx2 v165, v[172:173], s[40:41]
.LBB0_793:
	s_or_b64 exec, exec, s[12:13]
	v_add_u32_e32 v165, s25, v200
	v_cmp_gt_u32_e64 s[12:13], s59, v165
	v_mul_lo_u32 v185, v165, s73
	s_and_saveexec_b64 s[14:15], s[12:13]
	s_cbranch_execz .LBB0_795
	v_pk_fma_f32 v[172:173], v[92:93], v[152:153], v[156:157]
	v_mov_b64_e32 v[214:215], s[62:63]
	v_pk_fma_f32 v[172:173], v[100:101], v[148:149], v[172:173]
	v_pk_fma_f32 v[170:171], v[94:95], v[154:155], v[158:159]
	v_pk_fma_f32 v[172:173], v[108:109], v[144:145], v[172:173]
	v_pk_fma_f32 v[170:171], v[102:103], v[150:151], v[170:171]
	v_and_b32_e32 v179, 0x7fffffff, v173
	v_and_b32_e32 v178, 0x7fffffff, v172
	v_pk_fma_f32 v[212:213], v[178:179], s[58:59], 1.0 op_sel_hi:[1,0,0]
	v_pk_mul_f32 v[188:189], v[172:173], v[172:173]
	v_rcp_f32_e32 v212, v212
	v_rcp_f32_e32 v213, v213
	v_pk_mul_f32 v[188:189], v[188:189], s[56:57] op_sel_hi:[1,0]
	v_pk_fma_f32 v[170:171], v[110:111], v[146:147], v[170:171]
	v_exp_f32_e32 v188, v188
	v_pk_fma_f32 v[216:217], v[212:213], s[60:61], v[214:215] op_sel_hi:[1,0,0]
	v_exp_f32_e32 v189, v189
	v_pk_fma_f32 v[216:217], v[212:213], v[216:217], s[64:65] op_sel_hi:[1,1,0]
	v_max_f32_e32 v174, 0, v172
	v_pk_fma_f32 v[216:217], v[212:213], v[216:217], s[66:67] op_sel_hi:[1,1,0]
	v_and_b32_e32 v177, 0x7fffffff, v171
	v_pk_fma_f32 v[216:217], v[212:213], v[216:217], s[68:69] op_sel_hi:[1,1,0]
	v_and_b32_e32 v176, 0x7fffffff, v170
	v_pk_mul_f32 v[212:213], v[212:213], v[216:217]
	v_max_f32_e32 v175, 0, v173
	v_pk_mul_f32 v[188:189], v[188:189], v[212:213]
	v_pk_mul_f32 v[180:181], v[170:171], v[170:171]
	v_pk_fma_f32 v[172:173], v[178:179], v[188:189], v[174:175] neg_lo:[1,0,0] neg_hi:[1,0,0]
	v_pk_fma_f32 v[174:175], v[176:177], s[58:59], 1.0 op_sel_hi:[1,0,0]
	v_pk_mul_f32 v[178:179], v[180:181], s[56:57] op_sel_hi:[1,0]
	v_rcp_f32_e32 v174, v174
	v_rcp_f32_e32 v175, v175
	v_exp_f32_e32 v178, v178
	v_exp_f32_e32 v179, v179
	v_pk_fma_f32 v[212:213], v[90:91], v[138:139], v[142:143]
	v_pk_fma_f32 v[180:181], v[174:175], s[60:61], v[214:215] op_sel_hi:[1,0,0]
	v_pk_fma_f32 v[216:217], v[88:89], v[136:137], v[140:141]
	v_pk_fma_f32 v[180:181], v[174:175], v[180:181], s[64:65] op_sel_hi:[1,1,0]
	v_pk_fma_f32 v[212:213], v[98:99], v[134:135], v[212:213]
	v_pk_fma_f32 v[180:181], v[174:175], v[180:181], s[66:67] op_sel_hi:[1,1,0]
	v_pk_fma_f32 v[216:217], v[96:97], v[132:133], v[216:217]
	v_pk_fma_f32 v[180:181], v[174:175], v[180:181], s[68:69] op_sel_hi:[1,1,0]
	v_max_f32_e32 v170, 0, v170
	v_pk_mul_f32 v[174:175], v[174:175], v[180:181]
	v_max_f32_e32 v171, 0, v171
	v_pk_mul_f32 v[174:175], v[178:179], v[174:175]
	v_pk_fma_f32 v[212:213], v[106:107], v[130:131], v[212:213]
	v_pk_fma_f32 v[216:217], v[104:105], v[128:129], v[216:217]
	v_pk_fma_f32 v[170:171], v[176:177], v[174:175], v[170:171] neg_lo:[1,0,0] neg_hi:[1,0,0]
	v_pk_mul_f32 v[172:173], v[216:217], v[172:173]
	v_pk_mul_f32 v[170:171], v[212:213], v[170:171]
	v_add_lshl_u32 v165, v185, v164, 1
	v_cvt_pk_bf16_f32 v172, v172, v173
	v_cvt_pk_bf16_f32 v173, v170, v171
	global_store_dwordx2 v165, v[172:173], s[40:41]
; __device__ __forceinline__ unsigned pk2(float lo, float hi) { const f32x2 v = {lo, hi}; return __builtin_bit_cast(unsigned, __builtin_convertvector(v, bf16x2_hw)); }
;     template <bool EDGE> __device__ __forceinline__ void body(const f32x4 (&acc)[2][2][4][2], const pg8::Unit& u, int wr, int wc, int fr, int fq) const {
;     ...
; #pragma unroll
;             for (int k = 0; k < 8; ++k) {
;                 const int ai = k >> 2, m = k & 3, lr = 8 * fr + k, tau = tw0 + lr, sp = tau & 4095;
;                 const f32x4 cv = acc[ai][0][m][n], cg = acc[ai][1][m][n];
;                 const f32x4 p1v = k >= 1 ? acc[(k >= 1 ? k - 1 : 0) >> 2][0][(k >= 1 ? k - 1 : 0) & 3][n] : v7;
;                 const f32x4 p1g = k >= 1 ? acc[(k >= 1 ? k - 1 : 0) >> 2][1][(k >= 1 ? k - 1 : 0) & 3][n] : g7;
;                 const f32x4 p2v = k >= 2 ? acc[(k >= 2 ? k - 2 : 0) >> 2][0][(k >= 2 ? k - 2 : 0) & 3][n] : (k == 1 ? v7 : v6);
;                 const f32x4 p2g = k >= 2 ? acc[(k >= 2 ? k - 2 : 0) >> 2][1][(k >= 2 ? k - 2 : 0) & 3][n] : (k == 1 ? g7 : g6);
;                 f32x4 val, gat;
;                 if (EDGE) { const float m1 = sp >= 1 ? 1.f : 0.f, m2 = sp >= 2 ? 1.f : 0.f;
;                     val = bv + wv2 * cv + (wv1 * m1) * p1v + (wv0 * m2) * p2v; gat = bg + wg2 * cg + (wg1 * m1) * p1g + (wg0 * m2) * p2g; }
;                 else { val = bv + wv2 * cv + wv1 * p1v + wv0 * p2v; gat = bg + wg2 * cg + wg1 * p1g + wg0 * p2g; }
;                 const f32x2 g01 = gelu_pk((f32x2){gat[0], gat[1]}), g23 = gelu_pk((f32x2){gat[2], gat[3]});
;                 u32x2 w; w.x = pk2(g01.x * val[0], g01.y * val[1]); w.y = pk2(g23.x * val[2], g23.y * val[3]);
;                 if (lr >= 2 && tau < NT) *(u32x2*)((char*)hidden + (unsigned)(tau * DFF + ch) * 2u) = w;
;             }
.LBB0_795:
	s_or_b64 exec, exec, s[14:15]
	v_add_u32_e32 v165, s25, v201
	v_cmp_gt_u32_e64 s[14:15], s59, v165
	v_mul_lo_u32 v211, v165, s73
	s_and_saveexec_b64 s[16:17], s[14:15]
	s_cbranch_execz .LBB0_797
	v_pk_fma_f32 v[172:173], v[76:77], v[152:153], v[156:157]
	v_mov_b64_e32 v[214:215], s[62:63]
	v_pk_fma_f32 v[172:173], v[92:93], v[148:149], v[172:173]
	v_pk_fma_f32 v[170:171], v[78:79], v[154:155], v[158:159]
	v_pk_fma_f32 v[172:173], v[100:101], v[144:145], v[172:173]
	v_pk_fma_f32 v[170:171], v[94:95], v[150:151], v[170:171]
	v_and_b32_e32 v179, 0x7fffffff, v173
	v_and_b32_e32 v178, 0x7fffffff, v172
	v_pk_fma_f32 v[212:213], v[178:179], s[58:59], 1.0 op_sel_hi:[1,0,0]
	v_pk_mul_f32 v[188:189], v[172:173], v[172:173]
	v_rcp_f32_e32 v212, v212
	v_rcp_f32_e32 v213, v213
	v_pk_mul_f32 v[188:189], v[188:189], s[56:57] op_sel_hi:[1,0]
	v_pk_fma_f32 v[170:171], v[102:103], v[146:147], v[170:171]
	v_exp_f32_e32 v188, v188
	v_pk_fma_f32 v[216:217], v[212:213], s[60:61], v[214:215] op_sel_hi:[1,0,0]
	v_exp_f32_e32 v189, v189
	v_pk_fma_f32 v[216:217], v[212:213], v[216:217], s[64:65] op_sel_hi:[1,1,0]
	v_max_f32_e32 v174, 0, v172
	v_pk_fma_f32 v[216:217], v[212:213], v[216:217], s[66:67] op_sel_hi:[1,1,0]
	v_and_b32_e32 v177, 0x7fffffff, v171
	v_pk_fma_f32 v[216:217], v[212:213], v[216:217], s[68:69] op_sel_hi:[1,1,0]
	v_and_b32_e32 v176, 0x7fffffff, v170
	v_pk_mul_f32 v[212:213], v[212:213], v[216:217]
	v_max_f32_e32 v175, 0, v173
	v_pk_mul_f32 v[188:189], v[188:189], v[212:213]
	v_pk_mul_f32 v[180:181], v[170:171], v[170:171]
	v_pk_fma_f32 v[172:173], v[178:179], v[188:189], v[174:175] neg_lo:[1,0,0] neg_hi:[1,0,0]
	v_pk_fma_f32 v[174:175], v[176:177], s[58:59], 1.0 op_sel_hi:[1,0,0]
	v_pk_mul_f32 v[178:179], v[180:181], s[56:57] op_sel_hi:[1,0]
	v_rcp_f32_e32 v174, v174
	v_rcp_f32_e32 v175, v175
	v_exp_f32_e32 v178, v178
	v_exp_f32_e32 v179, v179
	v_pk_fma_f32 v[212:213], v[74:75], v[138:139], v[142:143]
	v_pk_fma_f32 v[180:181], v[174:175], s[60:61], v[214:215] op_sel_hi:[1,0,0]
	v_pk_fma_f32 v[216:217], v[72:73], v[136:137], v[140:141]
	v_pk_fma_f32 v[180:181], v[174:175], v[180:181], s[64:65] op_sel_hi:[1,1,0]
	v_pk_fma_f32 v[212:213], v[90:91], v[134:135], v[212:213]
	v_pk_fma_f32 v[180:181], v[174:175], v[180:181], s[66:67] op_sel_hi:[1,1,0]
	v_pk_fma_f32 v[216:217], v[88:89], v[132:133], v[216:217]
	v_pk_fma_f32 v[180:181], v[174:175], v[180:181], s[68:69] op_sel_hi:[1,1,0]
	v_max_f32_e32 v170, 0, v170
	v_pk_mul_f32 v[174:175], v[174:175], v[180:181]
	v_max_f32_e32 v171, 0, v171
	v_pk_mul_f32 v[174:175], v[178:179], v[174:175]
	v_pk_fma_f32 v[212:213], v[98:99], v[130:131], v[212:213]
	v_pk_fma_f32 v[216:217], v[96:97], v[128:129], v[216:217]
	v_pk_fma_f32 v[170:171], v[176:177], v[174:175], v[170:171] neg_lo:[1,0,0] neg_hi:[1,0,0]
	v_pk_mul_f32 v[172:173], v[216:217], v[172:173]
	v_pk_mul_f32 v[170:171], v[212:213], v[170:171]
	v_add_lshl_u32 v165, v211, v164, 1
	v_cvt_pk_bf16_f32 v172, v172, v173
	v_cvt_pk_bf16_f32 v173, v170, v171
	global_store_dwordx2 v165, v[172:173], s[40:41]
.LBB0_797:
	s_or_b64 exec, exec, s[16:17]
	v_add_u32_e32 v165, s25, v202
	v_cmp_gt_u32_e64 s[16:17], s59, v165
	v_mul_lo_u32 v212, v165, s73
	s_and_saveexec_b64 s[18:19], s[16:17]
	s_cbranch_execz .LBB0_799
	v_pk_fma_f32 v[172:173], v[84:85], v[152:153], v[156:157]
	v_mov_b64_e32 v[216:217], s[62:63]
	v_pk_fma_f32 v[172:173], v[76:77], v[148:149], v[172:173]
	v_pk_fma_f32 v[170:171], v[86:87], v[154:155], v[158:159]
	v_pk_fma_f32 v[172:173], v[92:93], v[144:145], v[172:173]
	v_pk_fma_f32 v[170:171], v[78:79], v[150:151], v[170:171]
	v_and_b32_e32 v179, 0x7fffffff, v173
	v_and_b32_e32 v178, 0x7fffffff, v172
	v_pk_fma_f32 v[214:215], v[178:179], s[58:59], 1.0 op_sel_hi:[1,0,0]
	v_pk_mul_f32 v[188:189], v[172:173], v[172:173]
	v_rcp_f32_e32 v214, v214
	v_rcp_f32_e32 v215, v215
	v_pk_mul_f32 v[188:189], v[188:189], s[56:57] op_sel_hi:[1,0]
	v_pk_fma_f32 v[170:171], v[94:95], v[146:147], v[170:171]
	v_exp_f32_e32 v188, v188
	v_pk_fma_f32 v[218:219], v[214:215], s[60:61], v[216:217] op_sel_hi:[1,0,0]
	v_exp_f32_e32 v189, v189
	v_pk_fma_f32 v[218:219], v[214:215], v[218:219], s[64:65] op_sel_hi:[1,1,0]
	v_max_f32_e32 v174, 0, v172
	v_pk_fma_f32 v[218:219], v[214:215], v[218:219], s[66:67] op_sel_hi:[1,1,0]
	v_and_b32_e32 v177, 0x7fffffff, v171
	v_pk_fma_f32 v[218:219], v[214:215], v[218:219], s[68:69] op_sel_hi:[1,1,0]
	v_and_b32_e32 v176, 0x7fffffff, v170
	v_pk_mul_f32 v[214:215], v[214:215], v[218:219]
	v_max_f32_e32 v175, 0, v173
	v_pk_mul_f32 v[188:189], v[188:189], v[214:215]
	v_pk_mul_f32 v[180:181], v[170:171], v[170:171]
	v_pk_fma_f32 v[172:173], v[178:179], v[188:189], v[174:175] neg_lo:[1,0,0] neg_hi:[1,0,0]
	v_pk_fma_f32 v[174:175], v[176:177], s[58:59], 1.0 op_sel_hi:[1,0,0]
	v_pk_mul_f32 v[178:179], v[180:181], s[56:57] op_sel_hi:[1,0]
	v_rcp_f32_e32 v174, v174
	v_rcp_f32_e32 v175, v175
	v_exp_f32_e32 v178, v178
	v_exp_f32_e32 v179, v179
	v_pk_fma_f32 v[214:215], v[70:71], v[138:139], v[142:143]
	v_pk_fma_f32 v[180:181], v[174:175], s[60:61], v[216:217] op_sel_hi:[1,0,0]
	v_pk_fma_f32 v[218:219], v[68:69], v[136:137], v[140:141]
	v_pk_fma_f32 v[180:181], v[174:175], v[180:181], s[64:65] op_sel_hi:[1,1,0]
	v_pk_fma_f32 v[214:215], v[74:75], v[134:135], v[214:215]
	v_pk_fma_f32 v[180:181], v[174:175], v[180:181], s[66:67] op_sel_hi:[1,1,0]
	v_pk_fma_f32 v[218:219], v[72:73], v[132:133], v[218:219]
	v_pk_fma_f32 v[180:181], v[174:175], v[180:181], s[68:69] op_sel_hi:[1,1,0]
	v_max_f32_e32 v170, 0, v170
	v_pk_mul_f32 v[174:175], v[174:175], v[180:181]
	v_max_f32_e32 v171, 0, v171
	v_pk_mul_f32 v[174:175], v[178:179], v[174:175]
	v_pk_fma_f32 v[214:215], v[90:91], v[130:131], v[214:215]
	v_pk_fma_f32 v[218:219], v[88:89], v[128:129], v[218:219]
	v_pk_fma_f32 v[170:171], v[176:177], v[174:175], v[170:171] neg_lo:[1,0,0] neg_hi:[1,0,0]
	v_pk_mul_f32 v[172:173], v[218:219], v[172:173]
	v_pk_mul_f32 v[170:171], v[214:215], v[170:171]
	v_add_lshl_u32 v165, v212, v164, 1
	v_cvt_pk_bf16_f32 v172, v172, v173
	v_cvt_pk_bf16_f32 v173, v170, v171
	global_store_dwordx2 v165, v[172:173], s[40:41]
;     template <bool EDGE> __device__ __forceinline__ void body(const f32x4 (&acc)[2][2][4][2], const pg8::Unit& u, int wr, int wc, int fr, int fq) const {
;     ...
;         for (int n = 0; n < 2; ++n) {
;             const int ch = chb + 4 * n;
;             const f32x4 wv0 = *(const f32x4*)(conv_w + ch), wv1 = *(const f32x4*)(conv_w + NUP + ch), wv2 = *(const f32x4*)(conv_w + 2 * NUP + ch), bv = *(const f32x4*)(conv_b + ch);
;             const f32x4 wg0 = *(const f32x4*)(conv_w + DFF + ch), wg1 = *(const f32x4*)(conv_w + NUP + DFF + ch), wg2 = *(const f32x4*)(conv_w + 2 * NUP + DFF + ch), bg = *(const f32x4*)(conv_b + DFF + ch);
;             const f32x4 v7 = dpp_shr1(acc[1][0][3][n]), v6 = dpp_shr1(acc[1][0][2][n]), g7 = dpp_shr1(acc[1][1][3][n]), g6 = dpp_shr1(acc[1][1][2][n]);
; #pragma unroll
;             for (int k = 0; k < 8; ++k) {
;                 const int ai = k >> 2, m = k & 3, lr = 8 * fr + k, tau = tw0 + lr, sp = tau & 4095;
;                 const f32x4 cv = acc[ai][0][m][n], cg = acc[ai][1][m][n];
;                 const f32x4 p1v = k >= 1 ? acc[(k >= 1 ? k - 1 : 0) >> 2][0][(k >= 1 ? k - 1 : 0) & 3][n] : v7;
;                 const f32x4 p1g = k >= 1 ? acc[(k >= 1 ? k - 1 : 0) >> 2][1][(k >= 1 ? k - 1 : 0) & 3][n] : g7;
;                 const f32x4 p2v = k >= 2 ? acc[(k >= 2 ? k - 2 : 0) >> 2][0][(k >= 2 ? k - 2 : 0) & 3][n] : (k == 1 ? v7 : v6);
;                 const f32x4 p2g = k >= 2 ? acc[(k >= 2 ? k - 2 : 0) >> 2][1][(k >= 2 ? k - 2 : 0) & 3][n] : (k == 1 ? g7 : g6);
;                 f32x4 val, gat;
;                 if (EDGE) { const float m1 = sp >= 1 ? 1.f : 0.f, m2 = sp >= 2 ? 1.f : 0.f;
;                     val = bv + wv2 * cv + (wv1 * m1) * p1v + (wv0 * m2) * p2v; gat = bg + wg2 * cg + (wg1 * m1) * p1g + (wg0 * m2) * p2g; }
;                 else { val = bv + wv2 * cv + wv1 * p1v + wv0 * p2v; gat = bg + wg2 * cg + wg1 * p1g + wg0 * p2g; }
;                 const f32x2 g01 = gelu_pk((f32x2){gat[0], gat[1]}), g23 = gelu_pk((f32x2){gat[2], gat[3]});
;                 u32x2 w; w.x = pk2(g01.x * val[0], g01.y * val[1]); w.y = pk2(g23.x * val[2], g23.y * val[3]);
;                 if (lr >= 2 && tau < NT) *(u32x2*)((char*)hidden + (unsigned)(tau * DFF + ch) * 2u) = w;
;             }
.LBB0_799:
	s_or_b64 exec, exec, s[18:19]
	v_add_u32_e32 v165, s25, v203
	v_cmp_gt_u32_e64 s[18:19], s59, v165
	v_mul_lo_u32 v213, v165, s73
	s_and_saveexec_b64 s[20:21], s[18:19]
	s_cbranch_execz .LBB0_801
	v_pk_fma_f32 v[152:153], v[80:81], v[152:153], v[156:157]
	v_pk_fma_f32 v[154:155], v[82:83], v[154:155], v[158:159]
	v_pk_fma_f32 v[148:149], v[84:85], v[148:149], v[152:153]
	v_pk_fma_f32 v[150:151], v[86:87], v[150:151], v[154:155]
	v_pk_fma_f32 v[144:145], v[76:77], v[144:145], v[148:149]
	v_pk_fma_f32 v[146:147], v[78:79], v[146:147], v[150:151]
	v_and_b32_e32 v153, 0x7fffffff, v145
	v_and_b32_e32 v152, 0x7fffffff, v144
	v_pk_fma_f32 v[158:159], v[152:153], s[58:59], 1.0 op_sel_hi:[1,0,0]
	v_pk_fma_f32 v[138:139], v[66:67], v[138:139], v[142:143]
	v_and_b32_e32 v151, 0x7fffffff, v147
	v_and_b32_e32 v150, 0x7fffffff, v146
	v_rcp_f32_e32 v158, v158
	v_rcp_f32_e32 v159, v159
	v_pk_fma_f32 v[134:135], v[70:71], v[134:135], v[138:139]
	v_pk_mul_f32 v[156:157], v[144:145], v[144:145]
	v_pk_fma_f32 v[130:131], v[74:75], v[130:131], v[134:135]
	v_pk_fma_f32 v[134:135], v[150:151], s[58:59], 1.0 op_sel_hi:[1,0,0]
	v_mov_b64_e32 v[170:171], s[62:63]
	v_rcp_f32_e32 v134, v134
	v_rcp_f32_e32 v135, v135
	v_pk_mul_f32 v[156:157], v[156:157], s[56:57] op_sel_hi:[1,0]
	v_pk_fma_f32 v[172:173], v[158:159], s[60:61], v[170:171] op_sel_hi:[1,0,0]
	v_pk_mul_f32 v[154:155], v[146:147], v[146:147]
	v_exp_f32_e32 v156, v156
	v_exp_f32_e32 v157, v157
	v_pk_fma_f32 v[172:173], v[158:159], v[172:173], s[64:65] op_sel_hi:[1,1,0]
	v_pk_fma_f32 v[136:137], v[64:65], v[136:137], v[140:141]
	v_pk_fma_f32 v[172:173], v[158:159], v[172:173], s[66:67] op_sel_hi:[1,1,0]
	v_pk_fma_f32 v[132:133], v[68:69], v[132:133], v[136:137]
	v_pk_mul_f32 v[136:137], v[154:155], s[56:57] op_sel_hi:[1,0]
	v_pk_fma_f32 v[138:139], v[134:135], s[60:61], v[170:171] op_sel_hi:[1,0,0]
	v_pk_fma_f32 v[172:173], v[158:159], v[172:173], s[68:69] op_sel_hi:[1,1,0]
	v_exp_f32_e32 v136, v136
	v_exp_f32_e32 v137, v137
	v_pk_fma_f32 v[138:139], v[134:135], v[138:139], s[64:65] op_sel_hi:[1,1,0]
	v_pk_mul_f32 v[158:159], v[158:159], v[172:173]
	v_pk_fma_f32 v[138:139], v[134:135], v[138:139], s[66:67] op_sel_hi:[1,1,0]
	v_max_f32_e32 v148, 0, v144
	v_pk_mul_f32 v[156:157], v[156:157], v[158:159]
	v_max_f32_e32 v149, 0, v145
	v_pk_fma_f32 v[138:139], v[134:135], v[138:139], s[68:69] op_sel_hi:[1,1,0]
	v_pk_fma_f32 v[128:129], v[72:73], v[128:129], v[132:133]
	v_pk_fma_f32 v[132:133], v[152:153], v[156:157], v[148:149] neg_lo:[1,0,0] neg_hi:[1,0,0]
	v_pk_mul_f32 v[134:135], v[134:135], v[138:139]
	v_pk_mul_f32 v[128:129], v[128:129], v[132:133]
	v_max_f32_e32 v132, 0, v146
	v_pk_mul_f32 v[134:135], v[136:137], v[134:135]
	v_max_f32_e32 v133, 0, v147
	v_pk_fma_f32 v[132:133], v[150:151], v[134:135], v[132:133] neg_lo:[1,0,0] neg_hi:[1,0,0]
	v_add_lshl_u32 v165, v213, v164, 1
	v_pk_mul_f32 v[130:131], v[130:131], v[132:133]
	v_cvt_pk_bf16_f32 v128, v128, v129
	v_cvt_pk_bf16_f32 v129, v130, v131
	global_store_dwordx2 v165, v[128:129], s[40:41]
.LBB0_801:
	s_or_b64 exec, exec, s[20:21]
	v_or_b32_e32 v164, 4, v164
	v_ashrrev_i32_e32 v165, 31, v164
	s_waitcnt vmcnt(0)
	v_lshlrev_b64 v[156:157], 2, v[164:165]
	v_lshl_add_u64 v[132:133], s[44:45], 0, v[156:157]
	v_lshl_add_u64 v[136:137], s[46:47], 0, v[156:157]
	global_load_dwordx4 v[128:131], v[166:167], off offset:16
	s_nop 0
	global_load_dwordx4 v[132:135], v[132:133], off
	s_nop 0
	global_load_dwordx4 v[136:139], v[136:137], off
	s_nop 0
	global_load_dwordx4 v[140:143], v[168:169], off offset:16
	v_lshl_add_u64 v[144:145], s[48:49], 0, v[156:157]
	v_lshl_add_u64 v[148:149], s[50:51], 0, v[156:157]
	v_lshl_add_u64 v[152:153], s[52:53], 0, v[156:157]
	v_lshl_add_u64 v[156:157], s[54:55], 0, v[156:157]
	global_load_dwordx4 v[144:147], v[144:145], off
	s_nop 0
	global_load_dwordx4 v[148:151], v[148:149], off
	v_mov_b32_e32 v166, 0
	global_load_dwordx4 v[152:155], v[152:153], off
	v_mov_b32_e32 v167, 0
	global_load_dwordx4 v[156:159], v[156:157], off
	v_mov_b32_e32 v168, 0
	v_mov_b32_e32 v169, 0
	v_mov_b32_e32 v174, 0
	v_mov_b32_e32 v175, 0
	v_mov_b32_e32 v176, 0
	v_mov_b32_e32 v177, 0
	v_mov_b32_e32 v170, 0
	v_mov_b32_e32 v171, 0
	v_mov_b32_e32 v172, 0
	v_mov_b32_e32 v173, 0
	v_mov_b32_e32 v178, 0
	v_mov_b32_e32 v179, 0
	v_mov_b32_e32 v180, 0
	v_mov_b32_e32 v181, 0
	v_mov_b32_dpp v166, v0 row_shr:1 row_mask:0xf bank_mask:0xf
	v_mov_b32_dpp v167, v1 row_shr:1 row_mask:0xf bank_mask:0xf
	v_mov_b32_dpp v168, v2 row_shr:1 row_mask:0xf bank_mask:0xf
	v_mov_b32_dpp v169, v3 row_shr:1 row_mask:0xf bank_mask:0xf
	v_mov_b32_dpp v174, v4 row_shr:1 row_mask:0xf bank_mask:0xf
	v_mov_b32_dpp v175, v5 row_shr:1 row_mask:0xf bank_mask:0xf
	v_mov_b32_dpp v176, v6 row_shr:1 row_mask:0xf bank_mask:0xf
	v_mov_b32_dpp v177, v7 row_shr:1 row_mask:0xf bank_mask:0xf
	v_mov_b32_dpp v170, v12 row_shr:1 row_mask:0xf bank_mask:0xf
	v_mov_b32_dpp v171, v13 row_shr:1 row_mask:0xf bank_mask:0xf
	v_mov_b32_dpp v172, v14 row_shr:1 row_mask:0xf bank_mask:0xf
	v_mov_b32_dpp v173, v15 row_shr:1 row_mask:0xf bank_mask:0xf
	v_mov_b32_dpp v178, v20 row_shr:1 row_mask:0xf bank_mask:0xf
	v_mov_b32_dpp v179, v21 row_shr:1 row_mask:0xf bank_mask:0xf
	v_mov_b32_dpp v180, v22 row_shr:1 row_mask:0xf bank_mask:0xf
	v_mov_b32_dpp v181, v23 row_shr:1 row_mask:0xf bank_mask:0xf
	s_waitcnt vmcnt(0)
	s_and_saveexec_b64 s[20:21], s[0:1]
	s_cbranch_execnz .LBB0_848
	s_or_b64 exec, exec, s[20:21]
	s_and_saveexec_b64 s[0:1], s[2:3]
	s_cbranch_execnz .LBB0_849

; __device__ __forceinline__ unsigned pk2(float lo, float hi) { const f32x2 v = {lo, hi}; return __builtin_bit_cast(unsigned, __builtin_convertvector(v, bf16x2_hw)); }
;     template <bool EDGE> __device__ __forceinline__ void body(const f32x4 (&acc)[2][2][4][2], const pg8::Unit& u, int wr, int wc, int fr, int fq) const {
;     ...
; #pragma unroll
;             for (int k = 0; k < 8; ++k) {
;                 const int ai = k >> 2, m = k & 3, lr = 8 * fr + k, tau = tw0 + lr, sp = tau & 4095;
;                 const f32x4 cv = acc[ai][0][m][n], cg = acc[ai][1][m][n];
;                 const f32x4 p1v = k >= 1 ? acc[(k >= 1 ? k - 1 : 0) >> 2][0][(k >= 1 ? k - 1 : 0) & 3][n] : v7;
;                 const f32x4 p1g = k >= 1 ? acc[(k >= 1 ? k - 1 : 0) >> 2][1][(k >= 1 ? k - 1 : 0) & 3][n] : g7;
;                 const f32x4 p2v = k >= 2 ? acc[(k >= 2 ? k - 2 : 0) >> 2][0][(k >= 2 ? k - 2 : 0) & 3][n] : (k == 1 ? v7 : v6);
;                 const f32x4 p2g = k >= 2 ? acc[(k >= 2 ? k - 2 : 0) >> 2][1][(k >= 2 ? k - 2 : 0) & 3][n] : (k == 1 ? g7 : g6);
;                 f32x4 val, gat;
;                 if (EDGE) { const float m1 = sp >= 1 ? 1.f : 0.f, m2 = sp >= 2 ? 1.f : 0.f;
;                     val = bv + wv2 * cv + (wv1 * m1) * p1v + (wv0 * m2) * p2v; gat = bg + wg2 * cg + (wg1 * m1) * p1g + (wg0 * m2) * p2g; }
;                 else { val = bv + wv2 * cv + wv1 * p1v + wv0 * p2v; gat = bg + wg2 * cg + wg1 * p1g + wg0 * p2g; }
;                 const f32x2 g01 = gelu_pk((f32x2){gat[0], gat[1]}), g23 = gelu_pk((f32x2){gat[2], gat[3]});
;                 u32x2 w; w.x = pk2(g01.x * val[0], g01.y * val[1]); w.y = pk2(g23.x * val[2], g23.y * val[3]);
;                 if (lr >= 2 && tau < NT) *(u32x2*)((char*)hidden + (unsigned)(tau * DFF + ch) * 2u) = w;
;             }
.LBB0_809:
	v_pk_fma_f32 v[152:153], v[12:13], v[152:153], v[156:157]
	v_pk_fma_f32 v[154:155], v[14:15], v[154:155], v[158:159]
	v_pk_fma_f32 v[148:149], v[20:21], v[148:149], v[152:153]
	v_pk_fma_f32 v[150:151], v[22:23], v[150:151], v[154:155]
	v_pk_fma_f32 v[144:145], v[16:17], v[144:145], v[148:149]
	v_pk_fma_f32 v[146:147], v[18:19], v[146:147], v[150:151]
	v_and_b32_e32 v153, 0x7fffffff, v145
	v_and_b32_e32 v152, 0x7fffffff, v144
	v_pk_fma_f32 v[158:159], v[152:153], s[58:59], 1.0 op_sel_hi:[1,0,0]
	v_pk_fma_f32 v[138:139], v[2:3], v[138:139], v[142:143]
	v_and_b32_e32 v151, 0x7fffffff, v147
	v_and_b32_e32 v150, 0x7fffffff, v146
	v_rcp_f32_e32 v158, v158
	v_rcp_f32_e32 v159, v159
	v_pk_fma_f32 v[134:135], v[6:7], v[134:135], v[138:139]
	v_add_lshl_u32 v168, v213, v164, 1
	v_pk_fma_f32 v[130:131], v[10:11], v[130:131], v[134:135]
	v_pk_fma_f32 v[134:135], v[150:151], s[58:59], 1.0 op_sel_hi:[1,0,0]
	v_pk_mul_f32 v[156:157], v[144:145], v[144:145]
	v_rcp_f32_e32 v134, v134
	v_rcp_f32_e32 v135, v135
	v_mov_b64_e32 v[164:165], s[62:63]
	v_pk_mul_f32 v[156:157], v[156:157], s[56:57] op_sel_hi:[1,0]
	v_pk_fma_f32 v[166:167], v[158:159], s[60:61], v[164:165] op_sel_hi:[1,0,0]
	v_pk_mul_f32 v[154:155], v[146:147], v[146:147]
	v_exp_f32_e32 v156, v156
	v_exp_f32_e32 v157, v157
	v_pk_fma_f32 v[166:167], v[158:159], v[166:167], s[64:65] op_sel_hi:[1,1,0]
	v_pk_fma_f32 v[136:137], v[0:1], v[136:137], v[140:141]
	v_pk_fma_f32 v[166:167], v[158:159], v[166:167], s[66:67] op_sel_hi:[1,1,0]
	v_pk_fma_f32 v[132:133], v[4:5], v[132:133], v[136:137]
	v_pk_mul_f32 v[136:137], v[154:155], s[56:57] op_sel_hi:[1,0]
	v_pk_fma_f32 v[138:139], v[134:135], s[60:61], v[164:165] op_sel_hi:[1,0,0]
	v_pk_fma_f32 v[166:167], v[158:159], v[166:167], s[68:69] op_sel_hi:[1,1,0]
	v_exp_f32_e32 v136, v136
	v_exp_f32_e32 v137, v137
	v_pk_fma_f32 v[138:139], v[134:135], v[138:139], s[64:65] op_sel_hi:[1,1,0]
	v_pk_mul_f32 v[158:159], v[158:159], v[166:167]
	v_pk_fma_f32 v[138:139], v[134:135], v[138:139], s[66:67] op_sel_hi:[1,1,0]
	v_max_f32_e32 v148, 0, v144
	v_pk_mul_f32 v[156:157], v[156:157], v[158:159]
	v_max_f32_e32 v149, 0, v145
	v_pk_fma_f32 v[138:139], v[134:135], v[138:139], s[68:69] op_sel_hi:[1,1,0]
	v_pk_fma_f32 v[128:129], v[8:9], v[128:129], v[132:133]
	v_pk_fma_f32 v[132:133], v[152:153], v[156:157], v[148:149] neg_lo:[1,0,0] neg_hi:[1,0,0]
	v_pk_mul_f32 v[134:135], v[134:135], v[138:139]
	v_pk_mul_f32 v[128:129], v[128:129], v[132:133]
	v_max_f32_e32 v132, 0, v146
	v_pk_mul_f32 v[134:135], v[136:137], v[134:135]
	v_max_f32_e32 v133, 0, v147
	v_pk_fma_f32 v[132:133], v[150:151], v[134:135], v[132:133] neg_lo:[1,0,0] neg_hi:[1,0,0]
	v_cvt_pk_bf16_f32 v128, v128, v129
	v_pk_mul_f32 v[130:131], v[130:131], v[132:133]
	s_nop 0
	v_cvt_pk_bf16_f32 v129, v130, v131
	global_store_dwordx2 v168, v[128:129], s[40:41]

; __device__ __forceinline__ unsigned pk2(float lo, float hi) { const f32x2 v = {lo, hi}; return __builtin_bit_cast(unsigned, __builtin_convertvector(v, bf16x2_hw)); }
;     template <bool EDGE> __device__ __forceinline__ void body(const f32x4 (&acc)[2][2][4][2], const pg8::Unit& u, int wr, int wc, int fr, int fq) const {
;     ...
;             const f32x4 wv0 = *(const f32x4*)(conv_w + ch), wv1 = *(const f32x4*)(conv_w + NUP + ch), wv2 = *(const f32x4*)(conv_w + 2 * NUP + ch), bv = *(const f32x4*)(conv_b + ch);
;             const f32x4 wg0 = *(const f32x4*)(conv_w + DFF + ch), wg1 = *(const f32x4*)(conv_w + NUP + DFF + ch), wg2 = *(const f32x4*)(conv_w + 2 * NUP + DFF + ch), bg = *(const f32x4*)(conv_b + DFF + ch);
;             const f32x4 v7 = dpp_shr1(acc[1][0][3][n]), v6 = dpp_shr1(acc[1][0][2][n]), g7 = dpp_shr1(acc[1][1][3][n]), g6 = dpp_shr1(acc[1][1][2][n]);
; #pragma unroll
;             for (int k = 0; k < 8; ++k) {
;                 const int ai = k >> 2, m = k & 3, lr = 8 * fr + k, tau = tw0 + lr, sp = tau & 4095;
;                 const f32x4 cv = acc[ai][0][m][n], cg = acc[ai][1][m][n];
;                 const f32x4 p1v = k >= 1 ? acc[(k >= 1 ? k - 1 : 0) >> 2][0][(k >= 1 ? k - 1 : 0) & 3][n] : v7;
;                 const f32x4 p1g = k >= 1 ? acc[(k >= 1 ? k - 1 : 0) >> 2][1][(k >= 1 ? k - 1 : 0) & 3][n] : g7;
;                 const f32x4 p2v = k >= 2 ? acc[(k >= 2 ? k - 2 : 0) >> 2][0][(k >= 2 ? k - 2 : 0) & 3][n] : (k == 1 ? v7 : v6);
;                 const f32x4 p2g = k >= 2 ? acc[(k >= 2 ? k - 2 : 0) >> 2][1][(k >= 2 ? k - 2 : 0) & 3][n] : (k == 1 ? g7 : g6);
;                 f32x4 val, gat;
;                 if (EDGE) { const float m1 = sp >= 1 ? 1.f : 0.f, m2 = sp >= 2 ? 1.f : 0.f;
;                     val = bv + wv2 * cv + (wv1 * m1) * p1v + (wv0 * m2) * p2v; gat = bg + wg2 * cg + (wg1 * m1) * p1g + (wg0 * m2) * p2g; }
;                 else { val = bv + wv2 * cv + wv1 * p1v + wv0 * p2v; gat = bg + wg2 * cg + wg1 * p1g + wg0 * p2g; }
;                 const f32x2 g01 = gelu_pk((f32x2){gat[0], gat[1]}), g23 = gelu_pk((f32x2){gat[2], gat[3]});
;                 u32x2 w; w.x = pk2(g01.x * val[0], g01.y * val[1]); w.y = pk2(g23.x * val[2], g23.y * val[3]);
;                 if (lr >= 2 && tau < NT) *(u32x2*)((char*)hidden + (unsigned)(tau * DFF + ch) * 2u) = w;
.LBB0_811:
	s_and_b64 vcc, exec, s[0:1]
	s_cbranch_vccz .LBB0_838
	v_lshl_or_b32 v164, s24, 7, v204
	v_ashrrev_i32_e32 v165, 31, v164
	s_waitcnt vmcnt(0)
	v_lshlrev_b64 v[156:157], 2, v[164:165]
	v_lshl_add_u64 v[166:167], s[28:29], 0, v[156:157]
	v_lshl_add_u64 v[132:133], s[44:45], 0, v[156:157]
	v_lshl_add_u64 v[136:137], s[46:47], 0, v[156:157]
	v_lshl_add_u64 v[168:169], s[30:31], 0, v[156:157]
	v_lshl_add_u64 v[144:145], s[48:49], 0, v[156:157]
	v_lshl_add_u64 v[148:149], s[50:51], 0, v[156:157]
	v_lshl_add_u64 v[152:153], s[52:53], 0, v[156:157]
	v_lshl_add_u64 v[156:157], s[54:55], 0, v[156:157]
	global_load_dwordx4 v[128:131], v[166:167], off
	s_nop 0
	global_load_dwordx4 v[132:135], v[132:133], off
	s_nop 0
	global_load_dwordx4 v[136:139], v[136:137], off
	v_add_u32_e32 v188, s25, v196
	global_load_dwordx4 v[140:143], v[168:169], off
	s_nop 0
	global_load_dwordx4 v[144:147], v[144:145], off
	s_nop 0
	global_load_dwordx4 v[148:151], v[148:149], off
	v_mov_b32_e32 v170, 0
	global_load_dwordx4 v[152:155], v[152:153], off
	v_mov_b32_e32 v171, 0
	global_load_dwordx4 v[156:159], v[156:157], off
	v_mov_b32_e32 v172, 0
	v_mov_b32_e32 v173, 0
	v_mov_b32_e32 v178, 0
	v_mov_b32_e32 v179, 0
	v_mov_b32_e32 v180, 0
	v_mov_b32_e32 v181, 0
	v_mov_b32_e32 v174, 0
	v_mov_b32_e32 v175, 0
	v_mov_b32_e32 v176, 0
	v_mov_b32_e32 v177, 0
	v_mov_b32_e32 v182, 0
	v_mov_b32_e32 v183, 0
	v_mov_b32_e32 v184, 0
	v_mov_b32_e32 v185, 0
	v_cmp_gt_i32_e32 vcc, s59, v188
	v_mov_b32_dpp v170, v64 row_shr:1 row_mask:0xf bank_mask:0xf
	v_mov_b32_dpp v171, v65 row_shr:1 row_mask:0xf bank_mask:0xf
	v_mov_b32_dpp v172, v66 row_shr:1 row_mask:0xf bank_mask:0xf
	v_mov_b32_dpp v173, v67 row_shr:1 row_mask:0xf bank_mask:0xf
	v_mov_b32_dpp v178, v68 row_shr:1 row_mask:0xf bank_mask:0xf
	v_mov_b32_dpp v179, v69 row_shr:1 row_mask:0xf bank_mask:0xf
	v_mov_b32_dpp v180, v70 row_shr:1 row_mask:0xf bank_mask:0xf
	v_mov_b32_dpp v181, v71 row_shr:1 row_mask:0xf bank_mask:0xf
	v_mov_b32_dpp v174, v80 row_shr:1 row_mask:0xf bank_mask:0xf
	v_mov_b32_dpp v175, v81 row_shr:1 row_mask:0xf bank_mask:0xf
	v_mov_b32_dpp v176, v82 row_shr:1 row_mask:0xf bank_mask:0xf
	v_mov_b32_dpp v177, v83 row_shr:1 row_mask:0xf bank_mask:0xf
	v_mov_b32_dpp v182, v84 row_shr:1 row_mask:0xf bank_mask:0xf
	v_mov_b32_dpp v183, v85 row_shr:1 row_mask:0xf bank_mask:0xf
	v_mov_b32_dpp v184, v86 row_shr:1 row_mask:0xf bank_mask:0xf
	v_mov_b32_dpp v185, v87 row_shr:1 row_mask:0xf bank_mask:0xf
	v_and_b32_e32 v165, 0xffe, v188
	s_and_b64 s[0:1], s[6:7], vcc
	v_mul_lo_u32 v210, v188, s73
	s_waitcnt vmcnt(0)
	s_and_saveexec_b64 s[2:3], s[0:1]
	s_cbranch_execz .LBB0_814
	v_cmp_eq_u32_e32 vcc, 0, v165
	v_pk_fma_f32 v[212:213], v[124:125], v[152:153], v[156:157]
	v_pk_fma_f32 v[188:189], v[126:127], v[154:155], v[158:159]
	v_cndmask_b32_e64 v214, 1.0, 0, vcc
	v_pk_mul_f32 v[218:219], v[214:215], v[148:149] op_sel_hi:[0,1]
	v_pk_mul_f32 v[216:217], v[214:215], v[150:151] op_sel_hi:[0,1]
	v_pk_fma_f32 v[212:213], v[218:219], v[174:175], v[212:213]
	v_pk_mul_f32 v[218:219], v[214:215], v[144:145] op_sel_hi:[0,1]
	v_pk_fma_f32 v[188:189], v[216:217], v[176:177], v[188:189]
	v_pk_mul_f32 v[216:217], v[214:215], v[146:147] op_sel_hi:[0,1]
	v_pk_fma_f32 v[182:183], v[218:219], v[182:183], v[212:213]
	v_pk_fma_f32 v[184:185], v[216:217], v[184:185], v[188:189]
	v_and_b32_e32 v217, 0x7fffffff, v183
	v_and_b32_e32 v216, 0x7fffffff, v182
	v_pk_fma_f32 v[222:223], v[216:217], s[58:59], 1.0 op_sel_hi:[1,0,0]
	v_pk_mul_f32 v[220:221], v[182:183], v[182:183]
	v_rcp_f32_e32 v222, v222
	v_rcp_f32_e32 v223, v223
	v_mov_b64_e32 v[224:225], s[62:63]
	v_pk_mul_f32 v[220:221], v[220:221], s[56:57] op_sel_hi:[1,0]
	v_max_f32_e32 v188, 0, v182
	v_pk_fma_f32 v[226:227], v[222:223], s[60:61], v[224:225] op_sel_hi:[1,0,0]
	v_exp_f32_e32 v220, v220
	v_exp_f32_e32 v221, v221
	v_pk_fma_f32 v[226:227], v[222:223], v[226:227], s[64:65] op_sel_hi:[1,1,0]
	v_and_b32_e32 v213, 0x7fffffff, v185
	v_pk_fma_f32 v[226:227], v[222:223], v[226:227], s[66:67] op_sel_hi:[1,1,0]
	v_and_b32_e32 v212, 0x7fffffff, v184
	v_pk_fma_f32 v[226:227], v[222:223], v[226:227], s[68:69] op_sel_hi:[1,1,0]
	v_max_f32_e32 v189, 0, v183
	v_pk_mul_f32 v[222:223], v[222:223], v[226:227]
	v_pk_fma_f32 v[226:227], v[120:121], v[136:137], v[140:141]
	v_pk_mul_f32 v[220:221], v[220:221], v[222:223]
	v_pk_fma_f32 v[222:223], v[122:123], v[138:139], v[142:143]
	v_pk_fma_f32 v[182:183], v[216:217], v[220:221], v[188:189] neg_lo:[1,0,0] neg_hi:[1,0,0]
	v_pk_fma_f32 v[188:189], v[212:213], s[58:59], 1.0 op_sel_hi:[1,0,0]
	v_pk_mul_f32 v[228:229], v[214:215], v[134:135] op_sel_hi:[0,1]
	v_rcp_f32_e32 v188, v188
	v_rcp_f32_e32 v189, v189
	v_pk_mul_f32 v[230:231], v[214:215], v[132:133] op_sel_hi:[0,1]
	v_pk_mul_f32 v[218:219], v[184:185], v[184:185]
	v_pk_fma_f32 v[222:223], v[228:229], v[172:173], v[222:223]
	v_pk_fma_f32 v[226:227], v[230:231], v[170:171], v[226:227]
	v_pk_mul_f32 v[228:229], v[214:215], v[130:131] op_sel_hi:[0,1]
	v_pk_mul_f32 v[214:215], v[214:215], v[128:129] op_sel_hi:[0,1]
	v_pk_fma_f32 v[178:179], v[214:215], v[178:179], v[226:227]
	v_pk_mul_f32 v[214:215], v[218:219], s[56:57] op_sel_hi:[1,0]
	v_pk_fma_f32 v[216:217], v[188:189], s[60:61], v[224:225] op_sel_hi:[1,0,0]
	v_exp_f32_e32 v214, v214
	v_exp_f32_e32 v215, v215
	v_pk_fma_f32 v[216:217], v[188:189], v[216:217], s[64:65] op_sel_hi:[1,1,0]
	v_pk_mul_f32 v[178:179], v[178:179], v[182:183]
	v_pk_fma_f32 v[216:217], v[188:189], v[216:217], s[66:67] op_sel_hi:[1,1,0]
	v_max_f32_e32 v182, 0, v184
	v_pk_fma_f32 v[216:217], v[188:189], v[216:217], s[68:69] op_sel_hi:[1,1,0]
	v_max_f32_e32 v183, 0, v185
	v_pk_mul_f32 v[188:189], v[188:189], v[216:217]
	v_pk_fma_f32 v[180:181], v[228:229], v[180:181], v[222:223]
	v_pk_mul_f32 v[188:189], v[214:215], v[188:189]
	v_add_lshl_u32 v211, v210, v164, 1
	v_pk_fma_f32 v[182:183], v[212:213], v[188:189], v[182:183] neg_lo:[1,0,0] neg_hi:[1,0,0]
	v_cvt_pk_bf16_f32 v178, v178, v179
	v_pk_mul_f32 v[180:181], v[180:181], v[182:183]
	s_nop 0
	v_cvt_pk_bf16_f32 v179, v180, v181
	global_store_dwordx2 v211, v[178:179], s[40:41]
; __device__ __forceinline__ unsigned pk2(float lo, float hi) { const f32x2 v = {lo, hi}; return __builtin_bit_cast(unsigned, __builtin_convertvector(v, bf16x2_hw)); }
;     template <bool EDGE> __device__ __forceinline__ void body(const f32x4 (&acc)[2][2][4][2], const pg8::Unit& u, int wr, int wc, int fr, int fq) const {
;     ...
;                 const int ai = k >> 2, m = k & 3, lr = 8 * fr + k, tau = tw0 + lr, sp = tau & 4095;
;                 const f32x4 cv = acc[ai][0][m][n], cg = acc[ai][1][m][n];
;                 const f32x4 p1v = k >= 1 ? acc[(k >= 1 ? k - 1 : 0) >> 2][0][(k >= 1 ? k - 1 : 0) & 3][n] : v7;
;                 const f32x4 p1g = k >= 1 ? acc[(k >= 1 ? k - 1 : 0) >> 2][1][(k >= 1 ? k - 1 : 0) & 3][n] : g7;
;                 const f32x4 p2v = k >= 2 ? acc[(k >= 2 ? k - 2 : 0) >> 2][0][(k >= 2 ? k - 2 : 0) & 3][n] : (k == 1 ? v7 : v6);
;                 const f32x4 p2g = k >= 2 ? acc[(k >= 2 ? k - 2 : 0) >> 2][1][(k >= 2 ? k - 2 : 0) & 3][n] : (k == 1 ? g7 : g6);
;                 f32x4 val, gat;
;                 if (EDGE) { const float m1 = sp >= 1 ? 1.f : 0.f, m2 = sp >= 2 ? 1.f : 0.f;
;                     val = bv + wv2 * cv + (wv1 * m1) * p1v + (wv0 * m2) * p2v; gat = bg + wg2 * cg + (wg1 * m1) * p1g + (wg0 * m2) * p2g; }
;                 else { val = bv + wv2 * cv + wv1 * p1v + wv0 * p2v; gat = bg + wg2 * cg + wg1 * p1g + wg0 * p2g; }
;                 const f32x2 g01 = gelu_pk((f32x2){gat[0], gat[1]}), g23 = gelu_pk((f32x2){gat[2], gat[3]});
;                 u32x2 w; w.x = pk2(g01.x * val[0], g01.y * val[1]); w.y = pk2(g23.x * val[2], g23.y * val[3]);
;                 if (lr >= 2 && tau < NT) *(u32x2*)((char*)hidden + (unsigned)(tau * DFF + ch) * 2u) = w;
.LBB0_814:
	s_or_b64 exec, exec, s[2:3]
	v_add_u32_e32 v179, s25, v197
	v_cmp_gt_i32_e32 vcc, s59, v179
	v_and_b32_e32 v178, 0xfff, v179
	s_and_b64 s[2:3], s[6:7], vcc
	v_mul_lo_u32 v179, v179, s73
	s_and_saveexec_b64 s[10:11], s[2:3]
	s_cbranch_execz .LBB0_816
	v_cmp_eq_u32_e32 vcc, 1, v178
	v_pk_fma_f32 v[182:183], v[116:117], v[152:153], v[156:157]
	v_pk_fma_f32 v[180:181], v[118:119], v[154:155], v[158:159]
	v_cndmask_b32_e64 v184, 1.0, 0, vcc
	v_pk_fma_f32 v[182:183], v[124:125], v[148:149], v[182:183]
	v_pk_mul_f32 v[212:213], v[184:185], v[144:145] op_sel_hi:[0,1]
	v_pk_fma_f32 v[180:181], v[126:127], v[150:151], v[180:181]
	v_pk_mul_f32 v[188:189], v[184:185], v[146:147] op_sel_hi:[0,1]
	v_pk_fma_f32 v[174:175], v[212:213], v[174:175], v[182:183]
	v_pk_fma_f32 v[176:177], v[188:189], v[176:177], v[180:181]
	v_and_b32_e32 v189, 0x7fffffff, v175
	v_and_b32_e32 v188, 0x7fffffff, v174
	v_pk_fma_f32 v[216:217], v[188:189], s[58:59], 1.0 op_sel_hi:[1,0,0]
	v_pk_mul_f32 v[214:215], v[174:175], v[174:175]
	v_rcp_f32_e32 v216, v216
	v_rcp_f32_e32 v217, v217
	v_mov_b64_e32 v[218:219], s[62:63]
	v_pk_mul_f32 v[214:215], v[214:215], s[56:57] op_sel_hi:[1,0]
	v_max_f32_e32 v180, 0, v174
	v_pk_fma_f32 v[220:221], v[216:217], s[60:61], v[218:219] op_sel_hi:[1,0,0]
	v_exp_f32_e32 v214, v214
	v_exp_f32_e32 v215, v215
	v_pk_fma_f32 v[220:221], v[216:217], v[220:221], s[64:65] op_sel_hi:[1,1,0]
	v_and_b32_e32 v183, 0x7fffffff, v177
	v_pk_fma_f32 v[220:221], v[216:217], v[220:221], s[66:67] op_sel_hi:[1,1,0]
	v_and_b32_e32 v182, 0x7fffffff, v176
	v_pk_fma_f32 v[220:221], v[216:217], v[220:221], s[68:69] op_sel_hi:[1,1,0]
	v_max_f32_e32 v181, 0, v175
	v_pk_mul_f32 v[216:217], v[216:217], v[220:221]
	v_pk_fma_f32 v[220:221], v[112:113], v[136:137], v[140:141]
	v_pk_mul_f32 v[214:215], v[214:215], v[216:217]
	v_pk_mul_f32 v[212:213], v[176:177], v[176:177]
	v_pk_fma_f32 v[174:175], v[188:189], v[214:215], v[180:181] neg_lo:[1,0,0] neg_hi:[1,0,0]
	v_pk_fma_f32 v[180:181], v[182:183], s[58:59], 1.0 op_sel_hi:[1,0,0]
	v_pk_fma_f32 v[220:221], v[120:121], v[132:133], v[220:221]
	v_rcp_f32_e32 v180, v180
	v_rcp_f32_e32 v181, v181
	v_pk_mul_f32 v[222:223], v[184:185], v[130:131] op_sel_hi:[0,1]
	v_pk_mul_f32 v[184:185], v[184:185], v[128:129] op_sel_hi:[0,1]
	v_pk_fma_f32 v[170:171], v[184:185], v[170:171], v[220:221]
	v_pk_mul_f32 v[184:185], v[212:213], s[56:57] op_sel_hi:[1,0]
	v_pk_fma_f32 v[188:189], v[180:181], s[60:61], v[218:219] op_sel_hi:[1,0,0]
	v_exp_f32_e32 v184, v184
	v_exp_f32_e32 v185, v185
	v_pk_fma_f32 v[188:189], v[180:181], v[188:189], s[64:65] op_sel_hi:[1,1,0]
	v_pk_fma_f32 v[216:217], v[114:115], v[138:139], v[142:143]
	v_pk_fma_f32 v[188:189], v[180:181], v[188:189], s[66:67] op_sel_hi:[1,1,0]
	v_pk_fma_f32 v[216:217], v[122:123], v[134:135], v[216:217]
	v_pk_fma_f32 v[188:189], v[180:181], v[188:189], s[68:69] op_sel_hi:[1,1,0]
	v_pk_mul_f32 v[170:171], v[170:171], v[174:175]
	v_pk_mul_f32 v[180:181], v[180:181], v[188:189]
	v_max_f32_e32 v174, 0, v176
	v_pk_mul_f32 v[180:181], v[184:185], v[180:181]
	v_max_f32_e32 v175, 0, v177
	v_pk_fma_f32 v[172:173], v[222:223], v[172:173], v[216:217]
	v_pk_fma_f32 v[174:175], v[182:183], v[180:181], v[174:175] neg_lo:[1,0,0] neg_hi:[1,0,0]
	v_add_lshl_u32 v211, v179, v164, 1
	v_pk_mul_f32 v[172:173], v[172:173], v[174:175]
	v_cvt_pk_bf16_f32 v170, v170, v171
	v_cvt_pk_bf16_f32 v171, v172, v173
	global_store_dwordx2 v211, v[170:171], s[40:41]
.LBB0_816:
	s_or_b64 exec, exec, s[10:11]
	v_add_u32_e32 v171, s25, v198
	v_and_b32_e32 v170, 0xffe, v171
	v_cmp_gt_i32_e32 vcc, s59, v171
	v_mul_lo_u32 v171, v171, s73
	s_and_saveexec_b64 s[12:13], vcc
	s_cbranch_execz .LBB0_818
	v_cmp_eq_u32_e64 s[10:11], 0, v170
	v_pk_fma_f32 v[174:175], v[108:109], v[152:153], v[156:157]
	v_pk_fma_f32 v[172:173], v[110:111], v[154:155], v[158:159]
	v_cndmask_b32_e64 v176, 1.0, 0, s[10:11]
	v_pk_mul_f32 v[182:183], v[176:177], v[148:149] op_sel_hi:[0,1]
	v_pk_mul_f32 v[180:181], v[176:177], v[150:151] op_sel_hi:[0,1]
	v_pk_fma_f32 v[174:175], v[116:117], v[182:183], v[174:175]
	v_pk_mul_f32 v[182:183], v[176:177], v[144:145] op_sel_hi:[0,1]
	v_pk_fma_f32 v[172:173], v[118:119], v[180:181], v[172:173]
	v_pk_mul_f32 v[180:181], v[176:177], v[146:147] op_sel_hi:[0,1]
	v_pk_fma_f32 v[124:125], v[124:125], v[182:183], v[174:175]
	v_pk_fma_f32 v[126:127], v[126:127], v[180:181], v[172:173]
	v_and_b32_e32 v181, 0x7fffffff, v125
	v_and_b32_e32 v180, 0x7fffffff, v124
	v_pk_fma_f32 v[188:189], v[180:181], s[58:59], 1.0 op_sel_hi:[1,0,0]
	v_pk_mul_f32 v[184:185], v[124:125], v[124:125]
	v_rcp_f32_e32 v188, v188
	v_rcp_f32_e32 v189, v189
	v_mov_b64_e32 v[212:213], s[62:63]
	v_pk_mul_f32 v[184:185], v[184:185], s[56:57] op_sel_hi:[1,0]
	v_max_f32_e32 v172, 0, v124
	v_pk_fma_f32 v[214:215], v[188:189], s[60:61], v[212:213] op_sel_hi:[1,0,0]
	v_exp_f32_e32 v184, v184
	v_exp_f32_e32 v185, v185
	v_pk_fma_f32 v[214:215], v[188:189], v[214:215], s[64:65] op_sel_hi:[1,1,0]
	v_and_b32_e32 v175, 0x7fffffff, v127
	v_pk_fma_f32 v[214:215], v[188:189], v[214:215], s[66:67] op_sel_hi:[1,1,0]
	v_and_b32_e32 v174, 0x7fffffff, v126
	v_pk_fma_f32 v[214:215], v[188:189], v[214:215], s[68:69] op_sel_hi:[1,1,0]
	v_max_f32_e32 v173, 0, v125
	v_pk_mul_f32 v[188:189], v[188:189], v[214:215]
	v_pk_fma_f32 v[214:215], v[104:105], v[136:137], v[140:141]
	v_pk_mul_f32 v[184:185], v[184:185], v[188:189]
	v_pk_fma_f32 v[188:189], v[106:107], v[138:139], v[142:143]
	v_pk_fma_f32 v[124:125], v[180:181], v[184:185], v[172:173] neg_lo:[1,0,0] neg_hi:[1,0,0]
	v_pk_fma_f32 v[172:173], v[174:175], s[58:59], 1.0 op_sel_hi:[1,0,0]
	v_pk_mul_f32 v[216:217], v[176:177], v[134:135] op_sel_hi:[0,1]
; __device__ __forceinline__ unsigned pk2(float lo, float hi) { const f32x2 v = {lo, hi}; return __builtin_bit_cast(unsigned, __builtin_convertvector(v, bf16x2_hw)); }
;     template <bool EDGE> __device__ __forceinline__ void body(const f32x4 (&acc)[2][2][4][2], const pg8::Unit& u, int wr, int wc, int fr, int fq) const {
;     ...
;                 const int ai = k >> 2, m = k & 3, lr = 8 * fr + k, tau = tw0 + lr, sp = tau & 4095;
;                 const f32x4 cv = acc[ai][0][m][n], cg = acc[ai][1][m][n];
;                 const f32x4 p1v = k >= 1 ? acc[(k >= 1 ? k - 1 : 0) >> 2][0][(k >= 1 ? k - 1 : 0) & 3][n] : v7;
;                 const f32x4 p1g = k >= 1 ? acc[(k >= 1 ? k - 1 : 0) >> 2][1][(k >= 1 ? k - 1 : 0) & 3][n] : g7;
;                 const f32x4 p2v = k >= 2 ? acc[(k >= 2 ? k - 2 : 0) >> 2][0][(k >= 2 ? k - 2 : 0) & 3][n] : (k == 1 ? v7 : v6);
;                 const f32x4 p2g = k >= 2 ? acc[(k >= 2 ? k - 2 : 0) >> 2][1][(k >= 2 ? k - 2 : 0) & 3][n] : (k == 1 ? g7 : g6);
;                 f32x4 val, gat;
;                 if (EDGE) { const float m1 = sp >= 1 ? 1.f : 0.f, m2 = sp >= 2 ? 1.f : 0.f;
;                     val = bv + wv2 * cv + (wv1 * m1) * p1v + (wv0 * m2) * p2v; gat = bg + wg2 * cg + (wg1 * m1) * p1g + (wg0 * m2) * p2g; }
;                 else { val = bv + wv2 * cv + wv1 * p1v + wv0 * p2v; gat = bg + wg2 * cg + wg1 * p1g + wg0 * p2g; }
;                 const f32x2 g01 = gelu_pk((f32x2){gat[0], gat[1]}), g23 = gelu_pk((f32x2){gat[2], gat[3]});
;                 u32x2 w; w.x = pk2(g01.x * val[0], g01.y * val[1]); w.y = pk2(g23.x * val[2], g23.y * val[3]);
;                 if (lr >= 2 && tau < NT) *(u32x2*)((char*)hidden + (unsigned)(tau * DFF + ch) * 2u) = w;
	v_rcp_f32_e32 v172, v172
	v_rcp_f32_e32 v173, v173
	v_pk_mul_f32 v[218:219], v[176:177], v[132:133] op_sel_hi:[0,1]
	v_pk_mul_f32 v[182:183], v[126:127], v[126:127]
	v_pk_fma_f32 v[188:189], v[114:115], v[216:217], v[188:189]
	v_pk_fma_f32 v[214:215], v[112:113], v[218:219], v[214:215]
	v_pk_mul_f32 v[216:217], v[176:177], v[130:131] op_sel_hi:[0,1]
	v_pk_mul_f32 v[176:177], v[176:177], v[128:129] op_sel_hi:[0,1]
	v_pk_fma_f32 v[120:121], v[120:121], v[176:177], v[214:215]
	v_pk_mul_f32 v[176:177], v[182:183], s[56:57] op_sel_hi:[1,0]
	v_pk_fma_f32 v[180:181], v[172:173], s[60:61], v[212:213] op_sel_hi:[1,0,0]
	v_exp_f32_e32 v176, v176
	v_exp_f32_e32 v177, v177
	v_pk_fma_f32 v[180:181], v[172:173], v[180:181], s[64:65] op_sel_hi:[1,1,0]
	v_pk_mul_f32 v[120:121], v[120:121], v[124:125]
	v_pk_fma_f32 v[180:181], v[172:173], v[180:181], s[66:67] op_sel_hi:[1,1,0]
	v_max_f32_e32 v124, 0, v126
	v_pk_fma_f32 v[180:181], v[172:173], v[180:181], s[68:69] op_sel_hi:[1,1,0]
	v_max_f32_e32 v125, 0, v127
	v_pk_mul_f32 v[172:173], v[172:173], v[180:181]
	v_pk_fma_f32 v[122:123], v[122:123], v[216:217], v[188:189]
	v_pk_mul_f32 v[172:173], v[176:177], v[172:173]
	v_add_lshl_u32 v211, v171, v164, 1
	v_pk_fma_f32 v[124:125], v[174:175], v[172:173], v[124:125] neg_lo:[1,0,0] neg_hi:[1,0,0]
	v_cvt_pk_bf16_f32 v120, v120, v121
	v_pk_mul_f32 v[122:123], v[122:123], v[124:125]
	s_nop 0
	v_cvt_pk_bf16_f32 v121, v122, v123
	global_store_dwordx2 v211, v[120:121], s[40:41]
.LBB0_818:
	s_or_b64 exec, exec, s[12:13]
	v_add_u32_e32 v121, s25, v199
	v_and_b32_e32 v120, 0xfff, v121
	v_cmp_gt_i32_e64 s[10:11], s59, v121
	v_mul_lo_u32 v121, v121, s73
	s_and_saveexec_b64 s[14:15], s[10:11]
	s_cbranch_execz .LBB0_820
	v_cmp_eq_u32_e64 s[12:13], 1, v120
	v_pk_fma_f32 v[124:125], v[100:101], v[152:153], v[156:157]
	v_pk_fma_f32 v[122:123], v[102:103], v[154:155], v[158:159]
	v_cndmask_b32_e64 v126, 1.0, 0, s[12:13]
	v_pk_fma_f32 v[124:125], v[108:109], v[148:149], v[124:125]
	v_pk_mul_f32 v[174:175], v[126:127], v[144:145] op_sel_hi:[0,1]
	v_pk_fma_f32 v[122:123], v[110:111], v[150:151], v[122:123]
	v_pk_mul_f32 v[172:173], v[126:127], v[146:147] op_sel_hi:[0,1]
	v_pk_fma_f32 v[116:117], v[116:117], v[174:175], v[124:125]
	v_pk_fma_f32 v[118:119], v[118:119], v[172:173], v[122:123]
	v_and_b32_e32 v173, 0x7fffffff, v117
	v_and_b32_e32 v172, 0x7fffffff, v116
	v_pk_fma_f32 v[180:181], v[172:173], s[58:59], 1.0 op_sel_hi:[1,0,0]
	v_pk_mul_f32 v[176:177], v[116:117], v[116:117]
	v_rcp_f32_e32 v180, v180
	v_rcp_f32_e32 v181, v181
	v_mov_b64_e32 v[182:183], s[62:63]
	v_pk_mul_f32 v[176:177], v[176:177], s[56:57] op_sel_hi:[1,0]
	v_max_f32_e32 v122, 0, v116
	v_pk_fma_f32 v[184:185], v[180:181], s[60:61], v[182:183] op_sel_hi:[1,0,0]
	v_exp_f32_e32 v176, v176
	v_exp_f32_e32 v177, v177
	v_pk_fma_f32 v[184:185], v[180:181], v[184:185], s[64:65] op_sel_hi:[1,1,0]
	v_and_b32_e32 v125, 0x7fffffff, v119
	v_pk_fma_f32 v[184:185], v[180:181], v[184:185], s[66:67] op_sel_hi:[1,1,0]
	v_and_b32_e32 v124, 0x7fffffff, v118
	v_pk_fma_f32 v[184:185], v[180:181], v[184:185], s[68:69] op_sel_hi:[1,1,0]
	v_max_f32_e32 v123, 0, v117
	v_pk_mul_f32 v[180:181], v[180:181], v[184:185]
	v_pk_fma_f32 v[184:185], v[96:97], v[136:137], v[140:141]
	v_pk_mul_f32 v[176:177], v[176:177], v[180:181]
	v_pk_mul_f32 v[174:175], v[118:119], v[118:119]
	v_pk_fma_f32 v[116:117], v[172:173], v[176:177], v[122:123] neg_lo:[1,0,0] neg_hi:[1,0,0]
	v_pk_fma_f32 v[122:123], v[124:125], s[58:59], 1.0 op_sel_hi:[1,0,0]
	v_pk_fma_f32 v[184:185], v[104:105], v[132:133], v[184:185]
	v_rcp_f32_e32 v122, v122
	v_rcp_f32_e32 v123, v123
	v_pk_mul_f32 v[188:189], v[126:127], v[130:131] op_sel_hi:[0,1]
	v_pk_mul_f32 v[126:127], v[126:127], v[128:129] op_sel_hi:[0,1]
	v_pk_fma_f32 v[112:113], v[112:113], v[126:127], v[184:185]
	v_pk_mul_f32 v[126:127], v[174:175], s[56:57] op_sel_hi:[1,0]
	v_pk_fma_f32 v[172:173], v[122:123], s[60:61], v[182:183] op_sel_hi:[1,0,0]
	v_exp_f32_e32 v126, v126
	v_exp_f32_e32 v127, v127
	v_pk_fma_f32 v[172:173], v[122:123], v[172:173], s[64:65] op_sel_hi:[1,1,0]
	v_pk_fma_f32 v[180:181], v[98:99], v[138:139], v[142:143]
	v_pk_fma_f32 v[172:173], v[122:123], v[172:173], s[66:67] op_sel_hi:[1,1,0]
	v_pk_fma_f32 v[180:181], v[106:107], v[134:135], v[180:181]
	v_pk_fma_f32 v[172:173], v[122:123], v[172:173], s[68:69] op_sel_hi:[1,1,0]
	v_pk_mul_f32 v[112:113], v[112:113], v[116:117]
	v_pk_mul_f32 v[122:123], v[122:123], v[172:173]
	v_max_f32_e32 v116, 0, v118
	v_pk_mul_f32 v[122:123], v[126:127], v[122:123]
	v_max_f32_e32 v117, 0, v119
	v_pk_fma_f32 v[114:115], v[114:115], v[188:189], v[180:181]
	v_pk_fma_f32 v[116:117], v[124:125], v[122:123], v[116:117] neg_lo:[1,0,0] neg_hi:[1,0,0]
	v_add_lshl_u32 v211, v121, v164, 1
	v_pk_mul_f32 v[114:115], v[114:115], v[116:117]
	v_cvt_pk_bf16_f32 v112, v112, v113
	v_cvt_pk_bf16_f32 v113, v114, v115
	global_store_dwordx2 v211, v[112:113], s[40:41]
; __device__ __forceinline__ unsigned pk2(float lo, float hi) { const f32x2 v = {lo, hi}; return __builtin_bit_cast(unsigned, __builtin_convertvector(v, bf16x2_hw)); }
;     template <bool EDGE> __device__ __forceinline__ void body(const f32x4 (&acc)[2][2][4][2], const pg8::Unit& u, int wr, int wc, int fr, int fq) const {
;     ...
;                 const int ai = k >> 2, m = k & 3, lr = 8 * fr + k, tau = tw0 + lr, sp = tau & 4095;
;                 const f32x4 cv = acc[ai][0][m][n], cg = acc[ai][1][m][n];
;                 const f32x4 p1v = k >= 1 ? acc[(k >= 1 ? k - 1 : 0) >> 2][0][(k >= 1 ? k - 1 : 0) & 3][n] : v7;
;                 const f32x4 p1g = k >= 1 ? acc[(k >= 1 ? k - 1 : 0) >> 2][1][(k >= 1 ? k - 1 : 0) & 3][n] : g7;
;                 const f32x4 p2v = k >= 2 ? acc[(k >= 2 ? k - 2 : 0) >> 2][0][(k >= 2 ? k - 2 : 0) & 3][n] : (k == 1 ? v7 : v6);
;                 const f32x4 p2g = k >= 2 ? acc[(k >= 2 ? k - 2 : 0) >> 2][1][(k >= 2 ? k - 2 : 0) & 3][n] : (k == 1 ? g7 : g6);
;                 f32x4 val, gat;
;                 if (EDGE) { const float m1 = sp >= 1 ? 1.f : 0.f, m2 = sp >= 2 ? 1.f : 0.f;
;                     val = bv + wv2 * cv + (wv1 * m1) * p1v + (wv0 * m2) * p2v; gat = bg + wg2 * cg + (wg1 * m1) * p1g + (wg0 * m2) * p2g; }
;                 else { val = bv + wv2 * cv + wv1 * p1v + wv0 * p2v; gat = bg + wg2 * cg + wg1 * p1g + wg0 * p2g; }
;                 const f32x2 g01 = gelu_pk((f32x2){gat[0], gat[1]}), g23 = gelu_pk((f32x2){gat[2], gat[3]});
;                 u32x2 w; w.x = pk2(g01.x * val[0], g01.y * val[1]); w.y = pk2(g23.x * val[2], g23.y * val[3]);
;                 if (lr >= 2 && tau < NT) *(u32x2*)((char*)hidden + (unsigned)(tau * DFF + ch) * 2u) = w;
.LBB0_820:
	s_or_b64 exec, exec, s[14:15]
	v_add_u32_e32 v112, s25, v200
	v_and_b32_e32 v115, 0xffe, v112
	v_cmp_gt_i32_e64 s[12:13], s59, v112
	v_mul_lo_u32 v118, v112, s73
	s_and_saveexec_b64 s[16:17], s[12:13]
	s_cbranch_execz .LBB0_822
	v_cmp_eq_u32_e64 s[14:15], 0, v115
	v_pk_fma_f32 v[116:117], v[92:93], v[152:153], v[156:157]
	v_pk_fma_f32 v[112:113], v[94:95], v[154:155], v[158:159]
	v_cndmask_b32_e64 v114, 1.0, 0, s[14:15]
	v_pk_mul_f32 v[124:125], v[114:115], v[148:149] op_sel_hi:[0,1]
	v_pk_mul_f32 v[122:123], v[114:115], v[150:151] op_sel_hi:[0,1]
	v_pk_fma_f32 v[116:117], v[100:101], v[124:125], v[116:117]
	v_pk_mul_f32 v[124:125], v[114:115], v[144:145] op_sel_hi:[0,1]
	v_pk_fma_f32 v[112:113], v[102:103], v[122:123], v[112:113]
	v_pk_mul_f32 v[122:123], v[114:115], v[146:147] op_sel_hi:[0,1]
	v_pk_fma_f32 v[108:109], v[108:109], v[124:125], v[116:117]
	v_pk_fma_f32 v[110:111], v[110:111], v[122:123], v[112:113]
	v_and_b32_e32 v123, 0x7fffffff, v109
	v_and_b32_e32 v122, 0x7fffffff, v108
	v_pk_fma_f32 v[172:173], v[122:123], s[58:59], 1.0 op_sel_hi:[1,0,0]
	v_pk_mul_f32 v[126:127], v[108:109], v[108:109]
	v_rcp_f32_e32 v172, v172
	v_rcp_f32_e32 v173, v173
	v_mov_b64_e32 v[174:175], s[62:63]
	v_pk_mul_f32 v[126:127], v[126:127], s[56:57] op_sel_hi:[1,0]
	v_max_f32_e32 v112, 0, v108
	v_pk_fma_f32 v[176:177], v[172:173], s[60:61], v[174:175] op_sel_hi:[1,0,0]
	v_exp_f32_e32 v126, v126
	v_exp_f32_e32 v127, v127
	v_pk_fma_f32 v[176:177], v[172:173], v[176:177], s[64:65] op_sel_hi:[1,1,0]
	v_and_b32_e32 v117, 0x7fffffff, v111
	v_pk_fma_f32 v[176:177], v[172:173], v[176:177], s[66:67] op_sel_hi:[1,1,0]
	v_and_b32_e32 v116, 0x7fffffff, v110
	v_pk_fma_f32 v[176:177], v[172:173], v[176:177], s[68:69] op_sel_hi:[1,1,0]
	v_max_f32_e32 v113, 0, v109
	v_pk_mul_f32 v[172:173], v[172:173], v[176:177]
	v_pk_mul_f32 v[124:125], v[110:111], v[110:111]
	v_pk_mul_f32 v[126:127], v[126:127], v[172:173]
	v_pk_fma_f32 v[176:177], v[88:89], v[136:137], v[140:141]
	v_pk_fma_f32 v[108:109], v[122:123], v[126:127], v[112:113] neg_lo:[1,0,0] neg_hi:[1,0,0]
	v_pk_fma_f32 v[112:113], v[116:117], s[58:59], 1.0 op_sel_hi:[1,0,0]
	v_pk_mul_f32 v[122:123], v[124:125], s[56:57] op_sel_hi:[1,0]
	v_rcp_f32_e32 v112, v112
	v_rcp_f32_e32 v113, v113
	v_exp_f32_e32 v122, v122
	v_exp_f32_e32 v123, v123
	v_pk_mul_f32 v[182:183], v[114:115], v[132:133] op_sel_hi:[0,1]
	v_pk_fma_f32 v[124:125], v[112:113], s[60:61], v[174:175] op_sel_hi:[1,0,0]
	v_pk_fma_f32 v[176:177], v[96:97], v[182:183], v[176:177]
	v_pk_fma_f32 v[124:125], v[112:113], v[124:125], s[64:65] op_sel_hi:[1,1,0]
	v_pk_mul_f32 v[182:183], v[114:115], v[128:129] op_sel_hi:[0,1]
	v_pk_fma_f32 v[124:125], v[112:113], v[124:125], s[66:67] op_sel_hi:[1,1,0]
	v_pk_fma_f32 v[172:173], v[90:91], v[138:139], v[142:143]
	v_pk_fma_f32 v[124:125], v[112:113], v[124:125], s[68:69] op_sel_hi:[1,1,0]
	v_pk_mul_f32 v[180:181], v[114:115], v[134:135] op_sel_hi:[0,1]
	v_pk_fma_f32 v[104:105], v[104:105], v[182:183], v[176:177]
	v_pk_mul_f32 v[112:113], v[112:113], v[124:125]
	v_pk_fma_f32 v[172:173], v[98:99], v[180:181], v[172:173]
	v_pk_mul_f32 v[180:181], v[114:115], v[130:131] op_sel_hi:[0,1]
	v_pk_mul_f32 v[104:105], v[104:105], v[108:109]
	v_max_f32_e32 v108, 0, v110
	v_pk_mul_f32 v[112:113], v[122:123], v[112:113]
	v_max_f32_e32 v109, 0, v111
	v_pk_fma_f32 v[106:107], v[106:107], v[180:181], v[172:173]
	v_pk_fma_f32 v[108:109], v[116:117], v[112:113], v[108:109] neg_lo:[1,0,0] neg_hi:[1,0,0]
	v_add_lshl_u32 v119, v118, v164, 1
	v_pk_mul_f32 v[106:107], v[106:107], v[108:109]
	v_cvt_pk_bf16_f32 v104, v104, v105
	v_cvt_pk_bf16_f32 v105, v106, v107
	global_store_dwordx2 v119, v[104:105], s[40:41]
.LBB0_822:
	s_or_b64 exec, exec, s[16:17]
	v_add_u32_e32 v104, s25, v201
	v_and_b32_e32 v114, 0xfff, v104
	v_cmp_gt_i32_e64 s[14:15], s59, v104
	v_mul_lo_u32 v119, v104, s73
	s_and_saveexec_b64 s[18:19], s[14:15]
	s_cbranch_execz .LBB0_824
	v_cmp_eq_u32_e64 s[16:17], 1, v114
	v_pk_fma_f32 v[106:107], v[76:77], v[152:153], v[156:157]
	v_pk_fma_f32 v[104:105], v[78:79], v[154:155], v[158:159]
	v_cndmask_b32_e64 v108, 1.0, 0, s[16:17]
	v_pk_fma_f32 v[106:107], v[92:93], v[148:149], v[106:107]
	v_pk_mul_f32 v[112:113], v[108:109], v[144:145] op_sel_hi:[0,1]
	v_pk_fma_f32 v[104:105], v[94:95], v[150:151], v[104:105]
	v_pk_mul_f32 v[110:111], v[108:109], v[146:147] op_sel_hi:[0,1]
	v_pk_fma_f32 v[100:101], v[100:101], v[112:113], v[106:107]
	v_pk_fma_f32 v[102:103], v[102:103], v[110:111], v[104:105]
	v_and_b32_e32 v111, 0x7fffffff, v101
	v_and_b32_e32 v110, 0x7fffffff, v100
	v_pk_fma_f32 v[122:123], v[110:111], s[58:59], 1.0 op_sel_hi:[1,0,0]
	v_pk_mul_f32 v[116:117], v[100:101], v[100:101]
	v_rcp_f32_e32 v122, v122
	v_rcp_f32_e32 v123, v123
	v_mov_b64_e32 v[124:125], s[62:63]
	v_pk_mul_f32 v[116:117], v[116:117], s[56:57] op_sel_hi:[1,0]
	v_max_f32_e32 v104, 0, v100
	v_pk_fma_f32 v[126:127], v[122:123], s[60:61], v[124:125] op_sel_hi:[1,0,0]
	v_exp_f32_e32 v116, v116
	v_exp_f32_e32 v117, v117
	v_pk_fma_f32 v[126:127], v[122:123], v[126:127], s[64:65] op_sel_hi:[1,1,0]
	v_and_b32_e32 v107, 0x7fffffff, v103
	v_pk_fma_f32 v[126:127], v[122:123], v[126:127], s[66:67] op_sel_hi:[1,1,0]
	v_and_b32_e32 v106, 0x7fffffff, v102
	v_pk_fma_f32 v[126:127], v[122:123], v[126:127], s[68:69] op_sel_hi:[1,1,0]
	v_max_f32_e32 v105, 0, v101
	v_pk_mul_f32 v[122:123], v[122:123], v[126:127]
	v_pk_fma_f32 v[126:127], v[72:73], v[136:137], v[140:141]
	v_pk_mul_f32 v[116:117], v[116:117], v[122:123]
	v_pk_mul_f32 v[112:113], v[102:103], v[102:103]
	v_pk_fma_f32 v[100:101], v[110:111], v[116:117], v[104:105] neg_lo:[1,0,0] neg_hi:[1,0,0]
; __device__ __forceinline__ unsigned pk2(float lo, float hi) { const f32x2 v = {lo, hi}; return __builtin_bit_cast(unsigned, __builtin_convertvector(v, bf16x2_hw)); }
;     template <bool EDGE> __device__ __forceinline__ void body(const f32x4 (&acc)[2][2][4][2], const pg8::Unit& u, int wr, int wc, int fr, int fq) const {
;     ...
;                 const int ai = k >> 2, m = k & 3, lr = 8 * fr + k, tau = tw0 + lr, sp = tau & 4095;
;                 const f32x4 cv = acc[ai][0][m][n], cg = acc[ai][1][m][n];
;                 const f32x4 p1v = k >= 1 ? acc[(k >= 1 ? k - 1 : 0) >> 2][0][(k >= 1 ? k - 1 : 0) & 3][n] : v7;
;                 const f32x4 p1g = k >= 1 ? acc[(k >= 1 ? k - 1 : 0) >> 2][1][(k >= 1 ? k - 1 : 0) & 3][n] : g7;
;                 const f32x4 p2v = k >= 2 ? acc[(k >= 2 ? k - 2 : 0) >> 2][0][(k >= 2 ? k - 2 : 0) & 3][n] : (k == 1 ? v7 : v6);
;                 const f32x4 p2g = k >= 2 ? acc[(k >= 2 ? k - 2 : 0) >> 2][1][(k >= 2 ? k - 2 : 0) & 3][n] : (k == 1 ? g7 : g6);
;                 f32x4 val, gat;
;                 if (EDGE) { const float m1 = sp >= 1 ? 1.f : 0.f, m2 = sp >= 2 ? 1.f : 0.f;
;                     val = bv + wv2 * cv + (wv1 * m1) * p1v + (wv0 * m2) * p2v; gat = bg + wg2 * cg + (wg1 * m1) * p1g + (wg0 * m2) * p2g; }
;                 else { val = bv + wv2 * cv + wv1 * p1v + wv0 * p2v; gat = bg + wg2 * cg + wg1 * p1g + wg0 * p2g; }
;                 const f32x2 g01 = gelu_pk((f32x2){gat[0], gat[1]}), g23 = gelu_pk((f32x2){gat[2], gat[3]});
;                 u32x2 w; w.x = pk2(g01.x * val[0], g01.y * val[1]); w.y = pk2(g23.x * val[2], g23.y * val[3]);
;                 if (lr >= 2 && tau < NT) *(u32x2*)((char*)hidden + (unsigned)(tau * DFF + ch) * 2u) = w;
	v_pk_fma_f32 v[104:105], v[106:107], s[58:59], 1.0 op_sel_hi:[1,0,0]
	v_pk_fma_f32 v[126:127], v[88:89], v[132:133], v[126:127]
	v_rcp_f32_e32 v104, v104
	v_rcp_f32_e32 v105, v105
	v_pk_mul_f32 v[172:173], v[108:109], v[130:131] op_sel_hi:[0,1]
	v_pk_mul_f32 v[108:109], v[108:109], v[128:129] op_sel_hi:[0,1]
	v_pk_fma_f32 v[96:97], v[96:97], v[108:109], v[126:127]
	v_pk_mul_f32 v[108:109], v[112:113], s[56:57] op_sel_hi:[1,0]
	v_pk_fma_f32 v[110:111], v[104:105], s[60:61], v[124:125] op_sel_hi:[1,0,0]
	v_exp_f32_e32 v108, v108
	v_exp_f32_e32 v109, v109
	v_pk_fma_f32 v[110:111], v[104:105], v[110:111], s[64:65] op_sel_hi:[1,1,0]
	v_pk_fma_f32 v[122:123], v[74:75], v[138:139], v[142:143]
	v_pk_fma_f32 v[110:111], v[104:105], v[110:111], s[66:67] op_sel_hi:[1,1,0]
	v_pk_fma_f32 v[122:123], v[90:91], v[134:135], v[122:123]
	v_pk_fma_f32 v[110:111], v[104:105], v[110:111], s[68:69] op_sel_hi:[1,1,0]
	v_pk_mul_f32 v[96:97], v[96:97], v[100:101]
	v_pk_mul_f32 v[104:105], v[104:105], v[110:111]
	v_max_f32_e32 v100, 0, v102
	v_pk_mul_f32 v[104:105], v[108:109], v[104:105]
	v_max_f32_e32 v101, 0, v103
	v_pk_fma_f32 v[98:99], v[98:99], v[172:173], v[122:123]
	v_pk_fma_f32 v[100:101], v[106:107], v[104:105], v[100:101] neg_lo:[1,0,0] neg_hi:[1,0,0]
	v_add_lshl_u32 v174, v119, v164, 1
	v_pk_mul_f32 v[98:99], v[98:99], v[100:101]
	v_cvt_pk_bf16_f32 v96, v96, v97
	v_cvt_pk_bf16_f32 v97, v98, v99
	global_store_dwordx2 v174, v[96:97], s[40:41]
.LBB0_824:
	s_or_b64 exec, exec, s[18:19]
	v_add_u32_e32 v96, s25, v202
	v_and_b32_e32 v117, 0xffe, v96
	v_cmp_gt_i32_e64 s[16:17], s59, v96
	v_mul_lo_u32 v122, v96, s73
	s_and_saveexec_b64 s[20:21], s[16:17]
	s_cbranch_execz .LBB0_826
	v_cmp_eq_u32_e64 s[18:19], 0, v117
	v_pk_fma_f32 v[98:99], v[84:85], v[152:153], v[156:157]
	v_pk_fma_f32 v[96:97], v[86:87], v[154:155], v[158:159]
	v_cndmask_b32_e64 v100, 1.0, 0, s[18:19]
	v_pk_mul_f32 v[104:105], v[100:101], v[148:149] op_sel_hi:[0,1]
	v_pk_mul_f32 v[102:103], v[100:101], v[150:151] op_sel_hi:[0,1]
	v_pk_fma_f32 v[98:99], v[76:77], v[104:105], v[98:99]
	v_pk_mul_f32 v[104:105], v[100:101], v[144:145] op_sel_hi:[0,1]
	v_pk_fma_f32 v[96:97], v[78:79], v[102:103], v[96:97]
	v_pk_mul_f32 v[102:103], v[100:101], v[146:147] op_sel_hi:[0,1]
	v_pk_fma_f32 v[92:93], v[92:93], v[104:105], v[98:99]
	v_pk_fma_f32 v[94:95], v[94:95], v[102:103], v[96:97]
	v_and_b32_e32 v103, 0x7fffffff, v93
	v_and_b32_e32 v102, 0x7fffffff, v92
	v_pk_fma_f32 v[108:109], v[102:103], s[58:59], 1.0 op_sel_hi:[1,0,0]
	v_pk_mul_f32 v[106:107], v[92:93], v[92:93]
	v_rcp_f32_e32 v108, v108
	v_rcp_f32_e32 v109, v109
	v_mov_b64_e32 v[110:111], s[62:63]
	v_pk_mul_f32 v[106:107], v[106:107], s[56:57] op_sel_hi:[1,0]
	v_max_f32_e32 v96, 0, v92
	v_pk_fma_f32 v[112:113], v[108:109], s[60:61], v[110:111] op_sel_hi:[1,0,0]
	v_exp_f32_e32 v106, v106
	v_exp_f32_e32 v107, v107
	v_pk_fma_f32 v[112:113], v[108:109], v[112:113], s[64:65] op_sel_hi:[1,1,0]
	v_and_b32_e32 v99, 0x7fffffff, v95
	v_pk_fma_f32 v[112:113], v[108:109], v[112:113], s[66:67] op_sel_hi:[1,1,0]
	v_and_b32_e32 v98, 0x7fffffff, v94
	v_pk_fma_f32 v[112:113], v[108:109], v[112:113], s[68:69] op_sel_hi:[1,1,0]
	v_max_f32_e32 v97, 0, v93
	v_pk_mul_f32 v[108:109], v[108:109], v[112:113]
	v_pk_fma_f32 v[112:113], v[68:69], v[136:137], v[140:141]
	v_pk_mul_f32 v[106:107], v[106:107], v[108:109]
	v_pk_fma_f32 v[108:109], v[70:71], v[138:139], v[142:143]
	v_pk_fma_f32 v[92:93], v[102:103], v[106:107], v[96:97] neg_lo:[1,0,0] neg_hi:[1,0,0]
	v_pk_fma_f32 v[96:97], v[98:99], s[58:59], 1.0 op_sel_hi:[1,0,0]
	v_pk_mul_f32 v[124:125], v[100:101], v[134:135] op_sel_hi:[0,1]
	v_rcp_f32_e32 v96, v96
	v_rcp_f32_e32 v97, v97
	v_pk_mul_f32 v[126:127], v[100:101], v[132:133] op_sel_hi:[0,1]
	v_pk_mul_f32 v[104:105], v[94:95], v[94:95]
	v_pk_fma_f32 v[108:109], v[74:75], v[124:125], v[108:109]
	v_pk_fma_f32 v[112:113], v[72:73], v[126:127], v[112:113]
	v_pk_mul_f32 v[124:125], v[100:101], v[130:131] op_sel_hi:[0,1]
	v_pk_mul_f32 v[100:101], v[100:101], v[128:129] op_sel_hi:[0,1]
	v_pk_fma_f32 v[88:89], v[88:89], v[100:101], v[112:113]
	v_pk_mul_f32 v[100:101], v[104:105], s[56:57] op_sel_hi:[1,0]
	v_pk_fma_f32 v[102:103], v[96:97], s[60:61], v[110:111] op_sel_hi:[1,0,0]
	v_exp_f32_e32 v100, v100
	v_exp_f32_e32 v101, v101
	v_pk_fma_f32 v[102:103], v[96:97], v[102:103], s[64:65] op_sel_hi:[1,1,0]
	v_pk_mul_f32 v[88:89], v[88:89], v[92:93]
	v_pk_fma_f32 v[102:103], v[96:97], v[102:103], s[66:67] op_sel_hi:[1,1,0]
	v_max_f32_e32 v92, 0, v94
	v_pk_fma_f32 v[102:103], v[96:97], v[102:103], s[68:69] op_sel_hi:[1,1,0]
	v_max_f32_e32 v93, 0, v95
	v_pk_mul_f32 v[96:97], v[96:97], v[102:103]
	v_pk_fma_f32 v[90:91], v[90:91], v[124:125], v[108:109]
	v_pk_mul_f32 v[96:97], v[100:101], v[96:97]
	v_add_lshl_u32 v116, v122, v164, 1
	v_pk_fma_f32 v[92:93], v[98:99], v[96:97], v[92:93] neg_lo:[1,0,0] neg_hi:[1,0,0]
	v_cvt_pk_bf16_f32 v88, v88, v89
	v_pk_mul_f32 v[90:91], v[90:91], v[92:93]
	s_nop 0
	v_cvt_pk_bf16_f32 v89, v90, v91
	global_store_dwordx2 v116, v[88:89], s[40:41]
; __device__ __forceinline__ unsigned pk2(float lo, float hi) { const f32x2 v = {lo, hi}; return __builtin_bit_cast(unsigned, __builtin_convertvector(v, bf16x2_hw)); }
;     template <bool EDGE> __device__ __forceinline__ void body(const f32x4 (&acc)[2][2][4][2], const pg8::Unit& u, int wr, int wc, int fr, int fq) const {
;     ...
;             const f32x4 wv0 = *(const f32x4*)(conv_w + ch), wv1 = *(const f32x4*)(conv_w + NUP + ch), wv2 = *(const f32x4*)(conv_w + 2 * NUP + ch), bv = *(const f32x4*)(conv_b + ch);
;             const f32x4 wg0 = *(const f32x4*)(conv_w + DFF + ch), wg1 = *(const f32x4*)(conv_w + NUP + DFF + ch), wg2 = *(const f32x4*)(conv_w + 2 * NUP + DFF + ch), bg = *(const f32x4*)(conv_b + DFF + ch);
;             const f32x4 v7 = dpp_shr1(acc[1][0][3][n]), v6 = dpp_shr1(acc[1][0][2][n]), g7 = dpp_shr1(acc[1][1][3][n]), g6 = dpp_shr1(acc[1][1][2][n]);
; #pragma unroll
;             for (int k = 0; k < 8; ++k) {
;                 const int ai = k >> 2, m = k & 3, lr = 8 * fr + k, tau = tw0 + lr, sp = tau & 4095;
;                 const f32x4 cv = acc[ai][0][m][n], cg = acc[ai][1][m][n];
;                 const f32x4 p1v = k >= 1 ? acc[(k >= 1 ? k - 1 : 0) >> 2][0][(k >= 1 ? k - 1 : 0) & 3][n] : v7;
;                 const f32x4 p1g = k >= 1 ? acc[(k >= 1 ? k - 1 : 0) >> 2][1][(k >= 1 ? k - 1 : 0) & 3][n] : g7;
;                 const f32x4 p2v = k >= 2 ? acc[(k >= 2 ? k - 2 : 0) >> 2][0][(k >= 2 ? k - 2 : 0) & 3][n] : (k == 1 ? v7 : v6);
;                 const f32x4 p2g = k >= 2 ? acc[(k >= 2 ? k - 2 : 0) >> 2][1][(k >= 2 ? k - 2 : 0) & 3][n] : (k == 1 ? g7 : g6);
;                 f32x4 val, gat;
;                 if (EDGE) { const float m1 = sp >= 1 ? 1.f : 0.f, m2 = sp >= 2 ? 1.f : 0.f;
;                     val = bv + wv2 * cv + (wv1 * m1) * p1v + (wv0 * m2) * p2v; gat = bg + wg2 * cg + (wg1 * m1) * p1g + (wg0 * m2) * p2g; }
;                 else { val = bv + wv2 * cv + wv1 * p1v + wv0 * p2v; gat = bg + wg2 * cg + wg1 * p1g + wg0 * p2g; }
;                 const f32x2 g01 = gelu_pk((f32x2){gat[0], gat[1]}), g23 = gelu_pk((f32x2){gat[2], gat[3]});
;                 u32x2 w; w.x = pk2(g01.x * val[0], g01.y * val[1]); w.y = pk2(g23.x * val[2], g23.y * val[3]);
;                 if (lr >= 2 && tau < NT) *(u32x2*)((char*)hidden + (unsigned)(tau * DFF + ch) * 2u) = w;
.LBB0_826:
	s_or_b64 exec, exec, s[20:21]
	v_add_u32_e32 v88, s25, v203
	v_and_b32_e32 v116, 0xfff, v88
	v_cmp_gt_i32_e64 s[18:19], s59, v88
	v_mul_lo_u32 v123, v88, s73
	s_and_saveexec_b64 s[24:25], s[18:19]
	s_cbranch_execz .LBB0_828
	v_pk_fma_f32 v[80:81], v[80:81], v[152:153], v[156:157]
	v_cmp_eq_u32_e64 s[20:21], 1, v116
	v_pk_fma_f32 v[80:81], v[84:85], v[148:149], v[80:81]
	v_pk_fma_f32 v[82:83], v[82:83], v[154:155], v[158:159]
	v_cndmask_b32_e64 v84, 1.0, 0, s[20:21]
	v_pk_mul_f32 v[88:89], v[84:85], v[144:145] op_sel_hi:[0,1]
	v_pk_fma_f32 v[82:83], v[86:87], v[150:151], v[82:83]
	v_pk_mul_f32 v[86:87], v[84:85], v[146:147] op_sel_hi:[0,1]
	v_pk_fma_f32 v[76:77], v[76:77], v[88:89], v[80:81]
	v_pk_fma_f32 v[78:79], v[78:79], v[86:87], v[82:83]
	v_and_b32_e32 v87, 0x7fffffff, v77
	v_and_b32_e32 v86, 0x7fffffff, v76
	v_pk_fma_f32 v[92:93], v[86:87], s[58:59], 1.0 op_sel_hi:[1,0,0]
	v_pk_fma_f32 v[66:67], v[66:67], v[138:139], v[142:143]
	v_pk_fma_f32 v[64:65], v[64:65], v[136:137], v[140:141]
	v_and_b32_e32 v83, 0x7fffffff, v79
	v_and_b32_e32 v82, 0x7fffffff, v78
	v_rcp_f32_e32 v92, v92
	v_rcp_f32_e32 v93, v93
	v_pk_fma_f32 v[66:67], v[70:71], v[134:135], v[66:67]
	v_pk_fma_f32 v[64:65], v[68:69], v[132:133], v[64:65]
	v_pk_mul_f32 v[70:71], v[84:85], v[128:129] op_sel_hi:[0,1]
	v_pk_fma_f32 v[64:65], v[72:73], v[70:71], v[64:65]
	v_pk_fma_f32 v[70:71], v[82:83], s[58:59], 1.0 op_sel_hi:[1,0,0]
	v_pk_mul_f32 v[90:91], v[76:77], v[76:77]
	v_rcp_f32_e32 v70, v70
	v_rcp_f32_e32 v71, v71
	v_mov_b64_e32 v[94:95], s[62:63]
	v_pk_mul_f32 v[90:91], v[90:91], s[56:57] op_sel_hi:[1,0]
	v_pk_fma_f32 v[96:97], v[92:93], s[60:61], v[94:95] op_sel_hi:[1,0,0]
	v_pk_mul_f32 v[88:89], v[78:79], v[78:79]
	v_exp_f32_e32 v90, v90
	v_exp_f32_e32 v91, v91
	v_pk_fma_f32 v[96:97], v[92:93], v[96:97], s[64:65] op_sel_hi:[1,1,0]
	v_pk_mul_f32 v[68:69], v[84:85], v[130:131] op_sel_hi:[0,1]
	v_pk_fma_f32 v[96:97], v[92:93], v[96:97], s[66:67] op_sel_hi:[1,1,0]
	v_pk_fma_f32 v[66:67], v[74:75], v[68:69], v[66:67]
	v_pk_mul_f32 v[72:73], v[88:89], s[56:57] op_sel_hi:[1,0]
	v_pk_fma_f32 v[74:75], v[70:71], s[60:61], v[94:95] op_sel_hi:[1,0,0]
	v_pk_fma_f32 v[96:97], v[92:93], v[96:97], s[68:69] op_sel_hi:[1,1,0]
	v_exp_f32_e32 v72, v72
	v_exp_f32_e32 v73, v73
	v_pk_fma_f32 v[74:75], v[70:71], v[74:75], s[64:65] op_sel_hi:[1,1,0]
	v_pk_mul_f32 v[92:93], v[92:93], v[96:97]
	v_pk_fma_f32 v[74:75], v[70:71], v[74:75], s[66:67] op_sel_hi:[1,1,0]
	v_max_f32_e32 v80, 0, v76
	v_pk_mul_f32 v[90:91], v[90:91], v[92:93]
	v_max_f32_e32 v81, 0, v77
	v_pk_fma_f32 v[74:75], v[70:71], v[74:75], s[68:69] op_sel_hi:[1,1,0]
	v_pk_fma_f32 v[68:69], v[86:87], v[90:91], v[80:81] neg_lo:[1,0,0] neg_hi:[1,0,0]
	v_pk_mul_f32 v[70:71], v[70:71], v[74:75]
	v_pk_mul_f32 v[64:65], v[64:65], v[68:69]
	v_max_f32_e32 v68, 0, v78
	v_pk_mul_f32 v[70:71], v[72:73], v[70:71]
	v_max_f32_e32 v69, 0, v79
	v_pk_fma_f32 v[68:69], v[82:83], v[70:71], v[68:69] neg_lo:[1,0,0] neg_hi:[1,0,0]
	v_add_lshl_u32 v98, v123, v164, 1
	v_pk_mul_f32 v[66:67], v[66:67], v[68:69]
	v_cvt_pk_bf16_f32 v64, v64, v65
	v_cvt_pk_bf16_f32 v65, v66, v67
	global_store_dwordx2 v98, v[64:65], s[40:41]
.LBB0_828:
	s_or_b64 exec, exec, s[24:25]
	v_or_b32_e32 v96, 4, v164
	v_ashrrev_i32_e32 v97, 31, v96
	v_lshlrev_b64 v[92:93], 2, v[96:97]
	v_lshl_add_u64 v[68:69], s[44:45], 0, v[92:93]
	v_lshl_add_u64 v[72:73], s[46:47], 0, v[92:93]
	global_load_dwordx4 v[64:67], v[166:167], off offset:16
	s_nop 0
	global_load_dwordx4 v[68:71], v[68:69], off
	s_nop 0
	global_load_dwordx4 v[72:75], v[72:73], off
	s_nop 0
	global_load_dwordx4 v[76:79], v[168:169], off offset:16
	v_lshl_add_u64 v[80:81], s[48:49], 0, v[92:93]
	v_lshl_add_u64 v[84:85], s[50:51], 0, v[92:93]
	v_lshl_add_u64 v[88:89], s[52:53], 0, v[92:93]
	v_lshl_add_u64 v[92:93], s[54:55], 0, v[92:93]
	global_load_dwordx4 v[80:83], v[80:81], off
	s_nop 0
	global_load_dwordx4 v[84:87], v[84:85], off
	v_mov_b32_e32 v98, 0
	global_load_dwordx4 v[88:91], v[88:89], off
	v_mov_b32_e32 v99, 0
	global_load_dwordx4 v[92:95], v[92:93], off
	v_mov_b32_e32 v100, 0
	v_mov_b32_e32 v101, 0
	v_mov_b32_e32 v106, 0
	v_mov_b32_e32 v107, 0
	v_mov_b32_e32 v108, 0
	v_mov_b32_e32 v109, 0
	v_mov_b32_e32 v102, 0
	v_mov_b32_e32 v103, 0
	v_mov_b32_e32 v104, 0
	v_mov_b32_e32 v105, 0
	v_mov_b32_e32 v110, 0
	v_mov_b32_e32 v111, 0
	v_mov_b32_e32 v112, 0
	v_mov_b32_e32 v113, 0
	v_mov_b32_dpp v98, v0 row_shr:1 row_mask:0xf bank_mask:0xf
	v_mov_b32_dpp v99, v1 row_shr:1 row_mask:0xf bank_mask:0xf
	v_mov_b32_dpp v100, v2 row_shr:1 row_mask:0xf bank_mask:0xf
	v_mov_b32_dpp v101, v3 row_shr:1 row_mask:0xf bank_mask:0xf
	v_mov_b32_dpp v106, v4 row_shr:1 row_mask:0xf bank_mask:0xf
	v_mov_b32_dpp v107, v5 row_shr:1 row_mask:0xf bank_mask:0xf
	v_mov_b32_dpp v108, v6 row_shr:1 row_mask:0xf bank_mask:0xf
	v_mov_b32_dpp v109, v7 row_shr:1 row_mask:0xf bank_mask:0xf
	v_mov_b32_dpp v102, v12 row_shr:1 row_mask:0xf bank_mask:0xf
	v_mov_b32_dpp v103, v13 row_shr:1 row_mask:0xf bank_mask:0xf
	v_mov_b32_dpp v104, v14 row_shr:1 row_mask:0xf bank_mask:0xf
	v_mov_b32_dpp v105, v15 row_shr:1 row_mask:0xf bank_mask:0xf
	v_mov_b32_dpp v110, v20 row_shr:1 row_mask:0xf bank_mask:0xf
	v_mov_b32_dpp v111, v21 row_shr:1 row_mask:0xf bank_mask:0xf
	v_mov_b32_dpp v112, v22 row_shr:1 row_mask:0xf bank_mask:0xf
	v_mov_b32_dpp v113, v23 row_shr:1 row_mask:0xf bank_mask:0xf
	s_waitcnt vmcnt(0)
	s_and_saveexec_b64 s[24:25], s[0:1]
	s_cbranch_execnz .LBB0_841
	s_or_b64 exec, exec, s[24:25]
	s_and_saveexec_b64 s[0:1], s[2:3]
	s_cbranch_execnz .LBB0_842

; __device__ __forceinline__ unsigned pk2(float lo, float hi) { const f32x2 v = {lo, hi}; return __builtin_bit_cast(unsigned, __builtin_convertvector(v, bf16x2_hw)); }
;     template <bool EDGE> __device__ __forceinline__ void body(const f32x4 (&acc)[2][2][4][2], const pg8::Unit& u, int wr, int wc, int fr, int fq) const {
;     ...
;                 const int ai = k >> 2, m = k & 3, lr = 8 * fr + k, tau = tw0 + lr, sp = tau & 4095;
;                 const f32x4 cv = acc[ai][0][m][n], cg = acc[ai][1][m][n];
;                 const f32x4 p1v = k >= 1 ? acc[(k >= 1 ? k - 1 : 0) >> 2][0][(k >= 1 ? k - 1 : 0) & 3][n] : v7;
;                 const f32x4 p1g = k >= 1 ? acc[(k >= 1 ? k - 1 : 0) >> 2][1][(k >= 1 ? k - 1 : 0) & 3][n] : g7;
;                 const f32x4 p2v = k >= 2 ? acc[(k >= 2 ? k - 2 : 0) >> 2][0][(k >= 2 ? k - 2 : 0) & 3][n] : (k == 1 ? v7 : v6);
;                 const f32x4 p2g = k >= 2 ? acc[(k >= 2 ? k - 2 : 0) >> 2][1][(k >= 2 ? k - 2 : 0) & 3][n] : (k == 1 ? g7 : g6);
;                 f32x4 val, gat;
;                 if (EDGE) { const float m1 = sp >= 1 ? 1.f : 0.f, m2 = sp >= 2 ? 1.f : 0.f;
;                     val = bv + wv2 * cv + (wv1 * m1) * p1v + (wv0 * m2) * p2v; gat = bg + wg2 * cg + (wg1 * m1) * p1g + (wg0 * m2) * p2g; }
;                 else { val = bv + wv2 * cv + wv1 * p1v + wv0 * p2v; gat = bg + wg2 * cg + wg1 * p1g + wg0 * p2g; }
;                 const f32x2 g01 = gelu_pk((f32x2){gat[0], gat[1]}), g23 = gelu_pk((f32x2){gat[2], gat[3]});
;                 u32x2 w; w.x = pk2(g01.x * val[0], g01.y * val[1]); w.y = pk2(g23.x * val[2], g23.y * val[3]);
;                 if (lr >= 2 && tau < NT) *(u32x2*)((char*)hidden + (unsigned)(tau * DFF + ch) * 2u) = w;
.LBB0_836:
	v_pk_fma_f32 v[12:13], v[12:13], v[88:89], v[92:93]
	v_cmp_eq_u32_e32 vcc, 1, v116
	v_pk_fma_f32 v[12:13], v[20:21], v[84:85], v[12:13]
	v_pk_fma_f32 v[14:15], v[14:15], v[90:91], v[94:95]
	v_cndmask_b32_e64 v20, 1.0, 0, vcc
	v_pk_mul_f32 v[24:25], v[20:21], v[80:81] op_sel_hi:[0,1]
	v_pk_fma_f32 v[14:15], v[22:23], v[86:87], v[14:15]
	v_pk_mul_f32 v[22:23], v[20:21], v[82:83] op_sel_hi:[0,1]
	v_pk_fma_f32 v[12:13], v[16:17], v[24:25], v[12:13]
	v_pk_fma_f32 v[14:15], v[18:19], v[22:23], v[14:15]
	v_and_b32_e32 v23, 0x7fffffff, v13
	v_and_b32_e32 v22, 0x7fffffff, v12
	v_pk_fma_f32 v[28:29], v[22:23], s[58:59], 1.0 op_sel_hi:[1,0,0]
	v_pk_fma_f32 v[2:3], v[2:3], v[74:75], v[78:79]
	v_pk_fma_f32 v[0:1], v[0:1], v[72:73], v[76:77]
	v_and_b32_e32 v19, 0x7fffffff, v15
	v_and_b32_e32 v18, 0x7fffffff, v14
	v_rcp_f32_e32 v28, v28
	v_rcp_f32_e32 v29, v29
	v_pk_fma_f32 v[2:3], v[6:7], v[70:71], v[2:3]
	v_pk_fma_f32 v[0:1], v[4:5], v[68:69], v[0:1]
	v_pk_mul_f32 v[6:7], v[20:21], v[64:65] op_sel_hi:[0,1]
	v_pk_fma_f32 v[0:1], v[8:9], v[6:7], v[0:1]
	v_pk_fma_f32 v[6:7], v[18:19], s[58:59], 1.0 op_sel_hi:[1,0,0]
	v_pk_mul_f32 v[26:27], v[12:13], v[12:13]
	v_rcp_f32_e32 v6, v6
	v_rcp_f32_e32 v7, v7
	v_mov_b64_e32 v[30:31], s[62:63]
	v_pk_mul_f32 v[26:27], v[26:27], s[56:57] op_sel_hi:[1,0]
	v_pk_fma_f32 v[32:33], v[28:29], s[60:61], v[30:31] op_sel_hi:[1,0,0]
	v_pk_mul_f32 v[24:25], v[14:15], v[14:15]
	v_exp_f32_e32 v26, v26
	v_exp_f32_e32 v27, v27
	v_pk_fma_f32 v[32:33], v[28:29], v[32:33], s[64:65] op_sel_hi:[1,1,0]
	v_pk_mul_f32 v[4:5], v[20:21], v[66:67] op_sel_hi:[0,1]
	v_pk_fma_f32 v[32:33], v[28:29], v[32:33], s[66:67] op_sel_hi:[1,1,0]
	v_pk_fma_f32 v[2:3], v[10:11], v[4:5], v[2:3]
	v_pk_mul_f32 v[8:9], v[24:25], s[56:57] op_sel_hi:[1,0]
	v_pk_fma_f32 v[10:11], v[6:7], s[60:61], v[30:31] op_sel_hi:[1,0,0]
	v_pk_fma_f32 v[32:33], v[28:29], v[32:33], s[68:69] op_sel_hi:[1,1,0]
	v_exp_f32_e32 v8, v8
	v_exp_f32_e32 v9, v9
	v_pk_fma_f32 v[10:11], v[6:7], v[10:11], s[64:65] op_sel_hi:[1,1,0]
	v_pk_mul_f32 v[28:29], v[28:29], v[32:33]
	v_pk_fma_f32 v[10:11], v[6:7], v[10:11], s[66:67] op_sel_hi:[1,1,0]
	v_max_f32_e32 v16, 0, v12
	v_pk_mul_f32 v[26:27], v[26:27], v[28:29]
	v_max_f32_e32 v17, 0, v13
	v_pk_fma_f32 v[10:11], v[6:7], v[10:11], s[68:69] op_sel_hi:[1,1,0]
	v_pk_fma_f32 v[4:5], v[22:23], v[26:27], v[16:17] neg_lo:[1,0,0] neg_hi:[1,0,0]
	v_pk_mul_f32 v[6:7], v[6:7], v[10:11]
	v_pk_mul_f32 v[0:1], v[0:1], v[4:5]
	v_max_f32_e32 v4, 0, v14
	v_pk_mul_f32 v[6:7], v[8:9], v[6:7]
	v_max_f32_e32 v5, 0, v15
	v_pk_fma_f32 v[4:5], v[18:19], v[6:7], v[4:5] neg_lo:[1,0,0] neg_hi:[1,0,0]
	v_add_lshl_u32 v34, v123, v96, 1
	v_pk_mul_f32 v[2:3], v[2:3], v[4:5]
	v_cvt_pk_bf16_f32 v0, v0, v1
	v_cvt_pk_bf16_f32 v1, v2, v3
	global_store_dwordx2 v34, v[0:1], s[40:41]

; __device__ __forceinline__ unsigned pk2(float lo, float hi) { const f32x2 v = {lo, hi}; return __builtin_bit_cast(unsigned, __builtin_convertvector(v, bf16x2_hw)); }
;     template <bool EDGE> __device__ __forceinline__ void body(const f32x4 (&acc)[2][2][4][2], const pg8::Unit& u, int wr, int wc, int fr, int fq) const {
;     ...
;                 const int ai = k >> 2, m = k & 3, lr = 8 * fr + k, tau = tw0 + lr, sp = tau & 4095;
;                 const f32x4 cv = acc[ai][0][m][n], cg = acc[ai][1][m][n];
;                 const f32x4 p1v = k >= 1 ? acc[(k >= 1 ? k - 1 : 0) >> 2][0][(k >= 1 ? k - 1 : 0) & 3][n] : v7;
;                 const f32x4 p1g = k >= 1 ? acc[(k >= 1 ? k - 1 : 0) >> 2][1][(k >= 1 ? k - 1 : 0) & 3][n] : g7;
;                 const f32x4 p2v = k >= 2 ? acc[(k >= 2 ? k - 2 : 0) >> 2][0][(k >= 2 ? k - 2 : 0) & 3][n] : (k == 1 ? v7 : v6);
;                 const f32x4 p2g = k >= 2 ? acc[(k >= 2 ? k - 2 : 0) >> 2][1][(k >= 2 ? k - 2 : 0) & 3][n] : (k == 1 ? g7 : g6);
;                 f32x4 val, gat;
;                 if (EDGE) { const float m1 = sp >= 1 ? 1.f : 0.f, m2 = sp >= 2 ? 1.f : 0.f;
;                     val = bv + wv2 * cv + (wv1 * m1) * p1v + (wv0 * m2) * p2v; gat = bg + wg2 * cg + (wg1 * m1) * p1g + (wg0 * m2) * p2g; }
;                 else { val = bv + wv2 * cv + wv1 * p1v + wv0 * p2v; gat = bg + wg2 * cg + wg1 * p1g + wg0 * p2g; }
;                 const f32x2 g01 = gelu_pk((f32x2){gat[0], gat[1]}), g23 = gelu_pk((f32x2){gat[2], gat[3]});
;                 u32x2 w; w.x = pk2(g01.x * val[0], g01.y * val[1]); w.y = pk2(g23.x * val[2], g23.y * val[3]);
;                 if (lr >= 2 && tau < NT) *(u32x2*)((char*)hidden + (unsigned)(tau * DFF + ch) * 2u) = w;
.LBB0_841:
	v_cmp_eq_u32_e64 s[20:21], 0, v165
	v_pk_fma_f32 v[126:127], v[60:61], v[88:89], v[92:93]
	v_pk_fma_f32 v[124:125], v[62:63], v[90:91], v[94:95]
	v_cndmask_b32_e64 v128, 1.0, 0, s[20:21]
	v_pk_mul_f32 v[132:133], v[128:129], v[84:85] op_sel_hi:[0,1]
	v_pk_mul_f32 v[130:131], v[128:129], v[86:87] op_sel_hi:[0,1]
	v_pk_fma_f32 v[126:127], v[132:133], v[102:103], v[126:127]
	v_pk_mul_f32 v[132:133], v[128:129], v[80:81] op_sel_hi:[0,1]
	v_pk_fma_f32 v[124:125], v[130:131], v[104:105], v[124:125]
	v_pk_mul_f32 v[130:131], v[128:129], v[82:83] op_sel_hi:[0,1]
	v_pk_fma_f32 v[110:111], v[132:133], v[110:111], v[126:127]
	v_pk_fma_f32 v[112:113], v[130:131], v[112:113], v[124:125]
	v_and_b32_e32 v131, 0x7fffffff, v111
	v_and_b32_e32 v130, 0x7fffffff, v110
	v_pk_fma_f32 v[136:137], v[130:131], s[58:59], 1.0 op_sel_hi:[1,0,0]
	v_pk_mul_f32 v[134:135], v[110:111], v[110:111]
	v_rcp_f32_e32 v136, v136
	v_rcp_f32_e32 v137, v137
	v_mov_b64_e32 v[138:139], s[62:63]
	v_pk_mul_f32 v[134:135], v[134:135], s[56:57] op_sel_hi:[1,0]
	v_max_f32_e32 v124, 0, v110
	v_pk_fma_f32 v[140:141], v[136:137], s[60:61], v[138:139] op_sel_hi:[1,0,0]
	v_exp_f32_e32 v134, v134
	v_exp_f32_e32 v135, v135
	v_pk_fma_f32 v[140:141], v[136:137], v[140:141], s[64:65] op_sel_hi:[1,1,0]
	v_and_b32_e32 v127, 0x7fffffff, v113
	v_pk_fma_f32 v[140:141], v[136:137], v[140:141], s[66:67] op_sel_hi:[1,1,0]
	v_and_b32_e32 v126, 0x7fffffff, v112
	v_pk_fma_f32 v[140:141], v[136:137], v[140:141], s[68:69] op_sel_hi:[1,1,0]
	v_max_f32_e32 v125, 0, v111
	v_pk_mul_f32 v[136:137], v[136:137], v[140:141]
	v_pk_fma_f32 v[140:141], v[56:57], v[72:73], v[76:77]
	v_pk_mul_f32 v[134:135], v[134:135], v[136:137]
	v_pk_fma_f32 v[136:137], v[58:59], v[74:75], v[78:79]
	v_pk_fma_f32 v[110:111], v[130:131], v[134:135], v[124:125] neg_lo:[1,0,0] neg_hi:[1,0,0]
	v_pk_fma_f32 v[124:125], v[126:127], s[58:59], 1.0 op_sel_hi:[1,0,0]
	v_pk_mul_f32 v[142:143], v[128:129], v[70:71] op_sel_hi:[0,1]
	v_rcp_f32_e32 v124, v124
	v_rcp_f32_e32 v125, v125
	v_pk_mul_f32 v[144:145], v[128:129], v[68:69] op_sel_hi:[0,1]
	v_pk_mul_f32 v[132:133], v[112:113], v[112:113]
	v_pk_fma_f32 v[136:137], v[142:143], v[100:101], v[136:137]
	v_pk_fma_f32 v[140:141], v[144:145], v[98:99], v[140:141]
	v_pk_mul_f32 v[142:143], v[128:129], v[66:67] op_sel_hi:[0,1]
	v_pk_mul_f32 v[128:129], v[128:129], v[64:65] op_sel_hi:[0,1]
	v_pk_fma_f32 v[106:107], v[128:129], v[106:107], v[140:141]
	v_pk_mul_f32 v[128:129], v[132:133], s[56:57] op_sel_hi:[1,0]
	v_pk_fma_f32 v[130:131], v[124:125], s[60:61], v[138:139] op_sel_hi:[1,0,0]
	v_exp_f32_e32 v128, v128
	v_exp_f32_e32 v129, v129
	v_pk_fma_f32 v[130:131], v[124:125], v[130:131], s[64:65] op_sel_hi:[1,1,0]
	v_pk_mul_f32 v[106:107], v[106:107], v[110:111]
	v_pk_fma_f32 v[130:131], v[124:125], v[130:131], s[66:67] op_sel_hi:[1,1,0]
	v_max_f32_e32 v110, 0, v112
	v_pk_fma_f32 v[130:131], v[124:125], v[130:131], s[68:69] op_sel_hi:[1,1,0]
	v_max_f32_e32 v111, 0, v113
	v_pk_mul_f32 v[124:125], v[124:125], v[130:131]
	v_pk_fma_f32 v[108:109], v[142:143], v[108:109], v[136:137]
	v_pk_mul_f32 v[124:125], v[128:129], v[124:125]
	v_add_lshl_u32 v97, v210, v96, 1
	v_pk_fma_f32 v[110:111], v[126:127], v[124:125], v[110:111] neg_lo:[1,0,0] neg_hi:[1,0,0]
	v_cvt_pk_bf16_f32 v106, v106, v107
	v_pk_mul_f32 v[108:109], v[108:109], v[110:111]
	s_nop 0
	v_cvt_pk_bf16_f32 v107, v108, v109
	global_store_dwordx2 v97, v[106:107], s[40:41]
	s_or_b64 exec, exec, s[24:25]
	s_and_saveexec_b64 s[0:1], s[2:3]
	s_cbranch_execz .LBB0_830
.LBB0_842:
	v_cmp_eq_u32_e64 s[20:21], 1, v178
	v_pk_fma_f32 v[108:109], v[52:53], v[88:89], v[92:93]
	v_pk_fma_f32 v[106:107], v[54:55], v[90:91], v[94:95]
	v_cndmask_b32_e64 v110, 1.0, 0, s[20:21]
	v_pk_fma_f32 v[108:109], v[60:61], v[84:85], v[108:109]
	v_pk_mul_f32 v[124:125], v[110:111], v[80:81] op_sel_hi:[0,1]
	v_pk_fma_f32 v[106:107], v[62:63], v[86:87], v[106:107]
	v_pk_mul_f32 v[112:113], v[110:111], v[82:83] op_sel_hi:[0,1]
	v_pk_fma_f32 v[102:103], v[124:125], v[102:103], v[108:109]
	v_pk_fma_f32 v[104:105], v[112:113], v[104:105], v[106:107]
	v_and_b32_e32 v113, 0x7fffffff, v103
	v_and_b32_e32 v112, 0x7fffffff, v102
	v_pk_fma_f32 v[128:129], v[112:113], s[58:59], 1.0 op_sel_hi:[1,0,0]
	v_pk_mul_f32 v[126:127], v[102:103], v[102:103]
	v_rcp_f32_e32 v128, v128
	v_rcp_f32_e32 v129, v129
	v_mov_b64_e32 v[130:131], s[62:63]
	v_pk_mul_f32 v[126:127], v[126:127], s[56:57] op_sel_hi:[1,0]
	v_max_f32_e32 v106, 0, v102
	v_pk_fma_f32 v[132:133], v[128:129], s[60:61], v[130:131] op_sel_hi:[1,0,0]
	v_exp_f32_e32 v126, v126
	v_exp_f32_e32 v127, v127
	v_pk_fma_f32 v[132:133], v[128:129], v[132:133], s[64:65] op_sel_hi:[1,1,0]
	v_and_b32_e32 v109, 0x7fffffff, v105
	v_pk_fma_f32 v[132:133], v[128:129], v[132:133], s[66:67] op_sel_hi:[1,1,0]
	v_and_b32_e32 v108, 0x7fffffff, v104
	v_pk_fma_f32 v[132:133], v[128:129], v[132:133], s[68:69] op_sel_hi:[1,1,0]
	v_max_f32_e32 v107, 0, v103
	v_pk_mul_f32 v[128:129], v[128:129], v[132:133]
	v_pk_fma_f32 v[132:133], v[48:49], v[72:73], v[76:77]
	v_pk_mul_f32 v[126:127], v[126:127], v[128:129]
	v_pk_mul_f32 v[124:125], v[104:105], v[104:105]
	v_pk_fma_f32 v[102:103], v[112:113], v[126:127], v[106:107] neg_lo:[1,0,0] neg_hi:[1,0,0]
	v_pk_fma_f32 v[106:107], v[108:109], s[58:59], 1.0 op_sel_hi:[1,0,0]
	v_pk_fma_f32 v[132:133], v[56:57], v[68:69], v[132:133]
	v_rcp_f32_e32 v106, v106
	v_rcp_f32_e32 v107, v107
	v_pk_mul_f32 v[134:135], v[110:111], v[66:67] op_sel_hi:[0,1]
	v_pk_mul_f32 v[110:111], v[110:111], v[64:65] op_sel_hi:[0,1]
	v_pk_fma_f32 v[98:99], v[110:111], v[98:99], v[132:133]
	v_pk_mul_f32 v[110:111], v[124:125], s[56:57] op_sel_hi:[1,0]
	v_pk_fma_f32 v[112:113], v[106:107], s[60:61], v[130:131] op_sel_hi:[1,0,0]
	v_exp_f32_e32 v110, v110
	v_exp_f32_e32 v111, v111
	v_pk_fma_f32 v[112:113], v[106:107], v[112:113], s[64:65] op_sel_hi:[1,1,0]
	v_pk_fma_f32 v[128:129], v[50:51], v[74:75], v[78:79]
	v_pk_fma_f32 v[112:113], v[106:107], v[112:113], s[66:67] op_sel_hi:[1,1,0]
	v_pk_fma_f32 v[128:129], v[58:59], v[70:71], v[128:129]
	v_pk_fma_f32 v[112:113], v[106:107], v[112:113], s[68:69] op_sel_hi:[1,1,0]
	v_pk_mul_f32 v[98:99], v[98:99], v[102:103]
	v_pk_mul_f32 v[106:107], v[106:107], v[112:113]
	v_max_f32_e32 v102, 0, v104
	v_pk_mul_f32 v[106:107], v[110:111], v[106:107]
	v_max_f32_e32 v103, 0, v105
	v_pk_fma_f32 v[100:101], v[134:135], v[100:101], v[128:129]
	v_pk_fma_f32 v[102:103], v[108:109], v[106:107], v[102:103] neg_lo:[1,0,0] neg_hi:[1,0,0]
	v_add_lshl_u32 v97, v179, v96, 1
	v_pk_mul_f32 v[100:101], v[100:101], v[102:103]
	v_cvt_pk_bf16_f32 v98, v98, v99
	v_cvt_pk_bf16_f32 v99, v100, v101
	global_store_dwordx2 v97, v[98:99], s[40:41]
	s_or_b64 exec, exec, s[0:1]
	s_and_saveexec_b64 s[0:1], vcc
	s_cbranch_execz .LBB0_831
; __device__ __forceinline__ unsigned pk2(float lo, float hi) { const f32x2 v = {lo, hi}; return __builtin_bit_cast(unsigned, __builtin_convertvector(v, bf16x2_hw)); }
;     template <bool EDGE> __device__ __forceinline__ void body(const f32x4 (&acc)[2][2][4][2], const pg8::Unit& u, int wr, int wc, int fr, int fq) const {
;     ...
;                 const int ai = k >> 2, m = k & 3, lr = 8 * fr + k, tau = tw0 + lr, sp = tau & 4095;
;                 const f32x4 cv = acc[ai][0][m][n], cg = acc[ai][1][m][n];
;                 const f32x4 p1v = k >= 1 ? acc[(k >= 1 ? k - 1 : 0) >> 2][0][(k >= 1 ? k - 1 : 0) & 3][n] : v7;
;                 const f32x4 p1g = k >= 1 ? acc[(k >= 1 ? k - 1 : 0) >> 2][1][(k >= 1 ? k - 1 : 0) & 3][n] : g7;
;                 const f32x4 p2v = k >= 2 ? acc[(k >= 2 ? k - 2 : 0) >> 2][0][(k >= 2 ? k - 2 : 0) & 3][n] : (k == 1 ? v7 : v6);
;                 const f32x4 p2g = k >= 2 ? acc[(k >= 2 ? k - 2 : 0) >> 2][1][(k >= 2 ? k - 2 : 0) & 3][n] : (k == 1 ? g7 : g6);
;                 f32x4 val, gat;
;                 if (EDGE) { const float m1 = sp >= 1 ? 1.f : 0.f, m2 = sp >= 2 ? 1.f : 0.f;
;                     val = bv + wv2 * cv + (wv1 * m1) * p1v + (wv0 * m2) * p2v; gat = bg + wg2 * cg + (wg1 * m1) * p1g + (wg0 * m2) * p2g; }
;                 else { val = bv + wv2 * cv + wv1 * p1v + wv0 * p2v; gat = bg + wg2 * cg + wg1 * p1g + wg0 * p2g; }
;                 const f32x2 g01 = gelu_pk((f32x2){gat[0], gat[1]}), g23 = gelu_pk((f32x2){gat[2], gat[3]});
;                 u32x2 w; w.x = pk2(g01.x * val[0], g01.y * val[1]); w.y = pk2(g23.x * val[2], g23.y * val[3]);
;                 if (lr >= 2 && tau < NT) *(u32x2*)((char*)hidden + (unsigned)(tau * DFF + ch) * 2u) = w;
.LBB0_843:
	v_cmp_eq_u32_e32 vcc, 0, v170
	v_pk_fma_f32 v[100:101], v[44:45], v[88:89], v[92:93]
	v_pk_fma_f32 v[98:99], v[46:47], v[90:91], v[94:95]
	v_cndmask_b32_e64 v102, 1.0, 0, vcc
	v_pk_mul_f32 v[106:107], v[102:103], v[84:85] op_sel_hi:[0,1]
	v_pk_mul_f32 v[104:105], v[102:103], v[86:87] op_sel_hi:[0,1]
	v_pk_fma_f32 v[100:101], v[52:53], v[106:107], v[100:101]
	v_pk_mul_f32 v[106:107], v[102:103], v[80:81] op_sel_hi:[0,1]
	v_pk_fma_f32 v[98:99], v[54:55], v[104:105], v[98:99]
	v_pk_mul_f32 v[104:105], v[102:103], v[82:83] op_sel_hi:[0,1]
	v_pk_fma_f32 v[60:61], v[60:61], v[106:107], v[100:101]
	v_pk_fma_f32 v[62:63], v[62:63], v[104:105], v[98:99]
	v_and_b32_e32 v105, 0x7fffffff, v61
	v_and_b32_e32 v104, 0x7fffffff, v60
	v_pk_fma_f32 v[110:111], v[104:105], s[58:59], 1.0 op_sel_hi:[1,0,0]
	v_pk_mul_f32 v[108:109], v[60:61], v[60:61]
	v_rcp_f32_e32 v110, v110
	v_rcp_f32_e32 v111, v111
	v_mov_b64_e32 v[112:113], s[62:63]
	v_pk_mul_f32 v[108:109], v[108:109], s[56:57] op_sel_hi:[1,0]
	v_max_f32_e32 v98, 0, v60
	v_pk_fma_f32 v[124:125], v[110:111], s[60:61], v[112:113] op_sel_hi:[1,0,0]
	v_exp_f32_e32 v108, v108
	v_exp_f32_e32 v109, v109
	v_pk_fma_f32 v[124:125], v[110:111], v[124:125], s[64:65] op_sel_hi:[1,1,0]
	v_and_b32_e32 v101, 0x7fffffff, v63
	v_pk_fma_f32 v[124:125], v[110:111], v[124:125], s[66:67] op_sel_hi:[1,1,0]
	v_and_b32_e32 v100, 0x7fffffff, v62
	v_pk_fma_f32 v[124:125], v[110:111], v[124:125], s[68:69] op_sel_hi:[1,1,0]
	v_max_f32_e32 v99, 0, v61
	v_pk_mul_f32 v[110:111], v[110:111], v[124:125]
	v_pk_fma_f32 v[124:125], v[40:41], v[72:73], v[76:77]
	v_pk_mul_f32 v[108:109], v[108:109], v[110:111]
	v_pk_fma_f32 v[110:111], v[42:43], v[74:75], v[78:79]
	v_pk_fma_f32 v[60:61], v[104:105], v[108:109], v[98:99] neg_lo:[1,0,0] neg_hi:[1,0,0]
	v_pk_fma_f32 v[98:99], v[100:101], s[58:59], 1.0 op_sel_hi:[1,0,0]
	v_pk_mul_f32 v[126:127], v[102:103], v[70:71] op_sel_hi:[0,1]
	v_rcp_f32_e32 v98, v98
	v_rcp_f32_e32 v99, v99
	v_pk_mul_f32 v[128:129], v[102:103], v[68:69] op_sel_hi:[0,1]
	v_pk_mul_f32 v[106:107], v[62:63], v[62:63]
	v_pk_fma_f32 v[110:111], v[50:51], v[126:127], v[110:111]
	v_pk_fma_f32 v[124:125], v[48:49], v[128:129], v[124:125]
	v_pk_mul_f32 v[126:127], v[102:103], v[66:67] op_sel_hi:[0,1]
	v_pk_mul_f32 v[102:103], v[102:103], v[64:65] op_sel_hi:[0,1]
	v_pk_fma_f32 v[56:57], v[56:57], v[102:103], v[124:125]
	v_pk_mul_f32 v[102:103], v[106:107], s[56:57] op_sel_hi:[1,0]
	v_pk_fma_f32 v[104:105], v[98:99], s[60:61], v[112:113] op_sel_hi:[1,0,0]
	v_exp_f32_e32 v102, v102
	v_exp_f32_e32 v103, v103
	v_pk_fma_f32 v[104:105], v[98:99], v[104:105], s[64:65] op_sel_hi:[1,1,0]
	v_pk_mul_f32 v[56:57], v[56:57], v[60:61]
	v_pk_fma_f32 v[104:105], v[98:99], v[104:105], s[66:67] op_sel_hi:[1,1,0]
	v_max_f32_e32 v60, 0, v62
	v_pk_fma_f32 v[104:105], v[98:99], v[104:105], s[68:69] op_sel_hi:[1,1,0]
	v_max_f32_e32 v61, 0, v63
	v_pk_mul_f32 v[98:99], v[98:99], v[104:105]
	v_pk_fma_f32 v[58:59], v[58:59], v[126:127], v[110:111]
	v_pk_mul_f32 v[98:99], v[102:103], v[98:99]
	v_add_lshl_u32 v97, v171, v96, 1
	v_pk_fma_f32 v[60:61], v[100:101], v[98:99], v[60:61] neg_lo:[1,0,0] neg_hi:[1,0,0]
	v_cvt_pk_bf16_f32 v56, v56, v57
	v_pk_mul_f32 v[58:59], v[58:59], v[60:61]
	s_nop 0
	v_cvt_pk_bf16_f32 v57, v58, v59
	global_store_dwordx2 v97, v[56:57], s[40:41]
	s_or_b64 exec, exec, s[0:1]
	s_and_saveexec_b64 s[0:1], s[10:11]
	s_cbranch_execz .LBB0_832
.LBB0_844:
	v_cmp_eq_u32_e32 vcc, 1, v120
	v_pk_fma_f32 v[58:59], v[36:37], v[88:89], v[92:93]
	v_pk_fma_f32 v[56:57], v[38:39], v[90:91], v[94:95]
	v_cndmask_b32_e64 v60, 1.0, 0, vcc
	v_pk_fma_f32 v[58:59], v[44:45], v[84:85], v[58:59]
	v_pk_mul_f32 v[98:99], v[60:61], v[80:81] op_sel_hi:[0,1]
	v_pk_fma_f32 v[56:57], v[46:47], v[86:87], v[56:57]
	v_pk_mul_f32 v[62:63], v[60:61], v[82:83] op_sel_hi:[0,1]
	v_pk_fma_f32 v[52:53], v[52:53], v[98:99], v[58:59]
	v_pk_fma_f32 v[54:55], v[54:55], v[62:63], v[56:57]
	v_and_b32_e32 v63, 0x7fffffff, v53
	v_and_b32_e32 v62, 0x7fffffff, v52
	v_pk_fma_f32 v[102:103], v[62:63], s[58:59], 1.0 op_sel_hi:[1,0,0]
	v_pk_mul_f32 v[100:101], v[52:53], v[52:53]
	v_rcp_f32_e32 v102, v102
	v_rcp_f32_e32 v103, v103
	v_mov_b64_e32 v[104:105], s[62:63]
	v_pk_mul_f32 v[100:101], v[100:101], s[56:57] op_sel_hi:[1,0]
	v_max_f32_e32 v56, 0, v52
	v_pk_fma_f32 v[106:107], v[102:103], s[60:61], v[104:105] op_sel_hi:[1,0,0]
	v_exp_f32_e32 v100, v100
	v_exp_f32_e32 v101, v101
	v_pk_fma_f32 v[106:107], v[102:103], v[106:107], s[64:65] op_sel_hi:[1,1,0]
	v_and_b32_e32 v59, 0x7fffffff, v55
	v_pk_fma_f32 v[106:107], v[102:103], v[106:107], s[66:67] op_sel_hi:[1,1,0]
	v_and_b32_e32 v58, 0x7fffffff, v54
	v_pk_fma_f32 v[106:107], v[102:103], v[106:107], s[68:69] op_sel_hi:[1,1,0]
	v_max_f32_e32 v57, 0, v53
	v_pk_mul_f32 v[102:103], v[102:103], v[106:107]
	v_pk_fma_f32 v[106:107], v[32:33], v[72:73], v[76:77]
	v_pk_mul_f32 v[100:101], v[100:101], v[102:103]
	v_pk_mul_f32 v[98:99], v[54:55], v[54:55]
	v_pk_fma_f32 v[52:53], v[62:63], v[100:101], v[56:57] neg_lo:[1,0,0] neg_hi:[1,0,0]
	v_pk_fma_f32 v[56:57], v[58:59], s[58:59], 1.0 op_sel_hi:[1,0,0]
	v_pk_fma_f32 v[106:107], v[40:41], v[68:69], v[106:107]
	v_rcp_f32_e32 v56, v56
	v_rcp_f32_e32 v57, v57
	v_pk_mul_f32 v[108:109], v[60:61], v[66:67] op_sel_hi:[0,1]
	v_pk_mul_f32 v[60:61], v[60:61], v[64:65] op_sel_hi:[0,1]
	v_pk_fma_f32 v[48:49], v[48:49], v[60:61], v[106:107]
	v_pk_mul_f32 v[60:61], v[98:99], s[56:57] op_sel_hi:[1,0]
	v_pk_fma_f32 v[62:63], v[56:57], s[60:61], v[104:105] op_sel_hi:[1,0,0]
	v_exp_f32_e32 v60, v60
	v_exp_f32_e32 v61, v61
	v_pk_fma_f32 v[62:63], v[56:57], v[62:63], s[64:65] op_sel_hi:[1,1,0]
	v_pk_fma_f32 v[102:103], v[34:35], v[74:75], v[78:79]
	v_pk_fma_f32 v[62:63], v[56:57], v[62:63], s[66:67] op_sel_hi:[1,1,0]
	v_pk_fma_f32 v[102:103], v[42:43], v[70:71], v[102:103]
	v_pk_fma_f32 v[62:63], v[56:57], v[62:63], s[68:69] op_sel_hi:[1,1,0]
	v_pk_mul_f32 v[48:49], v[48:49], v[52:53]
	v_pk_mul_f32 v[56:57], v[56:57], v[62:63]
	v_max_f32_e32 v52, 0, v54
	v_pk_mul_f32 v[56:57], v[60:61], v[56:57]
	v_max_f32_e32 v53, 0, v55
	v_pk_fma_f32 v[50:51], v[50:51], v[108:109], v[102:103]
	v_pk_fma_f32 v[52:53], v[58:59], v[56:57], v[52:53] neg_lo:[1,0,0] neg_hi:[1,0,0]
	v_add_lshl_u32 v97, v121, v96, 1
	v_pk_mul_f32 v[50:51], v[50:51], v[52:53]
	v_cvt_pk_bf16_f32 v48, v48, v49
	v_cvt_pk_bf16_f32 v49, v50, v51
	global_store_dwordx2 v97, v[48:49], s[40:41]
	s_or_b64 exec, exec, s[0:1]
	s_and_saveexec_b64 s[0:1], s[12:13]
	s_cbranch_execz .LBB0_833
; __device__ __forceinline__ unsigned pk2(float lo, float hi) { const f32x2 v = {lo, hi}; return __builtin_bit_cast(unsigned, __builtin_convertvector(v, bf16x2_hw)); }
;     template <bool EDGE> __device__ __forceinline__ void body(const f32x4 (&acc)[2][2][4][2], const pg8::Unit& u, int wr, int wc, int fr, int fq) const {
;     ...
;                 const int ai = k >> 2, m = k & 3, lr = 8 * fr + k, tau = tw0 + lr, sp = tau & 4095;
;                 const f32x4 cv = acc[ai][0][m][n], cg = acc[ai][1][m][n];
;                 const f32x4 p1v = k >= 1 ? acc[(k >= 1 ? k - 1 : 0) >> 2][0][(k >= 1 ? k - 1 : 0) & 3][n] : v7;
;                 const f32x4 p1g = k >= 1 ? acc[(k >= 1 ? k - 1 : 0) >> 2][1][(k >= 1 ? k - 1 : 0) & 3][n] : g7;
;                 const f32x4 p2v = k >= 2 ? acc[(k >= 2 ? k - 2 : 0) >> 2][0][(k >= 2 ? k - 2 : 0) & 3][n] : (k == 1 ? v7 : v6);
;                 const f32x4 p2g = k >= 2 ? acc[(k >= 2 ? k - 2 : 0) >> 2][1][(k >= 2 ? k - 2 : 0) & 3][n] : (k == 1 ? g7 : g6);
;                 f32x4 val, gat;
;                 if (EDGE) { const float m1 = sp >= 1 ? 1.f : 0.f, m2 = sp >= 2 ? 1.f : 0.f;
;                     val = bv + wv2 * cv + (wv1 * m1) * p1v + (wv0 * m2) * p2v; gat = bg + wg2 * cg + (wg1 * m1) * p1g + (wg0 * m2) * p2g; }
;                 else { val = bv + wv2 * cv + wv1 * p1v + wv0 * p2v; gat = bg + wg2 * cg + wg1 * p1g + wg0 * p2g; }
;                 const f32x2 g01 = gelu_pk((f32x2){gat[0], gat[1]}), g23 = gelu_pk((f32x2){gat[2], gat[3]});
;                 u32x2 w; w.x = pk2(g01.x * val[0], g01.y * val[1]); w.y = pk2(g23.x * val[2], g23.y * val[3]);
;                 if (lr >= 2 && tau < NT) *(u32x2*)((char*)hidden + (unsigned)(tau * DFF + ch) * 2u) = w;
.LBB0_845:
	v_cmp_eq_u32_e32 vcc, 0, v115
	v_pk_fma_f32 v[50:51], v[28:29], v[88:89], v[92:93]
	v_pk_fma_f32 v[48:49], v[30:31], v[90:91], v[94:95]
	v_cndmask_b32_e64 v52, 1.0, 0, vcc
	v_pk_mul_f32 v[56:57], v[52:53], v[84:85] op_sel_hi:[0,1]
	v_pk_mul_f32 v[54:55], v[52:53], v[86:87] op_sel_hi:[0,1]
	v_pk_fma_f32 v[50:51], v[36:37], v[56:57], v[50:51]
	v_pk_mul_f32 v[56:57], v[52:53], v[80:81] op_sel_hi:[0,1]
	v_pk_fma_f32 v[48:49], v[38:39], v[54:55], v[48:49]
	v_pk_mul_f32 v[54:55], v[52:53], v[82:83] op_sel_hi:[0,1]
	v_pk_fma_f32 v[44:45], v[44:45], v[56:57], v[50:51]
	v_pk_fma_f32 v[46:47], v[46:47], v[54:55], v[48:49]
	v_and_b32_e32 v55, 0x7fffffff, v45
	v_and_b32_e32 v54, 0x7fffffff, v44
	v_pk_fma_f32 v[60:61], v[54:55], s[58:59], 1.0 op_sel_hi:[1,0,0]
	v_pk_mul_f32 v[58:59], v[44:45], v[44:45]
	v_rcp_f32_e32 v60, v60
	v_rcp_f32_e32 v61, v61
	v_mov_b64_e32 v[62:63], s[62:63]
	v_pk_mul_f32 v[58:59], v[58:59], s[56:57] op_sel_hi:[1,0]
	v_max_f32_e32 v48, 0, v44
	v_pk_fma_f32 v[98:99], v[60:61], s[60:61], v[62:63] op_sel_hi:[1,0,0]
	v_exp_f32_e32 v58, v58
	v_exp_f32_e32 v59, v59
	v_pk_fma_f32 v[98:99], v[60:61], v[98:99], s[64:65] op_sel_hi:[1,1,0]
	v_and_b32_e32 v51, 0x7fffffff, v47
	v_pk_fma_f32 v[98:99], v[60:61], v[98:99], s[66:67] op_sel_hi:[1,1,0]
	v_and_b32_e32 v50, 0x7fffffff, v46
	v_pk_fma_f32 v[98:99], v[60:61], v[98:99], s[68:69] op_sel_hi:[1,1,0]
	v_max_f32_e32 v49, 0, v45
	v_pk_mul_f32 v[60:61], v[60:61], v[98:99]
	v_pk_fma_f32 v[98:99], v[24:25], v[72:73], v[76:77]
	v_pk_mul_f32 v[58:59], v[58:59], v[60:61]
	v_pk_fma_f32 v[60:61], v[26:27], v[74:75], v[78:79]
	v_pk_fma_f32 v[44:45], v[54:55], v[58:59], v[48:49] neg_lo:[1,0,0] neg_hi:[1,0,0]
	v_pk_fma_f32 v[48:49], v[50:51], s[58:59], 1.0 op_sel_hi:[1,0,0]
	v_pk_mul_f32 v[100:101], v[52:53], v[70:71] op_sel_hi:[0,1]
	v_rcp_f32_e32 v48, v48
	v_rcp_f32_e32 v49, v49
	v_pk_mul_f32 v[102:103], v[52:53], v[68:69] op_sel_hi:[0,1]
	v_pk_mul_f32 v[56:57], v[46:47], v[46:47]
	v_pk_fma_f32 v[60:61], v[34:35], v[100:101], v[60:61]
	v_pk_fma_f32 v[98:99], v[32:33], v[102:103], v[98:99]
	v_pk_mul_f32 v[100:101], v[52:53], v[66:67] op_sel_hi:[0,1]
	v_pk_mul_f32 v[52:53], v[52:53], v[64:65] op_sel_hi:[0,1]
	v_pk_fma_f32 v[40:41], v[40:41], v[52:53], v[98:99]
	v_pk_mul_f32 v[52:53], v[56:57], s[56:57] op_sel_hi:[1,0]
	v_pk_fma_f32 v[54:55], v[48:49], s[60:61], v[62:63] op_sel_hi:[1,0,0]
	v_exp_f32_e32 v52, v52
	v_exp_f32_e32 v53, v53
	v_pk_fma_f32 v[54:55], v[48:49], v[54:55], s[64:65] op_sel_hi:[1,1,0]
	v_pk_mul_f32 v[40:41], v[40:41], v[44:45]
	v_pk_fma_f32 v[54:55], v[48:49], v[54:55], s[66:67] op_sel_hi:[1,1,0]
	v_max_f32_e32 v44, 0, v46
	v_pk_fma_f32 v[54:55], v[48:49], v[54:55], s[68:69] op_sel_hi:[1,1,0]
	v_max_f32_e32 v45, 0, v47
	v_pk_mul_f32 v[48:49], v[48:49], v[54:55]
	v_pk_fma_f32 v[42:43], v[42:43], v[100:101], v[60:61]
	v_pk_mul_f32 v[48:49], v[52:53], v[48:49]
	v_add_lshl_u32 v97, v118, v96, 1
	v_pk_fma_f32 v[44:45], v[50:51], v[48:49], v[44:45] neg_lo:[1,0,0] neg_hi:[1,0,0]
	v_cvt_pk_bf16_f32 v40, v40, v41
	v_pk_mul_f32 v[42:43], v[42:43], v[44:45]
	s_nop 0
	v_cvt_pk_bf16_f32 v41, v42, v43
	global_store_dwordx2 v97, v[40:41], s[40:41]
	s_or_b64 exec, exec, s[0:1]
	s_and_saveexec_b64 s[0:1], s[14:15]
	s_cbranch_execz .LBB0_834
.LBB0_846:
	v_cmp_eq_u32_e32 vcc, 1, v114
	v_pk_fma_f32 v[42:43], v[16:17], v[88:89], v[92:93]
	v_pk_fma_f32 v[40:41], v[18:19], v[90:91], v[94:95]
	v_cndmask_b32_e64 v44, 1.0, 0, vcc
	v_pk_fma_f32 v[42:43], v[28:29], v[84:85], v[42:43]
	v_pk_mul_f32 v[48:49], v[44:45], v[80:81] op_sel_hi:[0,1]
	v_pk_fma_f32 v[40:41], v[30:31], v[86:87], v[40:41]
	v_pk_mul_f32 v[46:47], v[44:45], v[82:83] op_sel_hi:[0,1]
	v_pk_fma_f32 v[36:37], v[36:37], v[48:49], v[42:43]
	v_pk_fma_f32 v[38:39], v[38:39], v[46:47], v[40:41]
	v_and_b32_e32 v47, 0x7fffffff, v37
	v_and_b32_e32 v46, 0x7fffffff, v36
	v_pk_fma_f32 v[52:53], v[46:47], s[58:59], 1.0 op_sel_hi:[1,0,0]
	v_pk_mul_f32 v[50:51], v[36:37], v[36:37]
	v_rcp_f32_e32 v52, v52
	v_rcp_f32_e32 v53, v53
	v_mov_b64_e32 v[54:55], s[62:63]
	v_pk_mul_f32 v[50:51], v[50:51], s[56:57] op_sel_hi:[1,0]
	v_max_f32_e32 v40, 0, v36
	v_pk_fma_f32 v[56:57], v[52:53], s[60:61], v[54:55] op_sel_hi:[1,0,0]
	v_exp_f32_e32 v50, v50
	v_exp_f32_e32 v51, v51
	v_pk_fma_f32 v[56:57], v[52:53], v[56:57], s[64:65] op_sel_hi:[1,1,0]
	v_and_b32_e32 v43, 0x7fffffff, v39
	v_pk_fma_f32 v[56:57], v[52:53], v[56:57], s[66:67] op_sel_hi:[1,1,0]
	v_and_b32_e32 v42, 0x7fffffff, v38
	v_pk_fma_f32 v[56:57], v[52:53], v[56:57], s[68:69] op_sel_hi:[1,1,0]
	v_max_f32_e32 v41, 0, v37
	v_pk_mul_f32 v[52:53], v[52:53], v[56:57]
	v_pk_fma_f32 v[56:57], v[8:9], v[72:73], v[76:77]
	v_pk_mul_f32 v[50:51], v[50:51], v[52:53]
	v_pk_mul_f32 v[48:49], v[38:39], v[38:39]
	v_pk_fma_f32 v[36:37], v[46:47], v[50:51], v[40:41] neg_lo:[1,0,0] neg_hi:[1,0,0]
	v_pk_fma_f32 v[40:41], v[42:43], s[58:59], 1.0 op_sel_hi:[1,0,0]
	v_pk_fma_f32 v[56:57], v[24:25], v[68:69], v[56:57]
	v_rcp_f32_e32 v40, v40
	v_rcp_f32_e32 v41, v41
	v_pk_mul_f32 v[58:59], v[44:45], v[66:67] op_sel_hi:[0,1]
	v_pk_mul_f32 v[44:45], v[44:45], v[64:65] op_sel_hi:[0,1]
	v_pk_fma_f32 v[32:33], v[32:33], v[44:45], v[56:57]
	v_pk_mul_f32 v[44:45], v[48:49], s[56:57] op_sel_hi:[1,0]
	v_pk_fma_f32 v[46:47], v[40:41], s[60:61], v[54:55] op_sel_hi:[1,0,0]
	v_exp_f32_e32 v44, v44
	v_exp_f32_e32 v45, v45
	v_pk_fma_f32 v[46:47], v[40:41], v[46:47], s[64:65] op_sel_hi:[1,1,0]
	v_pk_fma_f32 v[52:53], v[10:11], v[74:75], v[78:79]
	v_pk_fma_f32 v[46:47], v[40:41], v[46:47], s[66:67] op_sel_hi:[1,1,0]
	v_pk_fma_f32 v[52:53], v[26:27], v[70:71], v[52:53]
	v_pk_fma_f32 v[46:47], v[40:41], v[46:47], s[68:69] op_sel_hi:[1,1,0]
	v_pk_mul_f32 v[32:33], v[32:33], v[36:37]
	v_pk_mul_f32 v[40:41], v[40:41], v[46:47]
	v_max_f32_e32 v36, 0, v38
	v_pk_mul_f32 v[40:41], v[44:45], v[40:41]
	v_max_f32_e32 v37, 0, v39
	v_pk_fma_f32 v[34:35], v[34:35], v[58:59], v[52:53]
	v_pk_fma_f32 v[36:37], v[42:43], v[40:41], v[36:37] neg_lo:[1,0,0] neg_hi:[1,0,0]
	v_add_lshl_u32 v60, v119, v96, 1
	v_pk_mul_f32 v[34:35], v[34:35], v[36:37]
	v_cvt_pk_bf16_f32 v32, v32, v33
	v_cvt_pk_bf16_f32 v33, v34, v35
	global_store_dwordx2 v60, v[32:33], s[40:41]
	s_or_b64 exec, exec, s[0:1]
	s_and_saveexec_b64 s[0:1], s[16:17]
	s_cbranch_execz .LBB0_835
; __device__ __forceinline__ unsigned pk2(float lo, float hi) { const f32x2 v = {lo, hi}; return __builtin_bit_cast(unsigned, __builtin_convertvector(v, bf16x2_hw)); }
;     template <bool EDGE> __device__ __forceinline__ void body(const f32x4 (&acc)[2][2][4][2], const pg8::Unit& u, int wr, int wc, int fr, int fq) const {
;     ...
;                 const int ai = k >> 2, m = k & 3, lr = 8 * fr + k, tau = tw0 + lr, sp = tau & 4095;
;                 const f32x4 cv = acc[ai][0][m][n], cg = acc[ai][1][m][n];
;                 const f32x4 p1v = k >= 1 ? acc[(k >= 1 ? k - 1 : 0) >> 2][0][(k >= 1 ? k - 1 : 0) & 3][n] : v7;
;                 const f32x4 p1g = k >= 1 ? acc[(k >= 1 ? k - 1 : 0) >> 2][1][(k >= 1 ? k - 1 : 0) & 3][n] : g7;
;                 const f32x4 p2v = k >= 2 ? acc[(k >= 2 ? k - 2 : 0) >> 2][0][(k >= 2 ? k - 2 : 0) & 3][n] : (k == 1 ? v7 : v6);
;                 const f32x4 p2g = k >= 2 ? acc[(k >= 2 ? k - 2 : 0) >> 2][1][(k >= 2 ? k - 2 : 0) & 3][n] : (k == 1 ? g7 : g6);
;                 f32x4 val, gat;
;                 if (EDGE) { const float m1 = sp >= 1 ? 1.f : 0.f, m2 = sp >= 2 ? 1.f : 0.f;
;                     val = bv + wv2 * cv + (wv1 * m1) * p1v + (wv0 * m2) * p2v; gat = bg + wg2 * cg + (wg1 * m1) * p1g + (wg0 * m2) * p2g; }
;                 else { val = bv + wv2 * cv + wv1 * p1v + wv0 * p2v; gat = bg + wg2 * cg + wg1 * p1g + wg0 * p2g; }
;                 const f32x2 g01 = gelu_pk((f32x2){gat[0], gat[1]}), g23 = gelu_pk((f32x2){gat[2], gat[3]});
;                 u32x2 w; w.x = pk2(g01.x * val[0], g01.y * val[1]); w.y = pk2(g23.x * val[2], g23.y * val[3]);
;                 if (lr >= 2 && tau < NT) *(u32x2*)((char*)hidden + (unsigned)(tau * DFF + ch) * 2u) = w;
.LBB0_847:
	v_cmp_eq_u32_e32 vcc, 0, v117
	v_pk_fma_f32 v[34:35], v[20:21], v[88:89], v[92:93]
	v_pk_fma_f32 v[32:33], v[22:23], v[90:91], v[94:95]
	v_cndmask_b32_e64 v36, 1.0, 0, vcc
	v_pk_mul_f32 v[40:41], v[36:37], v[84:85] op_sel_hi:[0,1]
	v_pk_mul_f32 v[38:39], v[36:37], v[86:87] op_sel_hi:[0,1]
	v_pk_fma_f32 v[34:35], v[16:17], v[40:41], v[34:35]
	v_pk_mul_f32 v[40:41], v[36:37], v[80:81] op_sel_hi:[0,1]
	v_pk_fma_f32 v[32:33], v[18:19], v[38:39], v[32:33]
	v_pk_mul_f32 v[38:39], v[36:37], v[82:83] op_sel_hi:[0,1]
	v_pk_fma_f32 v[28:29], v[28:29], v[40:41], v[34:35]
	v_pk_fma_f32 v[30:31], v[30:31], v[38:39], v[32:33]
	v_and_b32_e32 v39, 0x7fffffff, v29
	v_and_b32_e32 v38, 0x7fffffff, v28
	v_pk_fma_f32 v[44:45], v[38:39], s[58:59], 1.0 op_sel_hi:[1,0,0]
	v_pk_mul_f32 v[42:43], v[28:29], v[28:29]
	v_rcp_f32_e32 v44, v44
	v_rcp_f32_e32 v45, v45
	v_mov_b64_e32 v[46:47], s[62:63]
	v_pk_mul_f32 v[42:43], v[42:43], s[56:57] op_sel_hi:[1,0]
	v_max_f32_e32 v32, 0, v28
	v_pk_fma_f32 v[48:49], v[44:45], s[60:61], v[46:47] op_sel_hi:[1,0,0]
	v_exp_f32_e32 v42, v42
	v_exp_f32_e32 v43, v43
	v_pk_fma_f32 v[48:49], v[44:45], v[48:49], s[64:65] op_sel_hi:[1,1,0]
	v_and_b32_e32 v35, 0x7fffffff, v31
	v_pk_fma_f32 v[48:49], v[44:45], v[48:49], s[66:67] op_sel_hi:[1,1,0]
	v_and_b32_e32 v34, 0x7fffffff, v30
	v_pk_fma_f32 v[48:49], v[44:45], v[48:49], s[68:69] op_sel_hi:[1,1,0]
	v_max_f32_e32 v33, 0, v29
	v_pk_mul_f32 v[44:45], v[44:45], v[48:49]
	v_pk_fma_f32 v[48:49], v[4:5], v[72:73], v[76:77]
	v_pk_mul_f32 v[42:43], v[42:43], v[44:45]
	v_pk_fma_f32 v[44:45], v[6:7], v[74:75], v[78:79]
	v_pk_fma_f32 v[28:29], v[38:39], v[42:43], v[32:33] neg_lo:[1,0,0] neg_hi:[1,0,0]
	v_pk_fma_f32 v[32:33], v[34:35], s[58:59], 1.0 op_sel_hi:[1,0,0]
	v_pk_mul_f32 v[50:51], v[36:37], v[70:71] op_sel_hi:[0,1]
	v_rcp_f32_e32 v32, v32
	v_rcp_f32_e32 v33, v33
	v_pk_mul_f32 v[52:53], v[36:37], v[68:69] op_sel_hi:[0,1]
	v_pk_mul_f32 v[40:41], v[30:31], v[30:31]
	v_pk_fma_f32 v[44:45], v[10:11], v[50:51], v[44:45]
	v_pk_fma_f32 v[48:49], v[8:9], v[52:53], v[48:49]
	v_pk_mul_f32 v[50:51], v[36:37], v[66:67] op_sel_hi:[0,1]
	v_pk_mul_f32 v[36:37], v[36:37], v[64:65] op_sel_hi:[0,1]
	v_pk_fma_f32 v[24:25], v[24:25], v[36:37], v[48:49]
	v_pk_mul_f32 v[36:37], v[40:41], s[56:57] op_sel_hi:[1,0]
	v_pk_fma_f32 v[38:39], v[32:33], s[60:61], v[46:47] op_sel_hi:[1,0,0]
	v_exp_f32_e32 v36, v36
	v_exp_f32_e32 v37, v37
	v_pk_fma_f32 v[38:39], v[32:33], v[38:39], s[64:65] op_sel_hi:[1,1,0]
	v_pk_mul_f32 v[24:25], v[24:25], v[28:29]
	v_pk_fma_f32 v[38:39], v[32:33], v[38:39], s[66:67] op_sel_hi:[1,1,0]
	v_max_f32_e32 v28, 0, v30
	v_pk_fma_f32 v[38:39], v[32:33], v[38:39], s[68:69] op_sel_hi:[1,1,0]
	v_max_f32_e32 v29, 0, v31
	v_pk_mul_f32 v[32:33], v[32:33], v[38:39]
	v_pk_fma_f32 v[26:27], v[26:27], v[50:51], v[44:45]
	v_pk_mul_f32 v[32:33], v[36:37], v[32:33]
	v_add_lshl_u32 v54, v122, v96, 1
	v_pk_fma_f32 v[28:29], v[34:35], v[32:33], v[28:29] neg_lo:[1,0,0] neg_hi:[1,0,0]
	v_cvt_pk_bf16_f32 v24, v24, v25
	v_pk_mul_f32 v[26:27], v[26:27], v[28:29]
	s_nop 0
	v_cvt_pk_bf16_f32 v25, v26, v27
	global_store_dwordx2 v54, v[24:25], s[40:41]
	s_or_b64 exec, exec, s[0:1]
	s_and_saveexec_b64 s[0:1], s[18:19]
	s_cbranch_execnz .LBB0_836
	s_branch .LBB0_837
.LBB0_848:
	v_pk_fma_f32 v[214:215], v[60:61], v[152:153], v[156:157]
	v_mov_b64_e32 v[224:225], s[62:63]
	v_pk_fma_f32 v[214:215], v[148:149], v[170:171], v[214:215]
	v_pk_fma_f32 v[188:189], v[62:63], v[154:155], v[158:159]
	v_pk_fma_f32 v[178:179], v[144:145], v[178:179], v[214:215]
	v_pk_fma_f32 v[188:189], v[150:151], v[172:173], v[188:189]
	v_and_b32_e32 v217, 0x7fffffff, v179
	v_and_b32_e32 v216, 0x7fffffff, v178
	v_pk_fma_f32 v[222:223], v[216:217], s[58:59], 1.0 op_sel_hi:[1,0,0]
	v_pk_mul_f32 v[220:221], v[178:179], v[178:179]
	v_rcp_f32_e32 v222, v222
	v_rcp_f32_e32 v223, v223
	v_pk_mul_f32 v[220:221], v[220:221], s[56:57] op_sel_hi:[1,0]
	v_pk_fma_f32 v[180:181], v[146:147], v[180:181], v[188:189]
	v_exp_f32_e32 v220, v220
	v_pk_fma_f32 v[226:227], v[222:223], s[60:61], v[224:225] op_sel_hi:[1,0,0]
	v_exp_f32_e32 v221, v221
	v_pk_fma_f32 v[226:227], v[222:223], v[226:227], s[64:65] op_sel_hi:[1,1,0]
	v_max_f32_e32 v188, 0, v178
	v_pk_fma_f32 v[226:227], v[222:223], v[226:227], s[66:67] op_sel_hi:[1,1,0]
	v_and_b32_e32 v215, 0x7fffffff, v181
	v_pk_fma_f32 v[226:227], v[222:223], v[226:227], s[68:69] op_sel_hi:[1,1,0]
	v_and_b32_e32 v214, 0x7fffffff, v180
	v_pk_mul_f32 v[222:223], v[222:223], v[226:227]
	v_max_f32_e32 v189, 0, v179
	v_pk_mul_f32 v[220:221], v[220:221], v[222:223]
	v_pk_mul_f32 v[218:219], v[180:181], v[180:181]
	v_pk_fma_f32 v[178:179], v[216:217], v[220:221], v[188:189] neg_lo:[1,0,0] neg_hi:[1,0,0]
	v_pk_fma_f32 v[188:189], v[214:215], s[58:59], 1.0 op_sel_hi:[1,0,0]
	v_pk_mul_f32 v[216:217], v[218:219], s[56:57] op_sel_hi:[1,0]
	v_rcp_f32_e32 v188, v188
	v_rcp_f32_e32 v189, v189
	v_exp_f32_e32 v216, v216
	v_exp_f32_e32 v217, v217
	v_pk_fma_f32 v[226:227], v[56:57], v[136:137], v[140:141]
	v_pk_fma_f32 v[218:219], v[188:189], s[60:61], v[224:225] op_sel_hi:[1,0,0]
	v_pk_fma_f32 v[226:227], v[132:133], v[166:167], v[226:227]
	v_pk_fma_f32 v[218:219], v[188:189], v[218:219], s[64:65] op_sel_hi:[1,1,0]
	v_pk_fma_f32 v[222:223], v[58:59], v[138:139], v[142:143]
	v_pk_fma_f32 v[218:219], v[188:189], v[218:219], s[66:67] op_sel_hi:[1,1,0]
	v_pk_fma_f32 v[174:175], v[128:129], v[174:175], v[226:227]
	v_pk_fma_f32 v[218:219], v[188:189], v[218:219], s[68:69] op_sel_hi:[1,1,0]
	v_pk_fma_f32 v[222:223], v[134:135], v[168:169], v[222:223]
	v_pk_mul_f32 v[188:189], v[188:189], v[218:219]
	v_pk_mul_f32 v[174:175], v[174:175], v[178:179]
	v_max_f32_e32 v178, 0, v180
	v_pk_mul_f32 v[188:189], v[216:217], v[188:189]
	v_max_f32_e32 v179, 0, v181
	v_pk_fma_f32 v[176:177], v[130:131], v[176:177], v[222:223]
	v_pk_fma_f32 v[178:179], v[214:215], v[188:189], v[178:179] neg_lo:[1,0,0] neg_hi:[1,0,0]
	v_add_lshl_u32 v165, v210, v164, 1
	v_pk_mul_f32 v[176:177], v[176:177], v[178:179]
	v_cvt_pk_bf16_f32 v174, v174, v175
	v_cvt_pk_bf16_f32 v175, v176, v177
	global_store_dwordx2 v165, v[174:175], s[40:41]
	s_or_b64 exec, exec, s[20:21]
	s_and_saveexec_b64 s[0:1], s[2:3]
	s_cbranch_execz .LBB0_803
; __device__ __forceinline__ unsigned pk2(float lo, float hi) { const f32x2 v = {lo, hi}; return __builtin_bit_cast(unsigned, __builtin_convertvector(v, bf16x2_hw)); }
;     template <bool EDGE> __device__ __forceinline__ void body(const f32x4 (&acc)[2][2][4][2], const pg8::Unit& u, int wr, int wc, int fr, int fq) const {
;     ...
;                 const int ai = k >> 2, m = k & 3, lr = 8 * fr + k, tau = tw0 + lr, sp = tau & 4095;
;                 const f32x4 cv = acc[ai][0][m][n], cg = acc[ai][1][m][n];
;                 const f32x4 p1v = k >= 1 ? acc[(k >= 1 ? k - 1 : 0) >> 2][0][(k >= 1 ? k - 1 : 0) & 3][n] : v7;
;                 const f32x4 p1g = k >= 1 ? acc[(k >= 1 ? k - 1 : 0) >> 2][1][(k >= 1 ? k - 1 : 0) & 3][n] : g7;
;                 const f32x4 p2v = k >= 2 ? acc[(k >= 2 ? k - 2 : 0) >> 2][0][(k >= 2 ? k - 2 : 0) & 3][n] : (k == 1 ? v7 : v6);
;                 const f32x4 p2g = k >= 2 ? acc[(k >= 2 ? k - 2 : 0) >> 2][1][(k >= 2 ? k - 2 : 0) & 3][n] : (k == 1 ? g7 : g6);
;                 f32x4 val, gat;
;                 if (EDGE) { const float m1 = sp >= 1 ? 1.f : 0.f, m2 = sp >= 2 ? 1.f : 0.f;
;                     val = bv + wv2 * cv + (wv1 * m1) * p1v + (wv0 * m2) * p2v; gat = bg + wg2 * cg + (wg1 * m1) * p1g + (wg0 * m2) * p2g; }
;                 else { val = bv + wv2 * cv + wv1 * p1v + wv0 * p2v; gat = bg + wg2 * cg + wg1 * p1g + wg0 * p2g; }
;                 const f32x2 g01 = gelu_pk((f32x2){gat[0], gat[1]}), g23 = gelu_pk((f32x2){gat[2], gat[3]});
;                 u32x2 w; w.x = pk2(g01.x * val[0], g01.y * val[1]); w.y = pk2(g23.x * val[2], g23.y * val[3]);
;                 if (lr >= 2 && tau < NT) *(u32x2*)((char*)hidden + (unsigned)(tau * DFF + ch) * 2u) = w;
.LBB0_849:
	v_pk_fma_f32 v[176:177], v[52:53], v[152:153], v[156:157]
	v_mov_b64_e32 v[216:217], s[62:63]
	v_pk_fma_f32 v[176:177], v[60:61], v[148:149], v[176:177]
	v_pk_fma_f32 v[174:175], v[54:55], v[154:155], v[158:159]
	v_pk_fma_f32 v[170:171], v[144:145], v[170:171], v[176:177]
	v_pk_fma_f32 v[174:175], v[62:63], v[150:151], v[174:175]
	v_and_b32_e32 v179, 0x7fffffff, v171
	v_and_b32_e32 v178, 0x7fffffff, v170
	v_pk_fma_f32 v[214:215], v[178:179], s[58:59], 1.0 op_sel_hi:[1,0,0]
	v_pk_mul_f32 v[188:189], v[170:171], v[170:171]
	v_rcp_f32_e32 v214, v214
	v_rcp_f32_e32 v215, v215
	v_pk_mul_f32 v[188:189], v[188:189], s[56:57] op_sel_hi:[1,0]
	v_pk_fma_f32 v[172:173], v[146:147], v[172:173], v[174:175]
	v_exp_f32_e32 v188, v188
	v_pk_fma_f32 v[218:219], v[214:215], s[60:61], v[216:217] op_sel_hi:[1,0,0]
	v_exp_f32_e32 v189, v189
	v_pk_fma_f32 v[218:219], v[214:215], v[218:219], s[64:65] op_sel_hi:[1,1,0]
	v_max_f32_e32 v174, 0, v170
	v_pk_fma_f32 v[218:219], v[214:215], v[218:219], s[66:67] op_sel_hi:[1,1,0]
	v_and_b32_e32 v177, 0x7fffffff, v173
	v_pk_fma_f32 v[218:219], v[214:215], v[218:219], s[68:69] op_sel_hi:[1,1,0]
	v_and_b32_e32 v176, 0x7fffffff, v172
	v_pk_mul_f32 v[214:215], v[214:215], v[218:219]
	v_max_f32_e32 v175, 0, v171
	v_pk_mul_f32 v[188:189], v[188:189], v[214:215]
	v_pk_mul_f32 v[180:181], v[172:173], v[172:173]
	v_pk_fma_f32 v[170:171], v[178:179], v[188:189], v[174:175] neg_lo:[1,0,0] neg_hi:[1,0,0]
	v_pk_fma_f32 v[174:175], v[176:177], s[58:59], 1.0 op_sel_hi:[1,0,0]
	v_pk_mul_f32 v[178:179], v[180:181], s[56:57] op_sel_hi:[1,0]
	v_rcp_f32_e32 v174, v174
	v_rcp_f32_e32 v175, v175
	v_exp_f32_e32 v178, v178
	v_exp_f32_e32 v179, v179
	v_pk_fma_f32 v[218:219], v[48:49], v[136:137], v[140:141]
	v_pk_fma_f32 v[180:181], v[174:175], s[60:61], v[216:217] op_sel_hi:[1,0,0]
	v_pk_fma_f32 v[218:219], v[56:57], v[132:133], v[218:219]
	v_pk_fma_f32 v[180:181], v[174:175], v[180:181], s[64:65] op_sel_hi:[1,1,0]
	v_pk_fma_f32 v[214:215], v[50:51], v[138:139], v[142:143]
	v_pk_fma_f32 v[180:181], v[174:175], v[180:181], s[66:67] op_sel_hi:[1,1,0]
	v_pk_fma_f32 v[166:167], v[128:129], v[166:167], v[218:219]
	v_pk_fma_f32 v[180:181], v[174:175], v[180:181], s[68:69] op_sel_hi:[1,1,0]
	v_pk_fma_f32 v[214:215], v[58:59], v[134:135], v[214:215]
	v_pk_mul_f32 v[174:175], v[174:175], v[180:181]
	v_pk_mul_f32 v[166:167], v[166:167], v[170:171]
	v_max_f32_e32 v170, 0, v172
	v_pk_mul_f32 v[174:175], v[178:179], v[174:175]
	v_max_f32_e32 v171, 0, v173
	v_pk_fma_f32 v[168:169], v[130:131], v[168:169], v[214:215]
	v_pk_fma_f32 v[170:171], v[176:177], v[174:175], v[170:171] neg_lo:[1,0,0] neg_hi:[1,0,0]
	v_add_lshl_u32 v165, v182, v164, 1
	v_pk_mul_f32 v[168:169], v[168:169], v[170:171]
	v_cvt_pk_bf16_f32 v166, v166, v167
	v_cvt_pk_bf16_f32 v167, v168, v169
	global_store_dwordx2 v165, v[166:167], s[40:41]
	s_or_b64 exec, exec, s[0:1]
	s_and_saveexec_b64 s[0:1], vcc
	s_cbranch_execz .LBB0_804
.LBB0_850:
	v_pk_fma_f32 v[168:169], v[44:45], v[152:153], v[156:157]
	v_add_lshl_u32 v165, v183, v164, 1
	v_pk_fma_f32 v[168:169], v[52:53], v[148:149], v[168:169]
	v_mov_b64_e32 v[182:183], s[62:63]
	v_pk_fma_f32 v[168:169], v[60:61], v[144:145], v[168:169]
	v_pk_fma_f32 v[166:167], v[46:47], v[154:155], v[158:159]
	v_and_b32_e32 v175, 0x7fffffff, v169
	v_and_b32_e32 v174, 0x7fffffff, v168
	v_pk_fma_f32 v[180:181], v[174:175], s[58:59], 1.0 op_sel_hi:[1,0,0]
	v_pk_mul_f32 v[178:179], v[168:169], v[168:169]
	v_rcp_f32_e32 v180, v180
	v_rcp_f32_e32 v181, v181
	v_pk_mul_f32 v[178:179], v[178:179], s[56:57] op_sel_hi:[1,0]
	v_pk_fma_f32 v[166:167], v[54:55], v[150:151], v[166:167]
	v_exp_f32_e32 v178, v178
	v_pk_fma_f32 v[188:189], v[180:181], s[60:61], v[182:183] op_sel_hi:[1,0,0]
	v_exp_f32_e32 v179, v179
	v_pk_fma_f32 v[188:189], v[180:181], v[188:189], s[64:65] op_sel_hi:[1,1,0]
	v_pk_fma_f32 v[166:167], v[62:63], v[146:147], v[166:167]
	v_pk_fma_f32 v[188:189], v[180:181], v[188:189], s[66:67] op_sel_hi:[1,1,0]
	v_max_f32_e32 v170, 0, v168
	v_pk_fma_f32 v[188:189], v[180:181], v[188:189], s[68:69] op_sel_hi:[1,1,0]
	v_and_b32_e32 v173, 0x7fffffff, v167
	v_pk_mul_f32 v[180:181], v[180:181], v[188:189]
	v_and_b32_e32 v172, 0x7fffffff, v166
	v_pk_mul_f32 v[178:179], v[178:179], v[180:181]
	v_max_f32_e32 v171, 0, v169
	v_pk_fma_f32 v[168:169], v[174:175], v[178:179], v[170:171] neg_lo:[1,0,0] neg_hi:[1,0,0]
	v_pk_fma_f32 v[170:171], v[172:173], s[58:59], 1.0 op_sel_hi:[1,0,0]
	v_pk_mul_f32 v[176:177], v[166:167], v[166:167]
	v_rcp_f32_e32 v170, v170
	v_rcp_f32_e32 v171, v171
	v_pk_mul_f32 v[174:175], v[176:177], s[56:57] op_sel_hi:[1,0]
	v_pk_fma_f32 v[180:181], v[42:43], v[138:139], v[142:143]
	v_exp_f32_e32 v174, v174
	v_pk_fma_f32 v[176:177], v[170:171], s[60:61], v[182:183] op_sel_hi:[1,0,0]
	v_exp_f32_e32 v175, v175
	v_pk_fma_f32 v[176:177], v[170:171], v[176:177], s[64:65] op_sel_hi:[1,1,0]
	v_pk_fma_f32 v[188:189], v[40:41], v[136:137], v[140:141]
	v_pk_fma_f32 v[176:177], v[170:171], v[176:177], s[66:67] op_sel_hi:[1,1,0]
	v_pk_fma_f32 v[180:181], v[50:51], v[134:135], v[180:181]
	v_pk_fma_f32 v[176:177], v[170:171], v[176:177], s[68:69] op_sel_hi:[1,1,0]
	v_pk_fma_f32 v[188:189], v[48:49], v[132:133], v[188:189]
	v_pk_mul_f32 v[170:171], v[170:171], v[176:177]
	v_max_f32_e32 v166, 0, v166
	v_pk_mul_f32 v[170:171], v[174:175], v[170:171]
	v_max_f32_e32 v167, 0, v167
	v_pk_fma_f32 v[180:181], v[58:59], v[130:131], v[180:181]
	v_pk_fma_f32 v[188:189], v[56:57], v[128:129], v[188:189]
	v_pk_fma_f32 v[166:167], v[172:173], v[170:171], v[166:167] neg_lo:[1,0,0] neg_hi:[1,0,0]
	v_pk_mul_f32 v[168:169], v[188:189], v[168:169]
	v_pk_mul_f32 v[166:167], v[180:181], v[166:167]
	v_cvt_pk_bf16_f32 v168, v168, v169
	v_cvt_pk_bf16_f32 v169, v166, v167
	global_store_dwordx2 v165, v[168:169], s[40:41]
	s_or_b64 exec, exec, s[0:1]
	s_and_saveexec_b64 s[0:1], s[10:11]
	s_cbranch_execz .LBB0_805
; __device__ __forceinline__ unsigned pk2(float lo, float hi) { const f32x2 v = {lo, hi}; return __builtin_bit_cast(unsigned, __builtin_convertvector(v, bf16x2_hw)); }
;     template <bool EDGE> __device__ __forceinline__ void body(const f32x4 (&acc)[2][2][4][2], const pg8::Unit& u, int wr, int wc, int fr, int fq) const {
;     ...
;                 const int ai = k >> 2, m = k & 3, lr = 8 * fr + k, tau = tw0 + lr, sp = tau & 4095;
;                 const f32x4 cv = acc[ai][0][m][n], cg = acc[ai][1][m][n];
;                 const f32x4 p1v = k >= 1 ? acc[(k >= 1 ? k - 1 : 0) >> 2][0][(k >= 1 ? k - 1 : 0) & 3][n] : v7;
;                 const f32x4 p1g = k >= 1 ? acc[(k >= 1 ? k - 1 : 0) >> 2][1][(k >= 1 ? k - 1 : 0) & 3][n] : g7;
;                 const f32x4 p2v = k >= 2 ? acc[(k >= 2 ? k - 2 : 0) >> 2][0][(k >= 2 ? k - 2 : 0) & 3][n] : (k == 1 ? v7 : v6);
;                 const f32x4 p2g = k >= 2 ? acc[(k >= 2 ? k - 2 : 0) >> 2][1][(k >= 2 ? k - 2 : 0) & 3][n] : (k == 1 ? g7 : g6);
;                 f32x4 val, gat;
;                 if (EDGE) { const float m1 = sp >= 1 ? 1.f : 0.f, m2 = sp >= 2 ? 1.f : 0.f;
;                     val = bv + wv2 * cv + (wv1 * m1) * p1v + (wv0 * m2) * p2v; gat = bg + wg2 * cg + (wg1 * m1) * p1g + (wg0 * m2) * p2g; }
;                 else { val = bv + wv2 * cv + wv1 * p1v + wv0 * p2v; gat = bg + wg2 * cg + wg1 * p1g + wg0 * p2g; }
;                 const f32x2 g01 = gelu_pk((f32x2){gat[0], gat[1]}), g23 = gelu_pk((f32x2){gat[2], gat[3]});
;                 u32x2 w; w.x = pk2(g01.x * val[0], g01.y * val[1]); w.y = pk2(g23.x * val[2], g23.y * val[3]);
;                 if (lr >= 2 && tau < NT) *(u32x2*)((char*)hidden + (unsigned)(tau * DFF + ch) * 2u) = w;
.LBB0_851:
	v_pk_fma_f32 v[168:169], v[36:37], v[152:153], v[156:157]
	v_mov_b64_e32 v[182:183], s[62:63]
	v_pk_fma_f32 v[168:169], v[44:45], v[148:149], v[168:169]
	v_pk_fma_f32 v[166:167], v[38:39], v[154:155], v[158:159]
	v_pk_fma_f32 v[168:169], v[52:53], v[144:145], v[168:169]
	v_pk_fma_f32 v[166:167], v[46:47], v[150:151], v[166:167]
	v_and_b32_e32 v175, 0x7fffffff, v169
	v_and_b32_e32 v174, 0x7fffffff, v168
	v_pk_fma_f32 v[180:181], v[174:175], s[58:59], 1.0 op_sel_hi:[1,0,0]
	v_pk_mul_f32 v[178:179], v[168:169], v[168:169]
	v_rcp_f32_e32 v180, v180
	v_rcp_f32_e32 v181, v181
	v_pk_mul_f32 v[178:179], v[178:179], s[56:57] op_sel_hi:[1,0]
	v_pk_fma_f32 v[166:167], v[54:55], v[146:147], v[166:167]
	v_exp_f32_e32 v178, v178
	v_pk_fma_f32 v[188:189], v[180:181], s[60:61], v[182:183] op_sel_hi:[1,0,0]
	v_exp_f32_e32 v179, v179
	v_pk_fma_f32 v[188:189], v[180:181], v[188:189], s[64:65] op_sel_hi:[1,1,0]
	v_max_f32_e32 v170, 0, v168
	v_pk_fma_f32 v[188:189], v[180:181], v[188:189], s[66:67] op_sel_hi:[1,1,0]
	v_and_b32_e32 v173, 0x7fffffff, v167
	v_pk_fma_f32 v[188:189], v[180:181], v[188:189], s[68:69] op_sel_hi:[1,1,0]
	v_and_b32_e32 v172, 0x7fffffff, v166
	v_pk_mul_f32 v[180:181], v[180:181], v[188:189]
	v_max_f32_e32 v171, 0, v169
	v_pk_mul_f32 v[178:179], v[178:179], v[180:181]
	v_pk_mul_f32 v[176:177], v[166:167], v[166:167]
	v_pk_fma_f32 v[168:169], v[174:175], v[178:179], v[170:171] neg_lo:[1,0,0] neg_hi:[1,0,0]
	v_pk_fma_f32 v[170:171], v[172:173], s[58:59], 1.0 op_sel_hi:[1,0,0]
	v_pk_mul_f32 v[174:175], v[176:177], s[56:57] op_sel_hi:[1,0]
	v_rcp_f32_e32 v170, v170
	v_rcp_f32_e32 v171, v171
	v_exp_f32_e32 v174, v174
	v_exp_f32_e32 v175, v175
	v_pk_fma_f32 v[180:181], v[34:35], v[138:139], v[142:143]
	v_pk_fma_f32 v[176:177], v[170:171], s[60:61], v[182:183] op_sel_hi:[1,0,0]
	v_pk_fma_f32 v[188:189], v[32:33], v[136:137], v[140:141]
	v_pk_fma_f32 v[176:177], v[170:171], v[176:177], s[64:65] op_sel_hi:[1,1,0]
	v_pk_fma_f32 v[180:181], v[42:43], v[134:135], v[180:181]
	v_pk_fma_f32 v[176:177], v[170:171], v[176:177], s[66:67] op_sel_hi:[1,1,0]
	v_pk_fma_f32 v[188:189], v[40:41], v[132:133], v[188:189]
	v_pk_fma_f32 v[176:177], v[170:171], v[176:177], s[68:69] op_sel_hi:[1,1,0]
	v_max_f32_e32 v166, 0, v166
	v_pk_mul_f32 v[170:171], v[170:171], v[176:177]
	v_max_f32_e32 v167, 0, v167
	v_pk_mul_f32 v[170:171], v[174:175], v[170:171]
	v_pk_fma_f32 v[180:181], v[50:51], v[130:131], v[180:181]
	v_pk_fma_f32 v[188:189], v[48:49], v[128:129], v[188:189]
	v_pk_fma_f32 v[166:167], v[172:173], v[170:171], v[166:167] neg_lo:[1,0,0] neg_hi:[1,0,0]
	v_pk_mul_f32 v[168:169], v[188:189], v[168:169]
	v_pk_mul_f32 v[166:167], v[180:181], v[166:167]
	v_add_lshl_u32 v165, v184, v164, 1
	v_cvt_pk_bf16_f32 v168, v168, v169
	v_cvt_pk_bf16_f32 v169, v166, v167
	global_store_dwordx2 v165, v[168:169], s[40:41]
	s_or_b64 exec, exec, s[0:1]
	s_and_saveexec_b64 s[0:1], s[12:13]
	s_cbranch_execz .LBB0_806
.LBB0_852:
	v_pk_fma_f32 v[168:169], v[28:29], v[152:153], v[156:157]
	v_mov_b64_e32 v[182:183], s[62:63]
	v_pk_fma_f32 v[168:169], v[36:37], v[148:149], v[168:169]
	v_add_lshl_u32 v165, v185, v164, 1
	v_pk_fma_f32 v[168:169], v[44:45], v[144:145], v[168:169]
	v_pk_fma_f32 v[166:167], v[30:31], v[154:155], v[158:159]
	v_and_b32_e32 v175, 0x7fffffff, v169
	v_and_b32_e32 v174, 0x7fffffff, v168
	v_pk_fma_f32 v[180:181], v[174:175], s[58:59], 1.0 op_sel_hi:[1,0,0]
	v_pk_mul_f32 v[178:179], v[168:169], v[168:169]
	v_rcp_f32_e32 v180, v180
	v_rcp_f32_e32 v181, v181
	v_pk_mul_f32 v[178:179], v[178:179], s[56:57] op_sel_hi:[1,0]
	v_pk_fma_f32 v[166:167], v[38:39], v[150:151], v[166:167]
	v_exp_f32_e32 v178, v178
	v_pk_fma_f32 v[184:185], v[180:181], s[60:61], v[182:183] op_sel_hi:[1,0,0]
	v_exp_f32_e32 v179, v179
	v_pk_fma_f32 v[184:185], v[180:181], v[184:185], s[64:65] op_sel_hi:[1,1,0]
	v_pk_fma_f32 v[166:167], v[46:47], v[146:147], v[166:167]
	v_pk_fma_f32 v[184:185], v[180:181], v[184:185], s[66:67] op_sel_hi:[1,1,0]
	v_max_f32_e32 v170, 0, v168
	v_pk_fma_f32 v[184:185], v[180:181], v[184:185], s[68:69] op_sel_hi:[1,1,0]
	v_and_b32_e32 v173, 0x7fffffff, v167
	v_pk_mul_f32 v[180:181], v[180:181], v[184:185]
	v_and_b32_e32 v172, 0x7fffffff, v166
	v_pk_mul_f32 v[178:179], v[178:179], v[180:181]
	v_max_f32_e32 v171, 0, v169
	v_pk_fma_f32 v[168:169], v[174:175], v[178:179], v[170:171] neg_lo:[1,0,0] neg_hi:[1,0,0]
	v_pk_fma_f32 v[170:171], v[172:173], s[58:59], 1.0 op_sel_hi:[1,0,0]
	v_pk_mul_f32 v[176:177], v[166:167], v[166:167]
	v_rcp_f32_e32 v170, v170
	v_rcp_f32_e32 v171, v171
	v_pk_mul_f32 v[174:175], v[176:177], s[56:57] op_sel_hi:[1,0]
	v_pk_fma_f32 v[180:181], v[26:27], v[138:139], v[142:143]
	v_exp_f32_e32 v174, v174
	v_pk_fma_f32 v[176:177], v[170:171], s[60:61], v[182:183] op_sel_hi:[1,0,0]
	v_exp_f32_e32 v175, v175
	v_pk_fma_f32 v[176:177], v[170:171], v[176:177], s[64:65] op_sel_hi:[1,1,0]
	v_pk_fma_f32 v[184:185], v[24:25], v[136:137], v[140:141]
	v_pk_fma_f32 v[176:177], v[170:171], v[176:177], s[66:67] op_sel_hi:[1,1,0]
	v_pk_fma_f32 v[180:181], v[34:35], v[134:135], v[180:181]
	v_pk_fma_f32 v[176:177], v[170:171], v[176:177], s[68:69] op_sel_hi:[1,1,0]
	v_pk_fma_f32 v[184:185], v[32:33], v[132:133], v[184:185]
	v_pk_mul_f32 v[170:171], v[170:171], v[176:177]
	v_max_f32_e32 v166, 0, v166
	v_pk_mul_f32 v[170:171], v[174:175], v[170:171]
	v_max_f32_e32 v167, 0, v167
	v_pk_fma_f32 v[180:181], v[42:43], v[130:131], v[180:181]
	v_pk_fma_f32 v[184:185], v[40:41], v[128:129], v[184:185]
	v_pk_fma_f32 v[166:167], v[172:173], v[170:171], v[166:167] neg_lo:[1,0,0] neg_hi:[1,0,0]
	v_pk_mul_f32 v[168:169], v[184:185], v[168:169]
	v_pk_mul_f32 v[166:167], v[180:181], v[166:167]
	v_cvt_pk_bf16_f32 v168, v168, v169
	v_cvt_pk_bf16_f32 v169, v166, v167
	global_store_dwordx2 v165, v[168:169], s[40:41]
	s_or_b64 exec, exec, s[0:1]
	s_and_saveexec_b64 s[0:1], s[14:15]
	s_cbranch_execz .LBB0_807
; __device__ __forceinline__ unsigned pk2(float lo, float hi) { const f32x2 v = {lo, hi}; return __builtin_bit_cast(unsigned, __builtin_convertvector(v, bf16x2_hw)); }
;     template <bool EDGE> __device__ __forceinline__ void body(const f32x4 (&acc)[2][2][4][2], const pg8::Unit& u, int wr, int wc, int fr, int fq) const {
;     ...
;                 const int ai = k >> 2, m = k & 3, lr = 8 * fr + k, tau = tw0 + lr, sp = tau & 4095;
;                 const f32x4 cv = acc[ai][0][m][n], cg = acc[ai][1][m][n];
;                 const f32x4 p1v = k >= 1 ? acc[(k >= 1 ? k - 1 : 0) >> 2][0][(k >= 1 ? k - 1 : 0) & 3][n] : v7;
;                 const f32x4 p1g = k >= 1 ? acc[(k >= 1 ? k - 1 : 0) >> 2][1][(k >= 1 ? k - 1 : 0) & 3][n] : g7;
;                 const f32x4 p2v = k >= 2 ? acc[(k >= 2 ? k - 2 : 0) >> 2][0][(k >= 2 ? k - 2 : 0) & 3][n] : (k == 1 ? v7 : v6);
;                 const f32x4 p2g = k >= 2 ? acc[(k >= 2 ? k - 2 : 0) >> 2][1][(k >= 2 ? k - 2 : 0) & 3][n] : (k == 1 ? g7 : g6);
;                 f32x4 val, gat;
;                 if (EDGE) { const float m1 = sp >= 1 ? 1.f : 0.f, m2 = sp >= 2 ? 1.f : 0.f;
;                     val = bv + wv2 * cv + (wv1 * m1) * p1v + (wv0 * m2) * p2v; gat = bg + wg2 * cg + (wg1 * m1) * p1g + (wg0 * m2) * p2g; }
;                 else { val = bv + wv2 * cv + wv1 * p1v + wv0 * p2v; gat = bg + wg2 * cg + wg1 * p1g + wg0 * p2g; }
;                 const f32x2 g01 = gelu_pk((f32x2){gat[0], gat[1]}), g23 = gelu_pk((f32x2){gat[2], gat[3]});
;                 u32x2 w; w.x = pk2(g01.x * val[0], g01.y * val[1]); w.y = pk2(g23.x * val[2], g23.y * val[3]);
;                 if (lr >= 2 && tau < NT) *(u32x2*)((char*)hidden + (unsigned)(tau * DFF + ch) * 2u) = w;
.LBB0_853:
	v_pk_fma_f32 v[168:169], v[16:17], v[152:153], v[156:157]
	v_mov_b64_e32 v[182:183], s[62:63]
	v_pk_fma_f32 v[168:169], v[28:29], v[148:149], v[168:169]
	v_pk_fma_f32 v[166:167], v[18:19], v[154:155], v[158:159]
	v_pk_fma_f32 v[168:169], v[36:37], v[144:145], v[168:169]
	v_pk_fma_f32 v[166:167], v[30:31], v[150:151], v[166:167]
	v_and_b32_e32 v175, 0x7fffffff, v169
	v_and_b32_e32 v174, 0x7fffffff, v168
	v_pk_fma_f32 v[180:181], v[174:175], s[58:59], 1.0 op_sel_hi:[1,0,0]
	v_pk_mul_f32 v[178:179], v[168:169], v[168:169]
	v_rcp_f32_e32 v180, v180
	v_rcp_f32_e32 v181, v181
	v_pk_mul_f32 v[178:179], v[178:179], s[56:57] op_sel_hi:[1,0]
	v_pk_fma_f32 v[166:167], v[38:39], v[146:147], v[166:167]
	v_exp_f32_e32 v178, v178
	v_pk_fma_f32 v[184:185], v[180:181], s[60:61], v[182:183] op_sel_hi:[1,0,0]
	v_exp_f32_e32 v179, v179
	v_pk_fma_f32 v[184:185], v[180:181], v[184:185], s[64:65] op_sel_hi:[1,1,0]
	v_max_f32_e32 v170, 0, v168
	v_pk_fma_f32 v[184:185], v[180:181], v[184:185], s[66:67] op_sel_hi:[1,1,0]
	v_and_b32_e32 v173, 0x7fffffff, v167
	v_pk_fma_f32 v[184:185], v[180:181], v[184:185], s[68:69] op_sel_hi:[1,1,0]
	v_and_b32_e32 v172, 0x7fffffff, v166
	v_pk_mul_f32 v[180:181], v[180:181], v[184:185]
	v_max_f32_e32 v171, 0, v169
	v_pk_mul_f32 v[178:179], v[178:179], v[180:181]
	v_pk_mul_f32 v[176:177], v[166:167], v[166:167]
	v_pk_fma_f32 v[168:169], v[174:175], v[178:179], v[170:171] neg_lo:[1,0,0] neg_hi:[1,0,0]
	v_pk_fma_f32 v[170:171], v[172:173], s[58:59], 1.0 op_sel_hi:[1,0,0]
	v_pk_mul_f32 v[174:175], v[176:177], s[56:57] op_sel_hi:[1,0]
	v_rcp_f32_e32 v170, v170
	v_rcp_f32_e32 v171, v171
	v_exp_f32_e32 v174, v174
	v_exp_f32_e32 v175, v175
	v_pk_fma_f32 v[180:181], v[10:11], v[138:139], v[142:143]
	v_pk_fma_f32 v[176:177], v[170:171], s[60:61], v[182:183] op_sel_hi:[1,0,0]
	v_pk_fma_f32 v[184:185], v[8:9], v[136:137], v[140:141]
	v_pk_fma_f32 v[176:177], v[170:171], v[176:177], s[64:65] op_sel_hi:[1,1,0]
	v_pk_fma_f32 v[180:181], v[26:27], v[134:135], v[180:181]
	v_pk_fma_f32 v[176:177], v[170:171], v[176:177], s[66:67] op_sel_hi:[1,1,0]
	v_pk_fma_f32 v[184:185], v[24:25], v[132:133], v[184:185]
	v_pk_fma_f32 v[176:177], v[170:171], v[176:177], s[68:69] op_sel_hi:[1,1,0]
	v_max_f32_e32 v166, 0, v166
	v_pk_mul_f32 v[170:171], v[170:171], v[176:177]
	v_max_f32_e32 v167, 0, v167
	v_pk_mul_f32 v[170:171], v[174:175], v[170:171]
	v_pk_fma_f32 v[180:181], v[34:35], v[130:131], v[180:181]
	v_pk_fma_f32 v[184:185], v[32:33], v[128:129], v[184:185]
	v_pk_fma_f32 v[166:167], v[172:173], v[170:171], v[166:167] neg_lo:[1,0,0] neg_hi:[1,0,0]
	v_pk_mul_f32 v[168:169], v[184:185], v[168:169]
	v_pk_mul_f32 v[166:167], v[180:181], v[166:167]
	v_add_lshl_u32 v165, v211, v164, 1
	v_cvt_pk_bf16_f32 v168, v168, v169
	v_cvt_pk_bf16_f32 v169, v166, v167
	global_store_dwordx2 v165, v[168:169], s[40:41]
	s_or_b64 exec, exec, s[0:1]
	s_and_saveexec_b64 s[0:1], s[16:17]
	s_cbranch_execz .LBB0_808
.LBB0_854:
	v_pk_fma_f32 v[168:169], v[20:21], v[152:153], v[156:157]
	v_mov_b64_e32 v[182:183], s[62:63]
	v_pk_fma_f32 v[168:169], v[16:17], v[148:149], v[168:169]
	v_pk_fma_f32 v[166:167], v[22:23], v[154:155], v[158:159]
	v_pk_fma_f32 v[168:169], v[28:29], v[144:145], v[168:169]
	v_pk_fma_f32 v[166:167], v[18:19], v[150:151], v[166:167]
	v_and_b32_e32 v175, 0x7fffffff, v169
	v_and_b32_e32 v174, 0x7fffffff, v168
	v_pk_fma_f32 v[180:181], v[174:175], s[58:59], 1.0 op_sel_hi:[1,0,0]
	v_pk_mul_f32 v[178:179], v[168:169], v[168:169]
	v_rcp_f32_e32 v180, v180
	v_rcp_f32_e32 v181, v181
	v_pk_mul_f32 v[178:179], v[178:179], s[56:57] op_sel_hi:[1,0]
	v_pk_fma_f32 v[166:167], v[30:31], v[146:147], v[166:167]
	v_exp_f32_e32 v178, v178
	v_pk_fma_f32 v[184:185], v[180:181], s[60:61], v[182:183] op_sel_hi:[1,0,0]
	v_exp_f32_e32 v179, v179
	v_pk_fma_f32 v[184:185], v[180:181], v[184:185], s[64:65] op_sel_hi:[1,1,0]
	v_max_f32_e32 v170, 0, v168
	v_pk_fma_f32 v[184:185], v[180:181], v[184:185], s[66:67] op_sel_hi:[1,1,0]
	v_and_b32_e32 v173, 0x7fffffff, v167
	v_pk_fma_f32 v[184:185], v[180:181], v[184:185], s[68:69] op_sel_hi:[1,1,0]
	v_and_b32_e32 v172, 0x7fffffff, v166
	v_pk_mul_f32 v[180:181], v[180:181], v[184:185]
	v_max_f32_e32 v171, 0, v169
	v_pk_mul_f32 v[178:179], v[178:179], v[180:181]
	v_pk_mul_f32 v[176:177], v[166:167], v[166:167]
	v_pk_fma_f32 v[168:169], v[174:175], v[178:179], v[170:171] neg_lo:[1,0,0] neg_hi:[1,0,0]
	v_pk_fma_f32 v[170:171], v[172:173], s[58:59], 1.0 op_sel_hi:[1,0,0]
	v_pk_mul_f32 v[174:175], v[176:177], s[56:57] op_sel_hi:[1,0]
	v_rcp_f32_e32 v170, v170
	v_rcp_f32_e32 v171, v171
	v_exp_f32_e32 v174, v174
	v_exp_f32_e32 v175, v175
	v_pk_fma_f32 v[180:181], v[6:7], v[138:139], v[142:143]
	v_pk_fma_f32 v[176:177], v[170:171], s[60:61], v[182:183] op_sel_hi:[1,0,0]
	v_pk_fma_f32 v[184:185], v[4:5], v[136:137], v[140:141]
	v_pk_fma_f32 v[176:177], v[170:171], v[176:177], s[64:65] op_sel_hi:[1,1,0]
	v_pk_fma_f32 v[180:181], v[10:11], v[134:135], v[180:181]
	v_pk_fma_f32 v[176:177], v[170:171], v[176:177], s[66:67] op_sel_hi:[1,1,0]
	v_pk_fma_f32 v[184:185], v[8:9], v[132:133], v[184:185]
	v_pk_fma_f32 v[176:177], v[170:171], v[176:177], s[68:69] op_sel_hi:[1,1,0]
	v_max_f32_e32 v166, 0, v166
	v_pk_mul_f32 v[170:171], v[170:171], v[176:177]
	v_max_f32_e32 v167, 0, v167
	v_pk_mul_f32 v[170:171], v[174:175], v[170:171]
	v_pk_fma_f32 v[180:181], v[26:27], v[130:131], v[180:181]
	v_pk_fma_f32 v[184:185], v[24:25], v[128:129], v[184:185]
	v_pk_fma_f32 v[166:167], v[172:173], v[170:171], v[166:167] neg_lo:[1,0,0] neg_hi:[1,0,0]
	v_pk_mul_f32 v[168:169], v[184:185], v[168:169]
	v_pk_mul_f32 v[166:167], v[180:181], v[166:167]
	v_add_lshl_u32 v165, v212, v164, 1
	v_cvt_pk_bf16_f32 v168, v168, v169
	v_cvt_pk_bf16_f32 v169, v166, v167
	global_store_dwordx2 v165, v[168:169], s[40:41]
	s_or_b64 exec, exec, s[0:1]
	s_and_saveexec_b64 s[0:1], s[18:19]
	s_cbranch_execnz .LBB0_809
	s_branch .LBB0_810
